# both PEER apply+LN2 phases hand-written: U sweep for all tokens then V sweep (one table at a time in L2), 8-row load ring, 8-row batched wave reductions via LDS
# speedup vs baseline: 1.1278x; 1.0496x over previous
; #define TIDX tid_fn()
; __device__ __forceinline__ void ph_peer_apply(const Params& P, int layer, float* xlat, float* xctx_in, float* xctx_out, int nrows, bool write_next, char* smem, float* xlat_out = nullptr) {
;     ...
;   const int tid = TIDX, wave = tid >> 6, lane = tid & 63;
;   const bool lact = lane < P6_NB;
;   const int lb = lact ? lane : 0;
;   for (int row = blockIdx.x * (NTHR / 64) + wave; row < nrows; row += gridDim.x * (NTHR / 64)) {
;     float xv[32];
; #pragma unroll
;     for (int j8 = 0; j8 < 4; ++j8) {
;       const h16x8 t = *(const h16x8*)(xq + (size_t)row * D + lb * 32 + j8 * 8);
; #pragma unroll
;       for (int j = 0; j < 8; ++j) xv[j8 * 8 + j] = lact ? (float)t[j] : 0.f;
;     }
;     const int id0 = seli[(size_t)row * NSEL + lane], id1 = seli[(size_t)row * NSEL + 64 + lane];
;     const float g0 = selg[(size_t)row * NSEL + lane], g1 = selg[(size_t)row * NSEL + 64 + lane];
;     float a0 = 0.f, a1 = 0.f;
;     P6Blk bufA[PB_G], bufB[PB_G];
.LBB0_1953:
	s_or_b64 exec, exec, s[6:7]
	s_mov_b64 s[4:5], s[96:97]
	s_waitcnt lgkmcnt(0)
	v_mov_b32_e32 v1, v0
	s_barrier
	s_load_dwordx4 s[4:7], s[96:97], 0x170
	s_load_dwordx4 s[8:11], s[96:97], 0x30
	v_readfirstlane_b32 s12, v0
	s_lshr_b32 s12, s12, 6
	v_and_b32_e32 v1, 63, v0
	v_mul_u32_u24_e32 v2, 24, v1
	v_add_u32_e32 v3, 0x600, v1
	v_lshlrev_b32_e32 v224, 6, v1
	v_lshlrev_b32_e32 v225, 7, v1
	v_lshlrev_b32_e32 v226, 2, v1
	v_lshrrev_b32_e32 v192, 2, v1
	v_and_b32_e32 v193, 1, v1
	v_lshl_add_u32 v192, v192, 1, v193
	v_lshlrev_b32_e32 v227, 2, v192
	s_mul_i32 s15, s12, 0x2800
	v_add_u32_e32 v228, s15, v226
	v_add_u32_e32 v227, s15, v227
	s_mov_b32 s46, 0x3333
	s_mov_b32 s47, 0
	s_mov_b32 s34, 0x22222222
	s_mov_b32 s35, 0x22222222
	s_waitcnt lgkmcnt(0)
	s_mov_b64 s[40:41], s[4:5]
	s_mov_b64 s[4:5], s[6:7]
	s_mov_b64 s[6:7], s[40:41]
	s_add_u32 s16, s4, 0x3c7c000
	s_addc_u32 s17, s5, 0
	s_add_u32 s18, s4, 0x7c7c000
	s_addc_u32 s19, s5, 0
	s_add_u32 s13, s60, s12
	s_lshl_b32 s44, s84, 3
	s_mov_b32 s14, 0
	s_mov_b32 s45, s13
.Lap0_s1_tok:
	s_cmp_ge_u32 s45, 0x8200
	s_cbranch_scc1 .Lap0_s1_done
	s_lshl_b32 s15, s45, 12
	s_lshr_b32 s31, s45, 20
	s_add_u32 s20, s4, 0xbe4c000
	s_addc_u32 s21, s5, 0
	s_add_u32 s20, s20, s15
	s_addc_u32 s21, s21, s31
	s_lshl_b32 s15, s45, 9
	s_add_u32 s22, s4, 0x1404c000
	s_addc_u32 s23, s5, 0
	s_add_u32 s22, s22, s15
	s_addc_u32 s23, s23, 0
	s_add_u32 s24, s4, 0x1508c000
	s_addc_u32 s25, s5, 0
	s_add_u32 s24, s24, s15
	s_addc_u32 s25, s25, 0
	global_load_dwordx4 v[4:7], v224, s[20:21]
	global_load_dwordx4 v[8:11], v224, s[20:21] offset:16
	global_load_dwordx4 v[12:15], v224, s[20:21] offset:32
	global_load_dwordx4 v[16:19], v224, s[20:21] offset:48
	global_load_dword v36, v226, s[22:23]
	global_load_dword v37, v226, s[22:23] offset:256
	global_load_dword v40, v226, s[24:25]
	global_load_dword v41, v226, s[24:25] offset:256
	s_lshl_b32 s15, s14, 9
	v_add_u32_e32 v229, s15, v227
	s_waitcnt vmcnt(0)
	s_mov_b32 s28, 0
	v_readlane_b32 s29, v36, s28
	s_add_u32 s28, s28, 1
	s_mul_hi_u32 s27, s29, 0x640
	s_mul_i32 s26, s29, 0x640
	s_add_u32 s26, s16, s26
	s_addc_u32 s27, s17, s27
	global_load_dwordx4 v[48:51], v2, s[26:27]
	global_load_dwordx2 v[52:53], v2, s[26:27] offset:16
	global_load_ubyte v54, v3, s[26:27]
	v_readlane_b32 s29, v36, s28
	s_add_u32 s28, s28, 1
	s_mul_hi_u32 s27, s29, 0x640
	s_mul_i32 s26, s29, 0x640
	s_add_u32 s26, s16, s26
	s_addc_u32 s27, s17, s27
	global_load_dwordx4 v[56:59], v2, s[26:27]
	global_load_dwordx2 v[60:61], v2, s[26:27] offset:16
	global_load_ubyte v62, v3, s[26:27]
	v_readlane_b32 s29, v36, s28
	s_add_u32 s28, s28, 1
	s_mul_hi_u32 s27, s29, 0x640
	s_mul_i32 s26, s29, 0x640
	s_add_u32 s26, s16, s26
	s_addc_u32 s27, s17, s27
	global_load_dwordx4 v[64:67], v2, s[26:27]
	global_load_dwordx2 v[68:69], v2, s[26:27] offset:16
	global_load_ubyte v70, v3, s[26:27]
	v_readlane_b32 s29, v36, s28
	s_add_u32 s28, s28, 1
	s_mul_hi_u32 s27, s29, 0x640
	s_mul_i32 s26, s29, 0x640
	s_add_u32 s26, s16, s26
	s_addc_u32 s27, s17, s27
	global_load_dwordx4 v[72:75], v2, s[26:27]
	global_load_dwordx2 v[76:77], v2, s[26:27] offset:16
	global_load_ubyte v78, v3, s[26:27]
	v_readlane_b32 s29, v36, s28
	s_add_u32 s28, s28, 1
	s_mul_hi_u32 s27, s29, 0x640
	s_mul_i32 s26, s29, 0x640
	s_add_u32 s26, s16, s26
	s_addc_u32 s27, s17, s27
	global_load_dwordx4 v[80:83], v2, s[26:27]
	global_load_dwordx2 v[84:85], v2, s[26:27] offset:16
	global_load_ubyte v86, v3, s[26:27]
	v_readlane_b32 s29, v36, s28
	s_add_u32 s28, s28, 1
	s_mul_hi_u32 s27, s29, 0x640
	s_mul_i32 s26, s29, 0x640
	s_add_u32 s26, s16, s26
	s_addc_u32 s27, s17, s27
	global_load_dwordx4 v[88:91], v2, s[26:27]
	global_load_dwordx2 v[92:93], v2, s[26:27] offset:16
	global_load_ubyte v94, v3, s[26:27]
	v_readlane_b32 s29, v36, s28
	s_add_u32 s28, s28, 1
	s_mul_hi_u32 s27, s29, 0x640
	s_mul_i32 s26, s29, 0x640
	s_add_u32 s26, s16, s26
	s_addc_u32 s27, s17, s27
	global_load_dwordx4 v[96:99], v2, s[26:27]
	global_load_dwordx2 v[100:101], v2, s[26:27] offset:16
	global_load_ubyte v102, v3, s[26:27]
	v_readlane_b32 s29, v36, s28
	s_add_u32 s28, s28, 1
	s_mul_hi_u32 s27, s29, 0x640
	s_mul_i32 s26, s29, 0x640
	s_add_u32 s26, s16, s26
	s_addc_u32 s27, s17, s27
	global_load_dwordx4 v[104:107], v2, s[26:27]
	global_load_dwordx2 v[108:109], v2, s[26:27] offset:16
	global_load_ubyte v110, v3, s[26:27]
	s_mov_b32 s30, 7
; #define PB_FENCE asm volatile("" ::: "memory")
; __device__ __forceinline__ void ph_peer_apply(const Params& P, int layer, float* xlat, float* xctx_in, float* xctx_out, int nrows, bool write_next, char* smem, float* xlat_out = nullptr) {
;     ...
;     constexpr int NG = NSEL / PB_G;
;     PB_LOAD(bufA, tu, 0);
;     for (int gq = 0; gq < NG; gq += 2) {
;       PB_LOAD(bufB, tu, gq + 1); PB_FENCE;
;       PB_DOT(bufA, gq);
;       if (gq + 2 < NG) PB_LOAD(bufA, tu, gq + 2);
;       PB_FENCE;
;       PB_DOT(bufB, gq + 1);
;     }
.Lap0_s1_loop1:
	s_waitcnt vmcnt(21)
	v_lshlrev_b32_e32 v192, 23, v54
	v_cvt_scalef32_pk32_f32_fp6 v[112:143], v[48:53], v192
	v_fma_mix_f32 v144, v112, v4, 0 op_sel_hi:[0,1,0]
	v_fma_mix_f32 v145, v113, v4, 0 op_sel:[0,1,0] op_sel_hi:[0,1,0]
	v_fma_mix_f32 v144, v114, v5, v144 op_sel_hi:[0,1,0]
	v_fma_mix_f32 v145, v115, v5, v145 op_sel:[0,1,0] op_sel_hi:[0,1,0]
	v_fma_mix_f32 v144, v116, v6, v144 op_sel_hi:[0,1,0]
	v_fma_mix_f32 v145, v117, v6, v145 op_sel:[0,1,0] op_sel_hi:[0,1,0]
	v_fma_mix_f32 v144, v118, v7, v144 op_sel_hi:[0,1,0]
	v_fma_mix_f32 v145, v119, v7, v145 op_sel:[0,1,0] op_sel_hi:[0,1,0]
	v_fma_mix_f32 v144, v120, v8, v144 op_sel_hi:[0,1,0]
	v_fma_mix_f32 v145, v121, v8, v145 op_sel:[0,1,0] op_sel_hi:[0,1,0]
	v_fma_mix_f32 v144, v122, v9, v144 op_sel_hi:[0,1,0]
	v_fma_mix_f32 v145, v123, v9, v145 op_sel:[0,1,0] op_sel_hi:[0,1,0]
	v_fma_mix_f32 v144, v124, v10, v144 op_sel_hi:[0,1,0]
	v_fma_mix_f32 v145, v125, v10, v145 op_sel:[0,1,0] op_sel_hi:[0,1,0]
	v_fma_mix_f32 v144, v126, v11, v144 op_sel_hi:[0,1,0]
	v_fma_mix_f32 v145, v127, v11, v145 op_sel:[0,1,0] op_sel_hi:[0,1,0]
	v_fma_mix_f32 v144, v128, v12, v144 op_sel_hi:[0,1,0]
	v_fma_mix_f32 v145, v129, v12, v145 op_sel:[0,1,0] op_sel_hi:[0,1,0]
	v_fma_mix_f32 v144, v130, v13, v144 op_sel_hi:[0,1,0]
	v_fma_mix_f32 v145, v131, v13, v145 op_sel:[0,1,0] op_sel_hi:[0,1,0]
	v_fma_mix_f32 v144, v132, v14, v144 op_sel_hi:[0,1,0]
	v_fma_mix_f32 v145, v133, v14, v145 op_sel:[0,1,0] op_sel_hi:[0,1,0]
	v_fma_mix_f32 v144, v134, v15, v144 op_sel_hi:[0,1,0]
	v_fma_mix_f32 v145, v135, v15, v145 op_sel:[0,1,0] op_sel_hi:[0,1,0]
	v_fma_mix_f32 v144, v136, v16, v144 op_sel_hi:[0,1,0]
	v_fma_mix_f32 v145, v137, v16, v145 op_sel:[0,1,0] op_sel_hi:[0,1,0]
	v_fma_mix_f32 v144, v138, v17, v144 op_sel_hi:[0,1,0]
	v_fma_mix_f32 v145, v139, v17, v145 op_sel:[0,1,0] op_sel_hi:[0,1,0]
	v_fma_mix_f32 v144, v140, v18, v144 op_sel_hi:[0,1,0]
	v_fma_mix_f32 v145, v141, v18, v145 op_sel:[0,1,0] op_sel_hi:[0,1,0]
	v_fma_mix_f32 v144, v142, v19, v144 op_sel_hi:[0,1,0]
	v_fma_mix_f32 v145, v143, v19, v145 op_sel:[0,1,0] op_sel_hi:[0,1,0]
	v_add_f32_e32 v146, v144, v145
	v_readlane_b32 s29, v36, s28
	s_add_u32 s28, s28, 1
	s_mul_hi_u32 s27, s29, 0x640
	s_mul_i32 s26, s29, 0x640
	s_add_u32 s26, s16, s26
	s_addc_u32 s27, s17, s27
	global_load_dwordx4 v[48:51], v2, s[26:27]
	global_load_dwordx2 v[52:53], v2, s[26:27] offset:16
	global_load_ubyte v54, v3, s[26:27]
	s_waitcnt vmcnt(21)
	v_lshlrev_b32_e32 v192, 23, v62
	v_cvt_scalef32_pk32_f32_fp6 v[112:143], v[56:61], v192
	v_fma_mix_f32 v144, v112, v4, 0 op_sel_hi:[0,1,0]
	v_fma_mix_f32 v145, v113, v4, 0 op_sel:[0,1,0] op_sel_hi:[0,1,0]
	v_fma_mix_f32 v144, v114, v5, v144 op_sel_hi:[0,1,0]
	v_fma_mix_f32 v145, v115, v5, v145 op_sel:[0,1,0] op_sel_hi:[0,1,0]
	v_fma_mix_f32 v144, v116, v6, v144 op_sel_hi:[0,1,0]
	v_fma_mix_f32 v145, v117, v6, v145 op_sel:[0,1,0] op_sel_hi:[0,1,0]
	v_fma_mix_f32 v144, v118, v7, v144 op_sel_hi:[0,1,0]
	v_fma_mix_f32 v145, v119, v7, v145 op_sel:[0,1,0] op_sel_hi:[0,1,0]
	v_fma_mix_f32 v144, v120, v8, v144 op_sel_hi:[0,1,0]
	v_fma_mix_f32 v145, v121, v8, v145 op_sel:[0,1,0] op_sel_hi:[0,1,0]
	v_fma_mix_f32 v144, v122, v9, v144 op_sel_hi:[0,1,0]
	v_fma_mix_f32 v145, v123, v9, v145 op_sel:[0,1,0] op_sel_hi:[0,1,0]
	v_fma_mix_f32 v144, v124, v10, v144 op_sel_hi:[0,1,0]
	v_fma_mix_f32 v145, v125, v10, v145 op_sel:[0,1,0] op_sel_hi:[0,1,0]
	v_fma_mix_f32 v144, v126, v11, v144 op_sel_hi:[0,1,0]
	v_fma_mix_f32 v145, v127, v11, v145 op_sel:[0,1,0] op_sel_hi:[0,1,0]
	v_fma_mix_f32 v144, v128, v12, v144 op_sel_hi:[0,1,0]
	v_fma_mix_f32 v145, v129, v12, v145 op_sel:[0,1,0] op_sel_hi:[0,1,0]
	v_fma_mix_f32 v144, v130, v13, v144 op_sel_hi:[0,1,0]
	v_fma_mix_f32 v145, v131, v13, v145 op_sel:[0,1,0] op_sel_hi:[0,1,0]
	v_fma_mix_f32 v144, v132, v14, v144 op_sel_hi:[0,1,0]
	v_fma_mix_f32 v145, v133, v14, v145 op_sel:[0,1,0] op_sel_hi:[0,1,0]
	v_fma_mix_f32 v144, v134, v15, v144 op_sel_hi:[0,1,0]
	v_fma_mix_f32 v145, v135, v15, v145 op_sel:[0,1,0] op_sel_hi:[0,1,0]
	v_fma_mix_f32 v144, v136, v16, v144 op_sel_hi:[0,1,0]
	v_fma_mix_f32 v145, v137, v16, v145 op_sel:[0,1,0] op_sel_hi:[0,1,0]
	v_fma_mix_f32 v144, v138, v17, v144 op_sel_hi:[0,1,0]
	v_fma_mix_f32 v145, v139, v17, v145 op_sel:[0,1,0] op_sel_hi:[0,1,0]
	v_fma_mix_f32 v144, v140, v18, v144 op_sel_hi:[0,1,0]
	v_fma_mix_f32 v145, v141, v18, v145 op_sel:[0,1,0] op_sel_hi:[0,1,0]
	v_fma_mix_f32 v144, v142, v19, v144 op_sel_hi:[0,1,0]
	v_fma_mix_f32 v145, v143, v19, v145 op_sel:[0,1,0] op_sel_hi:[0,1,0]
	v_add_f32_e32 v147, v144, v145
	v_readlane_b32 s29, v36, s28
	s_add_u32 s28, s28, 1
	s_mul_hi_u32 s27, s29, 0x640
	s_mul_i32 s26, s29, 0x640
	s_add_u32 s26, s16, s26
	s_addc_u32 s27, s17, s27
	global_load_dwordx4 v[56:59], v2, s[26:27]
	global_load_dwordx2 v[60:61], v2, s[26:27] offset:16
	global_load_ubyte v62, v3, s[26:27]
	s_waitcnt vmcnt(21)
; #define PB_FENCE asm volatile("" ::: "memory")
; __device__ __forceinline__ void ph_peer_apply(const Params& P, int layer, float* xlat, float* xctx_in, float* xctx_out, int nrows, bool write_next, char* smem, float* xlat_out = nullptr) {
;     ...
;     constexpr int NG = NSEL / PB_G;
;     PB_LOAD(bufA, tu, 0);
;     for (int gq = 0; gq < NG; gq += 2) {
;       PB_LOAD(bufB, tu, gq + 1); PB_FENCE;
;       PB_DOT(bufA, gq);
;       if (gq + 2 < NG) PB_LOAD(bufA, tu, gq + 2);
;       PB_FENCE;
;       PB_DOT(bufB, gq + 1);
;     }
	v_lshlrev_b32_e32 v192, 23, v70
	v_cvt_scalef32_pk32_f32_fp6 v[112:143], v[64:69], v192
	v_fma_mix_f32 v144, v112, v4, 0 op_sel_hi:[0,1,0]
	v_fma_mix_f32 v145, v113, v4, 0 op_sel:[0,1,0] op_sel_hi:[0,1,0]
	v_fma_mix_f32 v144, v114, v5, v144 op_sel_hi:[0,1,0]
	v_fma_mix_f32 v145, v115, v5, v145 op_sel:[0,1,0] op_sel_hi:[0,1,0]
	v_fma_mix_f32 v144, v116, v6, v144 op_sel_hi:[0,1,0]
	v_fma_mix_f32 v145, v117, v6, v145 op_sel:[0,1,0] op_sel_hi:[0,1,0]
	v_fma_mix_f32 v144, v118, v7, v144 op_sel_hi:[0,1,0]
	v_fma_mix_f32 v145, v119, v7, v145 op_sel:[0,1,0] op_sel_hi:[0,1,0]
	v_fma_mix_f32 v144, v120, v8, v144 op_sel_hi:[0,1,0]
	v_fma_mix_f32 v145, v121, v8, v145 op_sel:[0,1,0] op_sel_hi:[0,1,0]
	v_fma_mix_f32 v144, v122, v9, v144 op_sel_hi:[0,1,0]
	v_fma_mix_f32 v145, v123, v9, v145 op_sel:[0,1,0] op_sel_hi:[0,1,0]
	v_fma_mix_f32 v144, v124, v10, v144 op_sel_hi:[0,1,0]
	v_fma_mix_f32 v145, v125, v10, v145 op_sel:[0,1,0] op_sel_hi:[0,1,0]
	v_fma_mix_f32 v144, v126, v11, v144 op_sel_hi:[0,1,0]
	v_fma_mix_f32 v145, v127, v11, v145 op_sel:[0,1,0] op_sel_hi:[0,1,0]
	v_fma_mix_f32 v144, v128, v12, v144 op_sel_hi:[0,1,0]
	v_fma_mix_f32 v145, v129, v12, v145 op_sel:[0,1,0] op_sel_hi:[0,1,0]
	v_fma_mix_f32 v144, v130, v13, v144 op_sel_hi:[0,1,0]
	v_fma_mix_f32 v145, v131, v13, v145 op_sel:[0,1,0] op_sel_hi:[0,1,0]
	v_fma_mix_f32 v144, v132, v14, v144 op_sel_hi:[0,1,0]
	v_fma_mix_f32 v145, v133, v14, v145 op_sel:[0,1,0] op_sel_hi:[0,1,0]
	v_fma_mix_f32 v144, v134, v15, v144 op_sel_hi:[0,1,0]
	v_fma_mix_f32 v145, v135, v15, v145 op_sel:[0,1,0] op_sel_hi:[0,1,0]
	v_fma_mix_f32 v144, v136, v16, v144 op_sel_hi:[0,1,0]
	v_fma_mix_f32 v145, v137, v16, v145 op_sel:[0,1,0] op_sel_hi:[0,1,0]
	v_fma_mix_f32 v144, v138, v17, v144 op_sel_hi:[0,1,0]
	v_fma_mix_f32 v145, v139, v17, v145 op_sel:[0,1,0] op_sel_hi:[0,1,0]
	v_fma_mix_f32 v144, v140, v18, v144 op_sel_hi:[0,1,0]
	v_fma_mix_f32 v145, v141, v18, v145 op_sel:[0,1,0] op_sel_hi:[0,1,0]
	v_fma_mix_f32 v144, v142, v19, v144 op_sel_hi:[0,1,0]
	v_fma_mix_f32 v145, v143, v19, v145 op_sel:[0,1,0] op_sel_hi:[0,1,0]
	v_add_f32_e32 v148, v144, v145
	v_readlane_b32 s29, v36, s28
	s_add_u32 s28, s28, 1
	s_mul_hi_u32 s27, s29, 0x640
	s_mul_i32 s26, s29, 0x640
	s_add_u32 s26, s16, s26
	s_addc_u32 s27, s17, s27
	global_load_dwordx4 v[64:67], v2, s[26:27]
	global_load_dwordx2 v[68:69], v2, s[26:27] offset:16
	global_load_ubyte v70, v3, s[26:27]
	s_waitcnt vmcnt(21)
	v_lshlrev_b32_e32 v192, 23, v78
	v_cvt_scalef32_pk32_f32_fp6 v[112:143], v[72:77], v192
	v_fma_mix_f32 v144, v112, v4, 0 op_sel_hi:[0,1,0]
	v_fma_mix_f32 v145, v113, v4, 0 op_sel:[0,1,0] op_sel_hi:[0,1,0]
	v_fma_mix_f32 v144, v114, v5, v144 op_sel_hi:[0,1,0]
	v_fma_mix_f32 v145, v115, v5, v145 op_sel:[0,1,0] op_sel_hi:[0,1,0]
	v_fma_mix_f32 v144, v116, v6, v144 op_sel_hi:[0,1,0]
	v_fma_mix_f32 v145, v117, v6, v145 op_sel:[0,1,0] op_sel_hi:[0,1,0]
	v_fma_mix_f32 v144, v118, v7, v144 op_sel_hi:[0,1,0]
	v_fma_mix_f32 v145, v119, v7, v145 op_sel:[0,1,0] op_sel_hi:[0,1,0]
	v_fma_mix_f32 v144, v120, v8, v144 op_sel_hi:[0,1,0]
	v_fma_mix_f32 v145, v121, v8, v145 op_sel:[0,1,0] op_sel_hi:[0,1,0]
	v_fma_mix_f32 v144, v122, v9, v144 op_sel_hi:[0,1,0]
	v_fma_mix_f32 v145, v123, v9, v145 op_sel:[0,1,0] op_sel_hi:[0,1,0]
	v_fma_mix_f32 v144, v124, v10, v144 op_sel_hi:[0,1,0]
	v_fma_mix_f32 v145, v125, v10, v145 op_sel:[0,1,0] op_sel_hi:[0,1,0]
	v_fma_mix_f32 v144, v126, v11, v144 op_sel_hi:[0,1,0]
	v_fma_mix_f32 v145, v127, v11, v145 op_sel:[0,1,0] op_sel_hi:[0,1,0]
	v_fma_mix_f32 v144, v128, v12, v144 op_sel_hi:[0,1,0]
	v_fma_mix_f32 v145, v129, v12, v145 op_sel:[0,1,0] op_sel_hi:[0,1,0]
	v_fma_mix_f32 v144, v130, v13, v144 op_sel_hi:[0,1,0]
	v_fma_mix_f32 v145, v131, v13, v145 op_sel:[0,1,0] op_sel_hi:[0,1,0]
	v_fma_mix_f32 v144, v132, v14, v144 op_sel_hi:[0,1,0]
	v_fma_mix_f32 v145, v133, v14, v145 op_sel:[0,1,0] op_sel_hi:[0,1,0]
	v_fma_mix_f32 v144, v134, v15, v144 op_sel_hi:[0,1,0]
	v_fma_mix_f32 v145, v135, v15, v145 op_sel:[0,1,0] op_sel_hi:[0,1,0]
	v_fma_mix_f32 v144, v136, v16, v144 op_sel_hi:[0,1,0]
	v_fma_mix_f32 v145, v137, v16, v145 op_sel:[0,1,0] op_sel_hi:[0,1,0]
	v_fma_mix_f32 v144, v138, v17, v144 op_sel_hi:[0,1,0]
	v_fma_mix_f32 v145, v139, v17, v145 op_sel:[0,1,0] op_sel_hi:[0,1,0]
	v_fma_mix_f32 v144, v140, v18, v144 op_sel_hi:[0,1,0]
	v_fma_mix_f32 v145, v141, v18, v145 op_sel:[0,1,0] op_sel_hi:[0,1,0]
	v_fma_mix_f32 v144, v142, v19, v144 op_sel_hi:[0,1,0]
	v_fma_mix_f32 v145, v143, v19, v145 op_sel:[0,1,0] op_sel_hi:[0,1,0]
	v_add_f32_e32 v149, v144, v145
	v_readlane_b32 s29, v36, s28
	s_add_u32 s28, s28, 1
	s_mul_hi_u32 s27, s29, 0x640
	s_mul_i32 s26, s29, 0x640
	s_add_u32 s26, s16, s26
	s_addc_u32 s27, s17, s27
	global_load_dwordx4 v[72:75], v2, s[26:27]
	global_load_dwordx2 v[76:77], v2, s[26:27] offset:16
	global_load_ubyte v78, v3, s[26:27]
	s_waitcnt vmcnt(21)
; #define PB_FENCE asm volatile("" ::: "memory")
; __device__ __forceinline__ void ph_peer_apply(const Params& P, int layer, float* xlat, float* xctx_in, float* xctx_out, int nrows, bool write_next, char* smem, float* xlat_out = nullptr) {
;     ...
;     constexpr int NG = NSEL / PB_G;
;     PB_LOAD(bufA, tu, 0);
;     for (int gq = 0; gq < NG; gq += 2) {
;       PB_LOAD(bufB, tu, gq + 1); PB_FENCE;
;       PB_DOT(bufA, gq);
;       if (gq + 2 < NG) PB_LOAD(bufA, tu, gq + 2);
;       PB_FENCE;
;       PB_DOT(bufB, gq + 1);
;     }
	v_lshlrev_b32_e32 v192, 23, v86
	v_cvt_scalef32_pk32_f32_fp6 v[112:143], v[80:85], v192
	v_fma_mix_f32 v144, v112, v4, 0 op_sel_hi:[0,1,0]
	v_fma_mix_f32 v145, v113, v4, 0 op_sel:[0,1,0] op_sel_hi:[0,1,0]
	v_fma_mix_f32 v144, v114, v5, v144 op_sel_hi:[0,1,0]
	v_fma_mix_f32 v145, v115, v5, v145 op_sel:[0,1,0] op_sel_hi:[0,1,0]
	v_fma_mix_f32 v144, v116, v6, v144 op_sel_hi:[0,1,0]
	v_fma_mix_f32 v145, v117, v6, v145 op_sel:[0,1,0] op_sel_hi:[0,1,0]
	v_fma_mix_f32 v144, v118, v7, v144 op_sel_hi:[0,1,0]
	v_fma_mix_f32 v145, v119, v7, v145 op_sel:[0,1,0] op_sel_hi:[0,1,0]
	v_fma_mix_f32 v144, v120, v8, v144 op_sel_hi:[0,1,0]
	v_fma_mix_f32 v145, v121, v8, v145 op_sel:[0,1,0] op_sel_hi:[0,1,0]
	v_fma_mix_f32 v144, v122, v9, v144 op_sel_hi:[0,1,0]
	v_fma_mix_f32 v145, v123, v9, v145 op_sel:[0,1,0] op_sel_hi:[0,1,0]
	v_fma_mix_f32 v144, v124, v10, v144 op_sel_hi:[0,1,0]
	v_fma_mix_f32 v145, v125, v10, v145 op_sel:[0,1,0] op_sel_hi:[0,1,0]
	v_fma_mix_f32 v144, v126, v11, v144 op_sel_hi:[0,1,0]
	v_fma_mix_f32 v145, v127, v11, v145 op_sel:[0,1,0] op_sel_hi:[0,1,0]
	v_fma_mix_f32 v144, v128, v12, v144 op_sel_hi:[0,1,0]
	v_fma_mix_f32 v145, v129, v12, v145 op_sel:[0,1,0] op_sel_hi:[0,1,0]
	v_fma_mix_f32 v144, v130, v13, v144 op_sel_hi:[0,1,0]
	v_fma_mix_f32 v145, v131, v13, v145 op_sel:[0,1,0] op_sel_hi:[0,1,0]
	v_fma_mix_f32 v144, v132, v14, v144 op_sel_hi:[0,1,0]
	v_fma_mix_f32 v145, v133, v14, v145 op_sel:[0,1,0] op_sel_hi:[0,1,0]
	v_fma_mix_f32 v144, v134, v15, v144 op_sel_hi:[0,1,0]
	v_fma_mix_f32 v145, v135, v15, v145 op_sel:[0,1,0] op_sel_hi:[0,1,0]
	v_fma_mix_f32 v144, v136, v16, v144 op_sel_hi:[0,1,0]
	v_fma_mix_f32 v145, v137, v16, v145 op_sel:[0,1,0] op_sel_hi:[0,1,0]
	v_fma_mix_f32 v144, v138, v17, v144 op_sel_hi:[0,1,0]
	v_fma_mix_f32 v145, v139, v17, v145 op_sel:[0,1,0] op_sel_hi:[0,1,0]
	v_fma_mix_f32 v144, v140, v18, v144 op_sel_hi:[0,1,0]
	v_fma_mix_f32 v145, v141, v18, v145 op_sel:[0,1,0] op_sel_hi:[0,1,0]
	v_fma_mix_f32 v144, v142, v19, v144 op_sel_hi:[0,1,0]
	v_fma_mix_f32 v145, v143, v19, v145 op_sel:[0,1,0] op_sel_hi:[0,1,0]
	v_add_f32_e32 v150, v144, v145
	v_readlane_b32 s29, v36, s28
	s_add_u32 s28, s28, 1
	s_mul_hi_u32 s27, s29, 0x640
	s_mul_i32 s26, s29, 0x640
	s_add_u32 s26, s16, s26
	s_addc_u32 s27, s17, s27
	global_load_dwordx4 v[80:83], v2, s[26:27]
	global_load_dwordx2 v[84:85], v2, s[26:27] offset:16
	global_load_ubyte v86, v3, s[26:27]
	s_waitcnt vmcnt(21)
	v_lshlrev_b32_e32 v192, 23, v94
	v_cvt_scalef32_pk32_f32_fp6 v[112:143], v[88:93], v192
	v_fma_mix_f32 v144, v112, v4, 0 op_sel_hi:[0,1,0]
	v_fma_mix_f32 v145, v113, v4, 0 op_sel:[0,1,0] op_sel_hi:[0,1,0]
	v_fma_mix_f32 v144, v114, v5, v144 op_sel_hi:[0,1,0]
	v_fma_mix_f32 v145, v115, v5, v145 op_sel:[0,1,0] op_sel_hi:[0,1,0]
	v_fma_mix_f32 v144, v116, v6, v144 op_sel_hi:[0,1,0]
	v_fma_mix_f32 v145, v117, v6, v145 op_sel:[0,1,0] op_sel_hi:[0,1,0]
	v_fma_mix_f32 v144, v118, v7, v144 op_sel_hi:[0,1,0]
	v_fma_mix_f32 v145, v119, v7, v145 op_sel:[0,1,0] op_sel_hi:[0,1,0]
	v_fma_mix_f32 v144, v120, v8, v144 op_sel_hi:[0,1,0]
	v_fma_mix_f32 v145, v121, v8, v145 op_sel:[0,1,0] op_sel_hi:[0,1,0]
	v_fma_mix_f32 v144, v122, v9, v144 op_sel_hi:[0,1,0]
	v_fma_mix_f32 v145, v123, v9, v145 op_sel:[0,1,0] op_sel_hi:[0,1,0]
	v_fma_mix_f32 v144, v124, v10, v144 op_sel_hi:[0,1,0]
	v_fma_mix_f32 v145, v125, v10, v145 op_sel:[0,1,0] op_sel_hi:[0,1,0]
	v_fma_mix_f32 v144, v126, v11, v144 op_sel_hi:[0,1,0]
	v_fma_mix_f32 v145, v127, v11, v145 op_sel:[0,1,0] op_sel_hi:[0,1,0]
	v_fma_mix_f32 v144, v128, v12, v144 op_sel_hi:[0,1,0]
	v_fma_mix_f32 v145, v129, v12, v145 op_sel:[0,1,0] op_sel_hi:[0,1,0]
	v_fma_mix_f32 v144, v130, v13, v144 op_sel_hi:[0,1,0]
	v_fma_mix_f32 v145, v131, v13, v145 op_sel:[0,1,0] op_sel_hi:[0,1,0]
	v_fma_mix_f32 v144, v132, v14, v144 op_sel_hi:[0,1,0]
	v_fma_mix_f32 v145, v133, v14, v145 op_sel:[0,1,0] op_sel_hi:[0,1,0]
	v_fma_mix_f32 v144, v134, v15, v144 op_sel_hi:[0,1,0]
	v_fma_mix_f32 v145, v135, v15, v145 op_sel:[0,1,0] op_sel_hi:[0,1,0]
	v_fma_mix_f32 v144, v136, v16, v144 op_sel_hi:[0,1,0]
	v_fma_mix_f32 v145, v137, v16, v145 op_sel:[0,1,0] op_sel_hi:[0,1,0]
	v_fma_mix_f32 v144, v138, v17, v144 op_sel_hi:[0,1,0]
	v_fma_mix_f32 v145, v139, v17, v145 op_sel:[0,1,0] op_sel_hi:[0,1,0]
	v_fma_mix_f32 v144, v140, v18, v144 op_sel_hi:[0,1,0]
	v_fma_mix_f32 v145, v141, v18, v145 op_sel:[0,1,0] op_sel_hi:[0,1,0]
	v_fma_mix_f32 v144, v142, v19, v144 op_sel_hi:[0,1,0]
	v_fma_mix_f32 v145, v143, v19, v145 op_sel:[0,1,0] op_sel_hi:[0,1,0]
	v_add_f32_e32 v151, v144, v145
	v_readlane_b32 s29, v36, s28
	s_add_u32 s28, s28, 1
	s_mul_hi_u32 s27, s29, 0x640
	s_mul_i32 s26, s29, 0x640
	s_add_u32 s26, s16, s26
	s_addc_u32 s27, s17, s27
	global_load_dwordx4 v[88:91], v2, s[26:27]
	global_load_dwordx2 v[92:93], v2, s[26:27] offset:16
	global_load_ubyte v94, v3, s[26:27]
	s_waitcnt vmcnt(21)
; __device__ __forceinline__ float row_sum16(float v) { v += __shfl_xor(v, 1); v += __shfl_xor(v, 2); v += __shfl_xor(v, 4); v += __shfl_xor(v, 8); return v; }
; __device__ __forceinline__ float wave_sum(float v) { v = row_sum16(v); v += __shfl_xor(v, 16); v += __shfl_xor(v, 32); return v; }
; #define PB_FENCE asm volatile("" ::: "memory")
; __device__ __forceinline__ float row_sum16(float v) { v += dppf<0xB1>(v); v += dppf<0x4E>(v); v += dppf<0x124>(v); v += dppf<0x128>(v); return v; }
; __device__ __forceinline__ float wave_sum(float v) {
;   v = row_sum16(v);
;   const float r0 = __builtin_bit_cast(float, __builtin_amdgcn_readlane(__builtin_bit_cast(int, v), 0));
;   const float r1 = __builtin_bit_cast(float, __builtin_amdgcn_readlane(__builtin_bit_cast(int, v), 16));
;   const float r2 = __builtin_bit_cast(float, __builtin_amdgcn_readlane(__builtin_bit_cast(int, v), 32));
;   const float r3 = __builtin_bit_cast(float, __builtin_amdgcn_readlane(__builtin_bit_cast(int, v), 48));
;   return (r0 + r1) + (r2 + r3);
; }
; __device__ __forceinline__ void ph_peer_apply(const Params& P, int layer, float* xlat, float* xctx_in, float* xctx_out, int nrows, bool write_next, char* smem, float* xlat_out = nullptr) {
;     ...
;     constexpr int NG = NSEL / PB_G;
;     PB_LOAD(bufA, tu, 0);
;     for (int gq = 0; gq < NG; gq += 2) {
;       PB_LOAD(bufB, tu, gq + 1); PB_FENCE;
;       PB_DOT(bufA, gq);
;       if (gq + 2 < NG) PB_LOAD(bufA, tu, gq + 2);
;       PB_FENCE;
;       PB_DOT(bufB, gq + 1);
;     }
	v_lshlrev_b32_e32 v192, 23, v102
	v_cvt_scalef32_pk32_f32_fp6 v[112:143], v[96:101], v192
	v_fma_mix_f32 v144, v112, v4, 0 op_sel_hi:[0,1,0]
	v_fma_mix_f32 v145, v113, v4, 0 op_sel:[0,1,0] op_sel_hi:[0,1,0]
	v_fma_mix_f32 v144, v114, v5, v144 op_sel_hi:[0,1,0]
	v_fma_mix_f32 v145, v115, v5, v145 op_sel:[0,1,0] op_sel_hi:[0,1,0]
	v_fma_mix_f32 v144, v116, v6, v144 op_sel_hi:[0,1,0]
	v_fma_mix_f32 v145, v117, v6, v145 op_sel:[0,1,0] op_sel_hi:[0,1,0]
	v_fma_mix_f32 v144, v118, v7, v144 op_sel_hi:[0,1,0]
	v_fma_mix_f32 v145, v119, v7, v145 op_sel:[0,1,0] op_sel_hi:[0,1,0]
	v_fma_mix_f32 v144, v120, v8, v144 op_sel_hi:[0,1,0]
	v_fma_mix_f32 v145, v121, v8, v145 op_sel:[0,1,0] op_sel_hi:[0,1,0]
	v_fma_mix_f32 v144, v122, v9, v144 op_sel_hi:[0,1,0]
	v_fma_mix_f32 v145, v123, v9, v145 op_sel:[0,1,0] op_sel_hi:[0,1,0]
	v_fma_mix_f32 v144, v124, v10, v144 op_sel_hi:[0,1,0]
	v_fma_mix_f32 v145, v125, v10, v145 op_sel:[0,1,0] op_sel_hi:[0,1,0]
	v_fma_mix_f32 v144, v126, v11, v144 op_sel_hi:[0,1,0]
	v_fma_mix_f32 v145, v127, v11, v145 op_sel:[0,1,0] op_sel_hi:[0,1,0]
	v_fma_mix_f32 v144, v128, v12, v144 op_sel_hi:[0,1,0]
	v_fma_mix_f32 v145, v129, v12, v145 op_sel:[0,1,0] op_sel_hi:[0,1,0]
	v_fma_mix_f32 v144, v130, v13, v144 op_sel_hi:[0,1,0]
	v_fma_mix_f32 v145, v131, v13, v145 op_sel:[0,1,0] op_sel_hi:[0,1,0]
	v_fma_mix_f32 v144, v132, v14, v144 op_sel_hi:[0,1,0]
	v_fma_mix_f32 v145, v133, v14, v145 op_sel:[0,1,0] op_sel_hi:[0,1,0]
	v_fma_mix_f32 v144, v134, v15, v144 op_sel_hi:[0,1,0]
	v_fma_mix_f32 v145, v135, v15, v145 op_sel:[0,1,0] op_sel_hi:[0,1,0]
	v_fma_mix_f32 v144, v136, v16, v144 op_sel_hi:[0,1,0]
	v_fma_mix_f32 v145, v137, v16, v145 op_sel:[0,1,0] op_sel_hi:[0,1,0]
	v_fma_mix_f32 v144, v138, v17, v144 op_sel_hi:[0,1,0]
	v_fma_mix_f32 v145, v139, v17, v145 op_sel:[0,1,0] op_sel_hi:[0,1,0]
	v_fma_mix_f32 v144, v140, v18, v144 op_sel_hi:[0,1,0]
	v_fma_mix_f32 v145, v141, v18, v145 op_sel:[0,1,0] op_sel_hi:[0,1,0]
	v_fma_mix_f32 v144, v142, v19, v144 op_sel_hi:[0,1,0]
	v_fma_mix_f32 v145, v143, v19, v145 op_sel:[0,1,0] op_sel_hi:[0,1,0]
	v_add_f32_e32 v152, v144, v145
	v_readlane_b32 s29, v36, s28
	s_add_u32 s28, s28, 1
	s_mul_hi_u32 s27, s29, 0x640
	s_mul_i32 s26, s29, 0x640
	s_add_u32 s26, s16, s26
	s_addc_u32 s27, s17, s27
	global_load_dwordx4 v[96:99], v2, s[26:27]
	global_load_dwordx2 v[100:101], v2, s[26:27] offset:16
	global_load_ubyte v102, v3, s[26:27]
	s_waitcnt vmcnt(21)
	v_lshlrev_b32_e32 v192, 23, v110
	v_cvt_scalef32_pk32_f32_fp6 v[112:143], v[104:109], v192
	v_fma_mix_f32 v144, v112, v4, 0 op_sel_hi:[0,1,0]
	v_fma_mix_f32 v145, v113, v4, 0 op_sel:[0,1,0] op_sel_hi:[0,1,0]
	v_fma_mix_f32 v144, v114, v5, v144 op_sel_hi:[0,1,0]
	v_fma_mix_f32 v145, v115, v5, v145 op_sel:[0,1,0] op_sel_hi:[0,1,0]
	v_fma_mix_f32 v144, v116, v6, v144 op_sel_hi:[0,1,0]
	v_fma_mix_f32 v145, v117, v6, v145 op_sel:[0,1,0] op_sel_hi:[0,1,0]
	v_fma_mix_f32 v144, v118, v7, v144 op_sel_hi:[0,1,0]
	v_fma_mix_f32 v145, v119, v7, v145 op_sel:[0,1,0] op_sel_hi:[0,1,0]
	v_fma_mix_f32 v144, v120, v8, v144 op_sel_hi:[0,1,0]
	v_fma_mix_f32 v145, v121, v8, v145 op_sel:[0,1,0] op_sel_hi:[0,1,0]
	v_fma_mix_f32 v144, v122, v9, v144 op_sel_hi:[0,1,0]
	v_fma_mix_f32 v145, v123, v9, v145 op_sel:[0,1,0] op_sel_hi:[0,1,0]
	v_fma_mix_f32 v144, v124, v10, v144 op_sel_hi:[0,1,0]
	v_fma_mix_f32 v145, v125, v10, v145 op_sel:[0,1,0] op_sel_hi:[0,1,0]
	v_fma_mix_f32 v144, v126, v11, v144 op_sel_hi:[0,1,0]
	v_fma_mix_f32 v145, v127, v11, v145 op_sel:[0,1,0] op_sel_hi:[0,1,0]
	v_fma_mix_f32 v144, v128, v12, v144 op_sel_hi:[0,1,0]
	v_fma_mix_f32 v145, v129, v12, v145 op_sel:[0,1,0] op_sel_hi:[0,1,0]
	v_fma_mix_f32 v144, v130, v13, v144 op_sel_hi:[0,1,0]
	v_fma_mix_f32 v145, v131, v13, v145 op_sel:[0,1,0] op_sel_hi:[0,1,0]
	v_fma_mix_f32 v144, v132, v14, v144 op_sel_hi:[0,1,0]
	v_fma_mix_f32 v145, v133, v14, v145 op_sel:[0,1,0] op_sel_hi:[0,1,0]
	v_fma_mix_f32 v144, v134, v15, v144 op_sel_hi:[0,1,0]
	v_fma_mix_f32 v145, v135, v15, v145 op_sel:[0,1,0] op_sel_hi:[0,1,0]
	v_fma_mix_f32 v144, v136, v16, v144 op_sel_hi:[0,1,0]
	v_fma_mix_f32 v145, v137, v16, v145 op_sel:[0,1,0] op_sel_hi:[0,1,0]
	v_fma_mix_f32 v144, v138, v17, v144 op_sel_hi:[0,1,0]
	v_fma_mix_f32 v145, v139, v17, v145 op_sel:[0,1,0] op_sel_hi:[0,1,0]
	v_fma_mix_f32 v144, v140, v18, v144 op_sel_hi:[0,1,0]
	v_fma_mix_f32 v145, v141, v18, v145 op_sel:[0,1,0] op_sel_hi:[0,1,0]
	v_fma_mix_f32 v144, v142, v19, v144 op_sel_hi:[0,1,0]
	v_fma_mix_f32 v145, v143, v19, v145 op_sel:[0,1,0] op_sel_hi:[0,1,0]
	v_add_f32_e32 v153, v144, v145
	v_readlane_b32 s29, v36, s28
	s_add_u32 s28, s28, 1
	s_mul_hi_u32 s27, s29, 0x640
	s_mul_i32 s26, s29, 0x640
	s_add_u32 s26, s16, s26
	s_addc_u32 s27, s17, s27
	global_load_dwordx4 v[104:107], v2, s[26:27]
	global_load_dwordx2 v[108:109], v2, s[26:27] offset:16
	global_load_ubyte v110, v3, s[26:27]
	v_add_f32_dpp v146, v146, v146 row_ror:8 row_mask:0xf bank_mask:0xf bound_ctrl:1
	v_add_f32_dpp v147, v147, v147 row_ror:8 row_mask:0xf bank_mask:0xf bound_ctrl:1
	v_add_f32_dpp v148, v148, v148 row_ror:8 row_mask:0xf bank_mask:0xf bound_ctrl:1
	v_add_f32_dpp v149, v149, v149 row_ror:8 row_mask:0xf bank_mask:0xf bound_ctrl:1
	v_add_f32_dpp v146, v150, v150 row_ror:8 row_mask:0xf bank_mask:0xc bound_ctrl:1
	v_add_f32_dpp v147, v151, v151 row_ror:8 row_mask:0xf bank_mask:0xc bound_ctrl:1
	v_add_f32_dpp v148, v152, v152 row_ror:8 row_mask:0xf bank_mask:0xc bound_ctrl:1
	v_add_f32_dpp v149, v153, v153 row_ror:8 row_mask:0xf bank_mask:0xc bound_ctrl:1
	v_add_f32_dpp v146, v146, v146 row_half_mirror row_mask:0xf bank_mask:0xf bound_ctrl:1
	v_add_f32_dpp v147, v147, v147 row_half_mirror row_mask:0xf bank_mask:0xf bound_ctrl:1
	v_add_f32_dpp v146, v148, v148 row_half_mirror row_mask:0xf bank_mask:0xa bound_ctrl:1
	v_add_f32_dpp v147, v149, v149 row_half_mirror row_mask:0xf bank_mask:0xa bound_ctrl:1
	s_nop 1
	v_add_f32_dpp v146, v146, v146 quad_perm:[1,0,3,2] row_mask:0xf bank_mask:0xf bound_ctrl:1
	v_add_f32_dpp v147, v147, v147 quad_perm:[1,0,3,2] row_mask:0xf bank_mask:0xf bound_ctrl:1
	s_nop 0
	v_add_f32_dpp v146, v146, v146 quad_perm:[2,3,0,1] row_mask:0xf bank_mask:0xf bound_ctrl:1
	v_add_f32_dpp v147, v147, v147 quad_perm:[2,3,0,1] row_mask:0xf bank_mask:0xf bound_ctrl:1
	v_mov_b32_e32 v193, v146
	v_mov_b32_e32 v194, v147
	s_nop 1
	v_permlane32_swap_b32_e32 v193, v146
	v_permlane32_swap_b32_e32 v194, v147
	v_add_f32_e32 v146, v146, v193
	v_add_f32_e32 v147, v147, v194
	v_mov_b32_e32 v193, v146
	v_mov_b32_e32 v194, v147
	s_nop 1
	v_permlane16_swap_b32_e32 v193, v146
	v_permlane16_swap_b32_e32 v194, v147
	v_add_f32_e32 v146, v146, v193
	v_add_f32_e32 v147, v147, v194
	v_cndmask_b32_e64 v146, v146, v147, s[34:35]
	s_mov_b64 exec, s[46:47]
	ds_write_b32 v229, v146
	s_mov_b64 exec, -1
	v_add_u32_e32 v229, 32, v229
	s_sub_u32 s30, s30, 1
	s_cmp_lg_u32 s30, 0
	s_cbranch_scc1 .Lap0_s1_loop1
	s_waitcnt vmcnt(21)
	v_lshlrev_b32_e32 v192, 23, v54
	v_cvt_scalef32_pk32_f32_fp6 v[112:143], v[48:53], v192
	v_fma_mix_f32 v144, v112, v4, 0 op_sel_hi:[0,1,0]
	v_fma_mix_f32 v145, v113, v4, 0 op_sel:[0,1,0] op_sel_hi:[0,1,0]
	v_fma_mix_f32 v144, v114, v5, v144 op_sel_hi:[0,1,0]
	v_fma_mix_f32 v145, v115, v5, v145 op_sel:[0,1,0] op_sel_hi:[0,1,0]
	v_fma_mix_f32 v144, v116, v6, v144 op_sel_hi:[0,1,0]
	v_fma_mix_f32 v145, v117, v6, v145 op_sel:[0,1,0] op_sel_hi:[0,1,0]
	v_fma_mix_f32 v144, v118, v7, v144 op_sel_hi:[0,1,0]
	v_fma_mix_f32 v145, v119, v7, v145 op_sel:[0,1,0] op_sel_hi:[0,1,0]
	v_fma_mix_f32 v144, v120, v8, v144 op_sel_hi:[0,1,0]
	v_fma_mix_f32 v145, v121, v8, v145 op_sel:[0,1,0] op_sel_hi:[0,1,0]
	v_fma_mix_f32 v144, v122, v9, v144 op_sel_hi:[0,1,0]
	v_fma_mix_f32 v145, v123, v9, v145 op_sel:[0,1,0] op_sel_hi:[0,1,0]
	v_fma_mix_f32 v144, v124, v10, v144 op_sel_hi:[0,1,0]
	v_fma_mix_f32 v145, v125, v10, v145 op_sel:[0,1,0] op_sel_hi:[0,1,0]
	v_fma_mix_f32 v144, v126, v11, v144 op_sel_hi:[0,1,0]
	v_fma_mix_f32 v145, v127, v11, v145 op_sel:[0,1,0] op_sel_hi:[0,1,0]
	v_fma_mix_f32 v144, v128, v12, v144 op_sel_hi:[0,1,0]
	v_fma_mix_f32 v145, v129, v12, v145 op_sel:[0,1,0] op_sel_hi:[0,1,0]
	v_fma_mix_f32 v144, v130, v13, v144 op_sel_hi:[0,1,0]
	v_fma_mix_f32 v145, v131, v13, v145 op_sel:[0,1,0] op_sel_hi:[0,1,0]
	v_fma_mix_f32 v144, v132, v14, v144 op_sel_hi:[0,1,0]
	v_fma_mix_f32 v145, v133, v14, v145 op_sel:[0,1,0] op_sel_hi:[0,1,0]
	v_fma_mix_f32 v144, v134, v15, v144 op_sel_hi:[0,1,0]
	v_fma_mix_f32 v145, v135, v15, v145 op_sel:[0,1,0] op_sel_hi:[0,1,0]
	v_fma_mix_f32 v144, v136, v16, v144 op_sel_hi:[0,1,0]
	v_fma_mix_f32 v145, v137, v16, v145 op_sel:[0,1,0] op_sel_hi:[0,1,0]
	v_fma_mix_f32 v144, v138, v17, v144 op_sel_hi:[0,1,0]
	v_fma_mix_f32 v145, v139, v17, v145 op_sel:[0,1,0] op_sel_hi:[0,1,0]
	v_fma_mix_f32 v144, v140, v18, v144 op_sel_hi:[0,1,0]
	v_fma_mix_f32 v145, v141, v18, v145 op_sel:[0,1,0] op_sel_hi:[0,1,0]
	v_fma_mix_f32 v144, v142, v19, v144 op_sel_hi:[0,1,0]
	v_fma_mix_f32 v145, v143, v19, v145 op_sel:[0,1,0] op_sel_hi:[0,1,0]
	v_add_f32_e32 v146, v144, v145
	s_waitcnt vmcnt(18)
	v_lshlrev_b32_e32 v192, 23, v62
	v_cvt_scalef32_pk32_f32_fp6 v[112:143], v[56:61], v192
	v_fma_mix_f32 v144, v112, v4, 0 op_sel_hi:[0,1,0]
	v_fma_mix_f32 v145, v113, v4, 0 op_sel:[0,1,0] op_sel_hi:[0,1,0]
	v_fma_mix_f32 v144, v114, v5, v144 op_sel_hi:[0,1,0]
	v_fma_mix_f32 v145, v115, v5, v145 op_sel:[0,1,0] op_sel_hi:[0,1,0]
	v_fma_mix_f32 v144, v116, v6, v144 op_sel_hi:[0,1,0]
	v_fma_mix_f32 v145, v117, v6, v145 op_sel:[0,1,0] op_sel_hi:[0,1,0]
	v_fma_mix_f32 v144, v118, v7, v144 op_sel_hi:[0,1,0]
	v_fma_mix_f32 v145, v119, v7, v145 op_sel:[0,1,0] op_sel_hi:[0,1,0]
	v_fma_mix_f32 v144, v120, v8, v144 op_sel_hi:[0,1,0]
	v_fma_mix_f32 v145, v121, v8, v145 op_sel:[0,1,0] op_sel_hi:[0,1,0]
	v_fma_mix_f32 v144, v122, v9, v144 op_sel_hi:[0,1,0]
	v_fma_mix_f32 v145, v123, v9, v145 op_sel:[0,1,0] op_sel_hi:[0,1,0]
	v_fma_mix_f32 v144, v124, v10, v144 op_sel_hi:[0,1,0]
	v_fma_mix_f32 v145, v125, v10, v145 op_sel:[0,1,0] op_sel_hi:[0,1,0]
	v_fma_mix_f32 v144, v126, v11, v144 op_sel_hi:[0,1,0]
	v_fma_mix_f32 v145, v127, v11, v145 op_sel:[0,1,0] op_sel_hi:[0,1,0]
	v_fma_mix_f32 v144, v128, v12, v144 op_sel_hi:[0,1,0]
	v_fma_mix_f32 v145, v129, v12, v145 op_sel:[0,1,0] op_sel_hi:[0,1,0]
	v_fma_mix_f32 v144, v130, v13, v144 op_sel_hi:[0,1,0]
	v_fma_mix_f32 v145, v131, v13, v145 op_sel:[0,1,0] op_sel_hi:[0,1,0]
	v_fma_mix_f32 v144, v132, v14, v144 op_sel_hi:[0,1,0]
	v_fma_mix_f32 v145, v133, v14, v145 op_sel:[0,1,0] op_sel_hi:[0,1,0]
	v_fma_mix_f32 v144, v134, v15, v144 op_sel_hi:[0,1,0]
	v_fma_mix_f32 v145, v135, v15, v145 op_sel:[0,1,0] op_sel_hi:[0,1,0]
	v_fma_mix_f32 v144, v136, v16, v144 op_sel_hi:[0,1,0]
	v_fma_mix_f32 v145, v137, v16, v145 op_sel:[0,1,0] op_sel_hi:[0,1,0]
	v_fma_mix_f32 v144, v138, v17, v144 op_sel_hi:[0,1,0]
	v_fma_mix_f32 v145, v139, v17, v145 op_sel:[0,1,0] op_sel_hi:[0,1,0]
	v_fma_mix_f32 v144, v140, v18, v144 op_sel_hi:[0,1,0]
	v_fma_mix_f32 v145, v141, v18, v145 op_sel:[0,1,0] op_sel_hi:[0,1,0]
	v_fma_mix_f32 v144, v142, v19, v144 op_sel_hi:[0,1,0]
	v_fma_mix_f32 v145, v143, v19, v145 op_sel:[0,1,0] op_sel_hi:[0,1,0]
	v_add_f32_e32 v147, v144, v145
	s_waitcnt vmcnt(15)
	v_lshlrev_b32_e32 v192, 23, v70
	v_cvt_scalef32_pk32_f32_fp6 v[112:143], v[64:69], v192
	v_fma_mix_f32 v144, v112, v4, 0 op_sel_hi:[0,1,0]
	v_fma_mix_f32 v145, v113, v4, 0 op_sel:[0,1,0] op_sel_hi:[0,1,0]
	v_fma_mix_f32 v144, v114, v5, v144 op_sel_hi:[0,1,0]
	v_fma_mix_f32 v145, v115, v5, v145 op_sel:[0,1,0] op_sel_hi:[0,1,0]
	v_fma_mix_f32 v144, v116, v6, v144 op_sel_hi:[0,1,0]
	v_fma_mix_f32 v145, v117, v6, v145 op_sel:[0,1,0] op_sel_hi:[0,1,0]
	v_fma_mix_f32 v144, v118, v7, v144 op_sel_hi:[0,1,0]
	v_fma_mix_f32 v145, v119, v7, v145 op_sel:[0,1,0] op_sel_hi:[0,1,0]
	v_fma_mix_f32 v144, v120, v8, v144 op_sel_hi:[0,1,0]
	v_fma_mix_f32 v145, v121, v8, v145 op_sel:[0,1,0] op_sel_hi:[0,1,0]
	v_fma_mix_f32 v144, v122, v9, v144 op_sel_hi:[0,1,0]
	v_fma_mix_f32 v145, v123, v9, v145 op_sel:[0,1,0] op_sel_hi:[0,1,0]
	v_fma_mix_f32 v144, v124, v10, v144 op_sel_hi:[0,1,0]
	v_fma_mix_f32 v145, v125, v10, v145 op_sel:[0,1,0] op_sel_hi:[0,1,0]
	v_fma_mix_f32 v144, v126, v11, v144 op_sel_hi:[0,1,0]
	v_fma_mix_f32 v145, v127, v11, v145 op_sel:[0,1,0] op_sel_hi:[0,1,0]
	v_fma_mix_f32 v144, v128, v12, v144 op_sel_hi:[0,1,0]
	v_fma_mix_f32 v145, v129, v12, v145 op_sel:[0,1,0] op_sel_hi:[0,1,0]
	v_fma_mix_f32 v144, v130, v13, v144 op_sel_hi:[0,1,0]
	v_fma_mix_f32 v145, v131, v13, v145 op_sel:[0,1,0] op_sel_hi:[0,1,0]
	v_fma_mix_f32 v144, v132, v14, v144 op_sel_hi:[0,1,0]
	v_fma_mix_f32 v145, v133, v14, v145 op_sel:[0,1,0] op_sel_hi:[0,1,0]
	v_fma_mix_f32 v144, v134, v15, v144 op_sel_hi:[0,1,0]
	v_fma_mix_f32 v145, v135, v15, v145 op_sel:[0,1,0] op_sel_hi:[0,1,0]
	v_fma_mix_f32 v144, v136, v16, v144 op_sel_hi:[0,1,0]
	v_fma_mix_f32 v145, v137, v16, v145 op_sel:[0,1,0] op_sel_hi:[0,1,0]
	v_fma_mix_f32 v144, v138, v17, v144 op_sel_hi:[0,1,0]
	v_fma_mix_f32 v145, v139, v17, v145 op_sel:[0,1,0] op_sel_hi:[0,1,0]
	v_fma_mix_f32 v144, v140, v18, v144 op_sel_hi:[0,1,0]
	v_fma_mix_f32 v145, v141, v18, v145 op_sel:[0,1,0] op_sel_hi:[0,1,0]
	v_fma_mix_f32 v144, v142, v19, v144 op_sel_hi:[0,1,0]
	v_fma_mix_f32 v145, v143, v19, v145 op_sel:[0,1,0] op_sel_hi:[0,1,0]
	v_add_f32_e32 v148, v144, v145
	s_waitcnt vmcnt(12)
	v_lshlrev_b32_e32 v192, 23, v78
	v_cvt_scalef32_pk32_f32_fp6 v[112:143], v[72:77], v192
	v_fma_mix_f32 v144, v112, v4, 0 op_sel_hi:[0,1,0]
	v_fma_mix_f32 v145, v113, v4, 0 op_sel:[0,1,0] op_sel_hi:[0,1,0]
	v_fma_mix_f32 v144, v114, v5, v144 op_sel_hi:[0,1,0]
	v_fma_mix_f32 v145, v115, v5, v145 op_sel:[0,1,0] op_sel_hi:[0,1,0]
	v_fma_mix_f32 v144, v116, v6, v144 op_sel_hi:[0,1,0]
	v_fma_mix_f32 v145, v117, v6, v145 op_sel:[0,1,0] op_sel_hi:[0,1,0]
	v_fma_mix_f32 v144, v118, v7, v144 op_sel_hi:[0,1,0]
	v_fma_mix_f32 v145, v119, v7, v145 op_sel:[0,1,0] op_sel_hi:[0,1,0]
	v_fma_mix_f32 v144, v120, v8, v144 op_sel_hi:[0,1,0]
	v_fma_mix_f32 v145, v121, v8, v145 op_sel:[0,1,0] op_sel_hi:[0,1,0]
	v_fma_mix_f32 v144, v122, v9, v144 op_sel_hi:[0,1,0]
	v_fma_mix_f32 v145, v123, v9, v145 op_sel:[0,1,0] op_sel_hi:[0,1,0]
	v_fma_mix_f32 v144, v124, v10, v144 op_sel_hi:[0,1,0]
	v_fma_mix_f32 v145, v125, v10, v145 op_sel:[0,1,0] op_sel_hi:[0,1,0]
	v_fma_mix_f32 v144, v126, v11, v144 op_sel_hi:[0,1,0]
	v_fma_mix_f32 v145, v127, v11, v145 op_sel:[0,1,0] op_sel_hi:[0,1,0]
	v_fma_mix_f32 v144, v128, v12, v144 op_sel_hi:[0,1,0]
	v_fma_mix_f32 v145, v129, v12, v145 op_sel:[0,1,0] op_sel_hi:[0,1,0]
	v_fma_mix_f32 v144, v130, v13, v144 op_sel_hi:[0,1,0]
	v_fma_mix_f32 v145, v131, v13, v145 op_sel:[0,1,0] op_sel_hi:[0,1,0]
	v_fma_mix_f32 v144, v132, v14, v144 op_sel_hi:[0,1,0]
	v_fma_mix_f32 v145, v133, v14, v145 op_sel:[0,1,0] op_sel_hi:[0,1,0]
	v_fma_mix_f32 v144, v134, v15, v144 op_sel_hi:[0,1,0]
	v_fma_mix_f32 v145, v135, v15, v145 op_sel:[0,1,0] op_sel_hi:[0,1,0]
	v_fma_mix_f32 v144, v136, v16, v144 op_sel_hi:[0,1,0]
	v_fma_mix_f32 v145, v137, v16, v145 op_sel:[0,1,0] op_sel_hi:[0,1,0]
	v_fma_mix_f32 v144, v138, v17, v144 op_sel_hi:[0,1,0]
	v_fma_mix_f32 v145, v139, v17, v145 op_sel:[0,1,0] op_sel_hi:[0,1,0]
	v_fma_mix_f32 v144, v140, v18, v144 op_sel_hi:[0,1,0]
	v_fma_mix_f32 v145, v141, v18, v145 op_sel:[0,1,0] op_sel_hi:[0,1,0]
	v_fma_mix_f32 v144, v142, v19, v144 op_sel_hi:[0,1,0]
	v_fma_mix_f32 v145, v143, v19, v145 op_sel:[0,1,0] op_sel_hi:[0,1,0]
	v_add_f32_e32 v149, v144, v145
	s_waitcnt vmcnt(9)
	v_lshlrev_b32_e32 v192, 23, v86
	v_cvt_scalef32_pk32_f32_fp6 v[112:143], v[80:85], v192
	v_fma_mix_f32 v144, v112, v4, 0 op_sel_hi:[0,1,0]
	v_fma_mix_f32 v145, v113, v4, 0 op_sel:[0,1,0] op_sel_hi:[0,1,0]
	v_fma_mix_f32 v144, v114, v5, v144 op_sel_hi:[0,1,0]
	v_fma_mix_f32 v145, v115, v5, v145 op_sel:[0,1,0] op_sel_hi:[0,1,0]
	v_fma_mix_f32 v144, v116, v6, v144 op_sel_hi:[0,1,0]
	v_fma_mix_f32 v145, v117, v6, v145 op_sel:[0,1,0] op_sel_hi:[0,1,0]
	v_fma_mix_f32 v144, v118, v7, v144 op_sel_hi:[0,1,0]
	v_fma_mix_f32 v145, v119, v7, v145 op_sel:[0,1,0] op_sel_hi:[0,1,0]
	v_fma_mix_f32 v144, v120, v8, v144 op_sel_hi:[0,1,0]
	v_fma_mix_f32 v145, v121, v8, v145 op_sel:[0,1,0] op_sel_hi:[0,1,0]
	v_fma_mix_f32 v144, v122, v9, v144 op_sel_hi:[0,1,0]
	v_fma_mix_f32 v145, v123, v9, v145 op_sel:[0,1,0] op_sel_hi:[0,1,0]
	v_fma_mix_f32 v144, v124, v10, v144 op_sel_hi:[0,1,0]
	v_fma_mix_f32 v145, v125, v10, v145 op_sel:[0,1,0] op_sel_hi:[0,1,0]
	v_fma_mix_f32 v144, v126, v11, v144 op_sel_hi:[0,1,0]
	v_fma_mix_f32 v145, v127, v11, v145 op_sel:[0,1,0] op_sel_hi:[0,1,0]
	v_fma_mix_f32 v144, v128, v12, v144 op_sel_hi:[0,1,0]
	v_fma_mix_f32 v145, v129, v12, v145 op_sel:[0,1,0] op_sel_hi:[0,1,0]
	v_fma_mix_f32 v144, v130, v13, v144 op_sel_hi:[0,1,0]
	v_fma_mix_f32 v145, v131, v13, v145 op_sel:[0,1,0] op_sel_hi:[0,1,0]
	v_fma_mix_f32 v144, v132, v14, v144 op_sel_hi:[0,1,0]
	v_fma_mix_f32 v145, v133, v14, v145 op_sel:[0,1,0] op_sel_hi:[0,1,0]
	v_fma_mix_f32 v144, v134, v15, v144 op_sel_hi:[0,1,0]
	v_fma_mix_f32 v145, v135, v15, v145 op_sel:[0,1,0] op_sel_hi:[0,1,0]
	v_fma_mix_f32 v144, v136, v16, v144 op_sel_hi:[0,1,0]
	v_fma_mix_f32 v145, v137, v16, v145 op_sel:[0,1,0] op_sel_hi:[0,1,0]
	v_fma_mix_f32 v144, v138, v17, v144 op_sel_hi:[0,1,0]
	v_fma_mix_f32 v145, v139, v17, v145 op_sel:[0,1,0] op_sel_hi:[0,1,0]
	v_fma_mix_f32 v144, v140, v18, v144 op_sel_hi:[0,1,0]
	v_fma_mix_f32 v145, v141, v18, v145 op_sel:[0,1,0] op_sel_hi:[0,1,0]
	v_fma_mix_f32 v144, v142, v19, v144 op_sel_hi:[0,1,0]
	v_fma_mix_f32 v145, v143, v19, v145 op_sel:[0,1,0] op_sel_hi:[0,1,0]
	v_add_f32_e32 v150, v144, v145
	s_waitcnt vmcnt(6)
	v_lshlrev_b32_e32 v192, 23, v94
	v_cvt_scalef32_pk32_f32_fp6 v[112:143], v[88:93], v192
	v_fma_mix_f32 v144, v112, v4, 0 op_sel_hi:[0,1,0]
	v_fma_mix_f32 v145, v113, v4, 0 op_sel:[0,1,0] op_sel_hi:[0,1,0]
	v_fma_mix_f32 v144, v114, v5, v144 op_sel_hi:[0,1,0]
	v_fma_mix_f32 v145, v115, v5, v145 op_sel:[0,1,0] op_sel_hi:[0,1,0]
	v_fma_mix_f32 v144, v116, v6, v144 op_sel_hi:[0,1,0]
	v_fma_mix_f32 v145, v117, v6, v145 op_sel:[0,1,0] op_sel_hi:[0,1,0]
	v_fma_mix_f32 v144, v118, v7, v144 op_sel_hi:[0,1,0]
	v_fma_mix_f32 v145, v119, v7, v145 op_sel:[0,1,0] op_sel_hi:[0,1,0]
	v_fma_mix_f32 v144, v120, v8, v144 op_sel_hi:[0,1,0]
	v_fma_mix_f32 v145, v121, v8, v145 op_sel:[0,1,0] op_sel_hi:[0,1,0]
	v_fma_mix_f32 v144, v122, v9, v144 op_sel_hi:[0,1,0]
	v_fma_mix_f32 v145, v123, v9, v145 op_sel:[0,1,0] op_sel_hi:[0,1,0]
	v_fma_mix_f32 v144, v124, v10, v144 op_sel_hi:[0,1,0]
	v_fma_mix_f32 v145, v125, v10, v145 op_sel:[0,1,0] op_sel_hi:[0,1,0]
	v_fma_mix_f32 v144, v126, v11, v144 op_sel_hi:[0,1,0]
	v_fma_mix_f32 v145, v127, v11, v145 op_sel:[0,1,0] op_sel_hi:[0,1,0]
	v_fma_mix_f32 v144, v128, v12, v144 op_sel_hi:[0,1,0]
	v_fma_mix_f32 v145, v129, v12, v145 op_sel:[0,1,0] op_sel_hi:[0,1,0]
	v_fma_mix_f32 v144, v130, v13, v144 op_sel_hi:[0,1,0]
	v_fma_mix_f32 v145, v131, v13, v145 op_sel:[0,1,0] op_sel_hi:[0,1,0]
	v_fma_mix_f32 v144, v132, v14, v144 op_sel_hi:[0,1,0]
	v_fma_mix_f32 v145, v133, v14, v145 op_sel:[0,1,0] op_sel_hi:[0,1,0]
	v_fma_mix_f32 v144, v134, v15, v144 op_sel_hi:[0,1,0]
	v_fma_mix_f32 v145, v135, v15, v145 op_sel:[0,1,0] op_sel_hi:[0,1,0]
	v_fma_mix_f32 v144, v136, v16, v144 op_sel_hi:[0,1,0]
	v_fma_mix_f32 v145, v137, v16, v145 op_sel:[0,1,0] op_sel_hi:[0,1,0]
	v_fma_mix_f32 v144, v138, v17, v144 op_sel_hi:[0,1,0]
	v_fma_mix_f32 v145, v139, v17, v145 op_sel:[0,1,0] op_sel_hi:[0,1,0]
	v_fma_mix_f32 v144, v140, v18, v144 op_sel_hi:[0,1,0]
	v_fma_mix_f32 v145, v141, v18, v145 op_sel:[0,1,0] op_sel_hi:[0,1,0]
	v_fma_mix_f32 v144, v142, v19, v144 op_sel_hi:[0,1,0]
	v_fma_mix_f32 v145, v143, v19, v145 op_sel:[0,1,0] op_sel_hi:[0,1,0]
	v_add_f32_e32 v151, v144, v145
	s_waitcnt vmcnt(3)
; __device__ __forceinline__ float row_sum16(float v) { v += __shfl_xor(v, 1); v += __shfl_xor(v, 2); v += __shfl_xor(v, 4); v += __shfl_xor(v, 8); return v; }
; __device__ __forceinline__ float wave_sum(float v) { v = row_sum16(v); v += __shfl_xor(v, 16); v += __shfl_xor(v, 32); return v; }
; __device__ __forceinline__ float row_sum16(float v) { v += dppf<0xB1>(v); v += dppf<0x4E>(v); v += dppf<0x124>(v); v += dppf<0x128>(v); return v; }
; __device__ __forceinline__ float wave_sum(float v) {
;   v = row_sum16(v);
;   const float r0 = __builtin_bit_cast(float, __builtin_amdgcn_readlane(__builtin_bit_cast(int, v), 0));
;   const float r1 = __builtin_bit_cast(float, __builtin_amdgcn_readlane(__builtin_bit_cast(int, v), 16));
;   const float r2 = __builtin_bit_cast(float, __builtin_amdgcn_readlane(__builtin_bit_cast(int, v), 32));
;   const float r3 = __builtin_bit_cast(float, __builtin_amdgcn_readlane(__builtin_bit_cast(int, v), 48));
;   return (r0 + r1) + (r2 + r3);
; }
	v_lshlrev_b32_e32 v192, 23, v102
	v_cvt_scalef32_pk32_f32_fp6 v[112:143], v[96:101], v192
	v_fma_mix_f32 v144, v112, v4, 0 op_sel_hi:[0,1,0]
	v_fma_mix_f32 v145, v113, v4, 0 op_sel:[0,1,0] op_sel_hi:[0,1,0]
	v_fma_mix_f32 v144, v114, v5, v144 op_sel_hi:[0,1,0]
	v_fma_mix_f32 v145, v115, v5, v145 op_sel:[0,1,0] op_sel_hi:[0,1,0]
	v_fma_mix_f32 v144, v116, v6, v144 op_sel_hi:[0,1,0]
	v_fma_mix_f32 v145, v117, v6, v145 op_sel:[0,1,0] op_sel_hi:[0,1,0]
	v_fma_mix_f32 v144, v118, v7, v144 op_sel_hi:[0,1,0]
	v_fma_mix_f32 v145, v119, v7, v145 op_sel:[0,1,0] op_sel_hi:[0,1,0]
	v_fma_mix_f32 v144, v120, v8, v144 op_sel_hi:[0,1,0]
	v_fma_mix_f32 v145, v121, v8, v145 op_sel:[0,1,0] op_sel_hi:[0,1,0]
	v_fma_mix_f32 v144, v122, v9, v144 op_sel_hi:[0,1,0]
	v_fma_mix_f32 v145, v123, v9, v145 op_sel:[0,1,0] op_sel_hi:[0,1,0]
	v_fma_mix_f32 v144, v124, v10, v144 op_sel_hi:[0,1,0]
	v_fma_mix_f32 v145, v125, v10, v145 op_sel:[0,1,0] op_sel_hi:[0,1,0]
	v_fma_mix_f32 v144, v126, v11, v144 op_sel_hi:[0,1,0]
	v_fma_mix_f32 v145, v127, v11, v145 op_sel:[0,1,0] op_sel_hi:[0,1,0]
	v_fma_mix_f32 v144, v128, v12, v144 op_sel_hi:[0,1,0]
	v_fma_mix_f32 v145, v129, v12, v145 op_sel:[0,1,0] op_sel_hi:[0,1,0]
	v_fma_mix_f32 v144, v130, v13, v144 op_sel_hi:[0,1,0]
	v_fma_mix_f32 v145, v131, v13, v145 op_sel:[0,1,0] op_sel_hi:[0,1,0]
	v_fma_mix_f32 v144, v132, v14, v144 op_sel_hi:[0,1,0]
	v_fma_mix_f32 v145, v133, v14, v145 op_sel:[0,1,0] op_sel_hi:[0,1,0]
	v_fma_mix_f32 v144, v134, v15, v144 op_sel_hi:[0,1,0]
	v_fma_mix_f32 v145, v135, v15, v145 op_sel:[0,1,0] op_sel_hi:[0,1,0]
	v_fma_mix_f32 v144, v136, v16, v144 op_sel_hi:[0,1,0]
	v_fma_mix_f32 v145, v137, v16, v145 op_sel:[0,1,0] op_sel_hi:[0,1,0]
	v_fma_mix_f32 v144, v138, v17, v144 op_sel_hi:[0,1,0]
	v_fma_mix_f32 v145, v139, v17, v145 op_sel:[0,1,0] op_sel_hi:[0,1,0]
	v_fma_mix_f32 v144, v140, v18, v144 op_sel_hi:[0,1,0]
	v_fma_mix_f32 v145, v141, v18, v145 op_sel:[0,1,0] op_sel_hi:[0,1,0]
	v_fma_mix_f32 v144, v142, v19, v144 op_sel_hi:[0,1,0]
	v_fma_mix_f32 v145, v143, v19, v145 op_sel:[0,1,0] op_sel_hi:[0,1,0]
	v_add_f32_e32 v152, v144, v145
	s_waitcnt vmcnt(0)
	v_lshlrev_b32_e32 v192, 23, v110
	v_cvt_scalef32_pk32_f32_fp6 v[112:143], v[104:109], v192
	v_fma_mix_f32 v144, v112, v4, 0 op_sel_hi:[0,1,0]
	v_fma_mix_f32 v145, v113, v4, 0 op_sel:[0,1,0] op_sel_hi:[0,1,0]
	v_fma_mix_f32 v144, v114, v5, v144 op_sel_hi:[0,1,0]
	v_fma_mix_f32 v145, v115, v5, v145 op_sel:[0,1,0] op_sel_hi:[0,1,0]
	v_fma_mix_f32 v144, v116, v6, v144 op_sel_hi:[0,1,0]
	v_fma_mix_f32 v145, v117, v6, v145 op_sel:[0,1,0] op_sel_hi:[0,1,0]
	v_fma_mix_f32 v144, v118, v7, v144 op_sel_hi:[0,1,0]
	v_fma_mix_f32 v145, v119, v7, v145 op_sel:[0,1,0] op_sel_hi:[0,1,0]
	v_fma_mix_f32 v144, v120, v8, v144 op_sel_hi:[0,1,0]
	v_fma_mix_f32 v145, v121, v8, v145 op_sel:[0,1,0] op_sel_hi:[0,1,0]
	v_fma_mix_f32 v144, v122, v9, v144 op_sel_hi:[0,1,0]
	v_fma_mix_f32 v145, v123, v9, v145 op_sel:[0,1,0] op_sel_hi:[0,1,0]
	v_fma_mix_f32 v144, v124, v10, v144 op_sel_hi:[0,1,0]
	v_fma_mix_f32 v145, v125, v10, v145 op_sel:[0,1,0] op_sel_hi:[0,1,0]
	v_fma_mix_f32 v144, v126, v11, v144 op_sel_hi:[0,1,0]
	v_fma_mix_f32 v145, v127, v11, v145 op_sel:[0,1,0] op_sel_hi:[0,1,0]
	v_fma_mix_f32 v144, v128, v12, v144 op_sel_hi:[0,1,0]
	v_fma_mix_f32 v145, v129, v12, v145 op_sel:[0,1,0] op_sel_hi:[0,1,0]
	v_fma_mix_f32 v144, v130, v13, v144 op_sel_hi:[0,1,0]
	v_fma_mix_f32 v145, v131, v13, v145 op_sel:[0,1,0] op_sel_hi:[0,1,0]
	v_fma_mix_f32 v144, v132, v14, v144 op_sel_hi:[0,1,0]
	v_fma_mix_f32 v145, v133, v14, v145 op_sel:[0,1,0] op_sel_hi:[0,1,0]
	v_fma_mix_f32 v144, v134, v15, v144 op_sel_hi:[0,1,0]
	v_fma_mix_f32 v145, v135, v15, v145 op_sel:[0,1,0] op_sel_hi:[0,1,0]
	v_fma_mix_f32 v144, v136, v16, v144 op_sel_hi:[0,1,0]
	v_fma_mix_f32 v145, v137, v16, v145 op_sel:[0,1,0] op_sel_hi:[0,1,0]
	v_fma_mix_f32 v144, v138, v17, v144 op_sel_hi:[0,1,0]
	v_fma_mix_f32 v145, v139, v17, v145 op_sel:[0,1,0] op_sel_hi:[0,1,0]
	v_fma_mix_f32 v144, v140, v18, v144 op_sel_hi:[0,1,0]
	v_fma_mix_f32 v145, v141, v18, v145 op_sel:[0,1,0] op_sel_hi:[0,1,0]
	v_fma_mix_f32 v144, v142, v19, v144 op_sel_hi:[0,1,0]
	v_fma_mix_f32 v145, v143, v19, v145 op_sel:[0,1,0] op_sel_hi:[0,1,0]
	v_add_f32_e32 v153, v144, v145
	v_add_f32_dpp v146, v146, v146 row_ror:8 row_mask:0xf bank_mask:0xf bound_ctrl:1
	v_add_f32_dpp v147, v147, v147 row_ror:8 row_mask:0xf bank_mask:0xf bound_ctrl:1
	v_add_f32_dpp v148, v148, v148 row_ror:8 row_mask:0xf bank_mask:0xf bound_ctrl:1
	v_add_f32_dpp v149, v149, v149 row_ror:8 row_mask:0xf bank_mask:0xf bound_ctrl:1
	v_add_f32_dpp v146, v150, v150 row_ror:8 row_mask:0xf bank_mask:0xc bound_ctrl:1
	v_add_f32_dpp v147, v151, v151 row_ror:8 row_mask:0xf bank_mask:0xc bound_ctrl:1
	v_add_f32_dpp v148, v152, v152 row_ror:8 row_mask:0xf bank_mask:0xc bound_ctrl:1
	v_add_f32_dpp v149, v153, v153 row_ror:8 row_mask:0xf bank_mask:0xc bound_ctrl:1
	v_add_f32_dpp v146, v146, v146 row_half_mirror row_mask:0xf bank_mask:0xf bound_ctrl:1
	v_add_f32_dpp v147, v147, v147 row_half_mirror row_mask:0xf bank_mask:0xf bound_ctrl:1
	v_add_f32_dpp v146, v148, v148 row_half_mirror row_mask:0xf bank_mask:0xa bound_ctrl:1
	v_add_f32_dpp v147, v149, v149 row_half_mirror row_mask:0xf bank_mask:0xa bound_ctrl:1
	s_nop 1
	v_add_f32_dpp v146, v146, v146 quad_perm:[1,0,3,2] row_mask:0xf bank_mask:0xf bound_ctrl:1
	v_add_f32_dpp v147, v147, v147 quad_perm:[1,0,3,2] row_mask:0xf bank_mask:0xf bound_ctrl:1
	s_nop 0
	v_add_f32_dpp v146, v146, v146 quad_perm:[2,3,0,1] row_mask:0xf bank_mask:0xf bound_ctrl:1
	v_add_f32_dpp v147, v147, v147 quad_perm:[2,3,0,1] row_mask:0xf bank_mask:0xf bound_ctrl:1
	v_mov_b32_e32 v193, v146
; __device__ __forceinline__ float row_sum16(float v) { v += __shfl_xor(v, 1); v += __shfl_xor(v, 2); v += __shfl_xor(v, 4); v += __shfl_xor(v, 8); return v; }
; __device__ __forceinline__ float wave_sum(float v) { v = row_sum16(v); v += __shfl_xor(v, 16); v += __shfl_xor(v, 32); return v; }
; #define PB_FENCE asm volatile("" ::: "memory")
; __device__ __forceinline__ float row_sum16(float v) { v += dppf<0xB1>(v); v += dppf<0x4E>(v); v += dppf<0x124>(v); v += dppf<0x128>(v); return v; }
; __device__ __forceinline__ float wave_sum(float v) {
;   v = row_sum16(v);
;   const float r0 = __builtin_bit_cast(float, __builtin_amdgcn_readlane(__builtin_bit_cast(int, v), 0));
;   const float r1 = __builtin_bit_cast(float, __builtin_amdgcn_readlane(__builtin_bit_cast(int, v), 16));
;   const float r2 = __builtin_bit_cast(float, __builtin_amdgcn_readlane(__builtin_bit_cast(int, v), 32));
;   const float r3 = __builtin_bit_cast(float, __builtin_amdgcn_readlane(__builtin_bit_cast(int, v), 48));
;   return (r0 + r1) + (r2 + r3);
; }
; __device__ __forceinline__ void ph_peer_apply(const Params& P, int layer, float* xlat, float* xctx_in, float* xctx_out, int nrows, bool write_next, char* smem, float* xlat_out = nullptr) {
;     ...
;     constexpr int NG = NSEL / PB_G;
;     PB_LOAD(bufA, tu, 0);
;     for (int gq = 0; gq < NG; gq += 2) {
;       PB_LOAD(bufB, tu, gq + 1); PB_FENCE;
;       PB_DOT(bufA, gq);
;       if (gq + 2 < NG) PB_LOAD(bufA, tu, gq + 2);
;       PB_FENCE;
;       PB_DOT(bufB, gq + 1);
;     }
	v_mov_b32_e32 v194, v147
	s_nop 1
	v_permlane32_swap_b32_e32 v193, v146
	v_permlane32_swap_b32_e32 v194, v147
	v_add_f32_e32 v146, v146, v193
	v_add_f32_e32 v147, v147, v194
	v_mov_b32_e32 v193, v146
	v_mov_b32_e32 v194, v147
	s_nop 1
	v_permlane16_swap_b32_e32 v193, v146
	v_permlane16_swap_b32_e32 v194, v147
	v_add_f32_e32 v146, v146, v193
	v_add_f32_e32 v147, v147, v194
	v_cndmask_b32_e64 v146, v146, v147, s[34:35]
	s_mov_b64 exec, s[46:47]
	ds_write_b32 v229, v146
	s_mov_b64 exec, -1
	v_add_u32_e32 v229, 32, v229
	s_mov_b32 s28, 0
	v_readlane_b32 s29, v37, s28
	s_add_u32 s28, s28, 1
	s_mul_hi_u32 s27, s29, 0x640
	s_mul_i32 s26, s29, 0x640
	s_add_u32 s26, s16, s26
	s_addc_u32 s27, s17, s27
	global_load_dwordx4 v[48:51], v2, s[26:27]
	global_load_dwordx2 v[52:53], v2, s[26:27] offset:16
	global_load_ubyte v54, v3, s[26:27]
	v_readlane_b32 s29, v37, s28
	s_add_u32 s28, s28, 1
	s_mul_hi_u32 s27, s29, 0x640
	s_mul_i32 s26, s29, 0x640
	s_add_u32 s26, s16, s26
	s_addc_u32 s27, s17, s27
	global_load_dwordx4 v[56:59], v2, s[26:27]
	global_load_dwordx2 v[60:61], v2, s[26:27] offset:16
	global_load_ubyte v62, v3, s[26:27]
	v_readlane_b32 s29, v37, s28
	s_add_u32 s28, s28, 1
	s_mul_hi_u32 s27, s29, 0x640
	s_mul_i32 s26, s29, 0x640
	s_add_u32 s26, s16, s26
	s_addc_u32 s27, s17, s27
	global_load_dwordx4 v[64:67], v2, s[26:27]
	global_load_dwordx2 v[68:69], v2, s[26:27] offset:16
	global_load_ubyte v70, v3, s[26:27]
	v_readlane_b32 s29, v37, s28
	s_add_u32 s28, s28, 1
	s_mul_hi_u32 s27, s29, 0x640
	s_mul_i32 s26, s29, 0x640
	s_add_u32 s26, s16, s26
	s_addc_u32 s27, s17, s27
	global_load_dwordx4 v[72:75], v2, s[26:27]
	global_load_dwordx2 v[76:77], v2, s[26:27] offset:16
	global_load_ubyte v78, v3, s[26:27]
	v_readlane_b32 s29, v37, s28
	s_add_u32 s28, s28, 1
	s_mul_hi_u32 s27, s29, 0x640
	s_mul_i32 s26, s29, 0x640
	s_add_u32 s26, s16, s26
	s_addc_u32 s27, s17, s27
	global_load_dwordx4 v[80:83], v2, s[26:27]
	global_load_dwordx2 v[84:85], v2, s[26:27] offset:16
	global_load_ubyte v86, v3, s[26:27]
	v_readlane_b32 s29, v37, s28
	s_add_u32 s28, s28, 1
	s_mul_hi_u32 s27, s29, 0x640
	s_mul_i32 s26, s29, 0x640
	s_add_u32 s26, s16, s26
	s_addc_u32 s27, s17, s27
	global_load_dwordx4 v[88:91], v2, s[26:27]
	global_load_dwordx2 v[92:93], v2, s[26:27] offset:16
	global_load_ubyte v94, v3, s[26:27]
	v_readlane_b32 s29, v37, s28
	s_add_u32 s28, s28, 1
	s_mul_hi_u32 s27, s29, 0x640
	s_mul_i32 s26, s29, 0x640
	s_add_u32 s26, s16, s26
	s_addc_u32 s27, s17, s27
	global_load_dwordx4 v[96:99], v2, s[26:27]
	global_load_dwordx2 v[100:101], v2, s[26:27] offset:16
	global_load_ubyte v102, v3, s[26:27]
	v_readlane_b32 s29, v37, s28
	s_add_u32 s28, s28, 1
	s_mul_hi_u32 s27, s29, 0x640
	s_mul_i32 s26, s29, 0x640
	s_add_u32 s26, s16, s26
	s_addc_u32 s27, s17, s27
	global_load_dwordx4 v[104:107], v2, s[26:27]
	global_load_dwordx2 v[108:109], v2, s[26:27] offset:16
	global_load_ubyte v110, v3, s[26:27]
	s_mov_b32 s30, 7
.Lap0_s1_loop2:
	s_waitcnt vmcnt(21)
	v_lshlrev_b32_e32 v192, 23, v54
	v_cvt_scalef32_pk32_f32_fp6 v[112:143], v[48:53], v192
	v_fma_mix_f32 v144, v112, v4, 0 op_sel_hi:[0,1,0]
	v_fma_mix_f32 v145, v113, v4, 0 op_sel:[0,1,0] op_sel_hi:[0,1,0]
	v_fma_mix_f32 v144, v114, v5, v144 op_sel_hi:[0,1,0]
	v_fma_mix_f32 v145, v115, v5, v145 op_sel:[0,1,0] op_sel_hi:[0,1,0]
	v_fma_mix_f32 v144, v116, v6, v144 op_sel_hi:[0,1,0]
	v_fma_mix_f32 v145, v117, v6, v145 op_sel:[0,1,0] op_sel_hi:[0,1,0]
	v_fma_mix_f32 v144, v118, v7, v144 op_sel_hi:[0,1,0]
	v_fma_mix_f32 v145, v119, v7, v145 op_sel:[0,1,0] op_sel_hi:[0,1,0]
	v_fma_mix_f32 v144, v120, v8, v144 op_sel_hi:[0,1,0]
	v_fma_mix_f32 v145, v121, v8, v145 op_sel:[0,1,0] op_sel_hi:[0,1,0]
	v_fma_mix_f32 v144, v122, v9, v144 op_sel_hi:[0,1,0]
	v_fma_mix_f32 v145, v123, v9, v145 op_sel:[0,1,0] op_sel_hi:[0,1,0]
	v_fma_mix_f32 v144, v124, v10, v144 op_sel_hi:[0,1,0]
	v_fma_mix_f32 v145, v125, v10, v145 op_sel:[0,1,0] op_sel_hi:[0,1,0]
	v_fma_mix_f32 v144, v126, v11, v144 op_sel_hi:[0,1,0]
	v_fma_mix_f32 v145, v127, v11, v145 op_sel:[0,1,0] op_sel_hi:[0,1,0]
	v_fma_mix_f32 v144, v128, v12, v144 op_sel_hi:[0,1,0]
	v_fma_mix_f32 v145, v129, v12, v145 op_sel:[0,1,0] op_sel_hi:[0,1,0]
	v_fma_mix_f32 v144, v130, v13, v144 op_sel_hi:[0,1,0]
	v_fma_mix_f32 v145, v131, v13, v145 op_sel:[0,1,0] op_sel_hi:[0,1,0]
	v_fma_mix_f32 v144, v132, v14, v144 op_sel_hi:[0,1,0]
	v_fma_mix_f32 v145, v133, v14, v145 op_sel:[0,1,0] op_sel_hi:[0,1,0]
	v_fma_mix_f32 v144, v134, v15, v144 op_sel_hi:[0,1,0]
	v_fma_mix_f32 v145, v135, v15, v145 op_sel:[0,1,0] op_sel_hi:[0,1,0]
	v_fma_mix_f32 v144, v136, v16, v144 op_sel_hi:[0,1,0]
	v_fma_mix_f32 v145, v137, v16, v145 op_sel:[0,1,0] op_sel_hi:[0,1,0]
	v_fma_mix_f32 v144, v138, v17, v144 op_sel_hi:[0,1,0]
	v_fma_mix_f32 v145, v139, v17, v145 op_sel:[0,1,0] op_sel_hi:[0,1,0]
	v_fma_mix_f32 v144, v140, v18, v144 op_sel_hi:[0,1,0]
	v_fma_mix_f32 v145, v141, v18, v145 op_sel:[0,1,0] op_sel_hi:[0,1,0]
	v_fma_mix_f32 v144, v142, v19, v144 op_sel_hi:[0,1,0]
	v_fma_mix_f32 v145, v143, v19, v145 op_sel:[0,1,0] op_sel_hi:[0,1,0]
	v_add_f32_e32 v146, v144, v145
	v_readlane_b32 s29, v37, s28
	s_add_u32 s28, s28, 1
	s_mul_hi_u32 s27, s29, 0x640
	s_mul_i32 s26, s29, 0x640
	s_add_u32 s26, s16, s26
	s_addc_u32 s27, s17, s27
	global_load_dwordx4 v[48:51], v2, s[26:27]
	global_load_dwordx2 v[52:53], v2, s[26:27] offset:16
	global_load_ubyte v54, v3, s[26:27]
	s_waitcnt vmcnt(21)
; #define PB_FENCE asm volatile("" ::: "memory")
; __device__ __forceinline__ void ph_peer_apply(const Params& P, int layer, float* xlat, float* xctx_in, float* xctx_out, int nrows, bool write_next, char* smem, float* xlat_out = nullptr) {
;     ...
;     constexpr int NG = NSEL / PB_G;
;     PB_LOAD(bufA, tu, 0);
;     for (int gq = 0; gq < NG; gq += 2) {
;       PB_LOAD(bufB, tu, gq + 1); PB_FENCE;
;       PB_DOT(bufA, gq);
;       if (gq + 2 < NG) PB_LOAD(bufA, tu, gq + 2);
;       PB_FENCE;
;       PB_DOT(bufB, gq + 1);
;     }
	v_lshlrev_b32_e32 v192, 23, v62
	v_cvt_scalef32_pk32_f32_fp6 v[112:143], v[56:61], v192
	v_fma_mix_f32 v144, v112, v4, 0 op_sel_hi:[0,1,0]
	v_fma_mix_f32 v145, v113, v4, 0 op_sel:[0,1,0] op_sel_hi:[0,1,0]
	v_fma_mix_f32 v144, v114, v5, v144 op_sel_hi:[0,1,0]
	v_fma_mix_f32 v145, v115, v5, v145 op_sel:[0,1,0] op_sel_hi:[0,1,0]
	v_fma_mix_f32 v144, v116, v6, v144 op_sel_hi:[0,1,0]
	v_fma_mix_f32 v145, v117, v6, v145 op_sel:[0,1,0] op_sel_hi:[0,1,0]
	v_fma_mix_f32 v144, v118, v7, v144 op_sel_hi:[0,1,0]
	v_fma_mix_f32 v145, v119, v7, v145 op_sel:[0,1,0] op_sel_hi:[0,1,0]
	v_fma_mix_f32 v144, v120, v8, v144 op_sel_hi:[0,1,0]
	v_fma_mix_f32 v145, v121, v8, v145 op_sel:[0,1,0] op_sel_hi:[0,1,0]
	v_fma_mix_f32 v144, v122, v9, v144 op_sel_hi:[0,1,0]
	v_fma_mix_f32 v145, v123, v9, v145 op_sel:[0,1,0] op_sel_hi:[0,1,0]
	v_fma_mix_f32 v144, v124, v10, v144 op_sel_hi:[0,1,0]
	v_fma_mix_f32 v145, v125, v10, v145 op_sel:[0,1,0] op_sel_hi:[0,1,0]
	v_fma_mix_f32 v144, v126, v11, v144 op_sel_hi:[0,1,0]
	v_fma_mix_f32 v145, v127, v11, v145 op_sel:[0,1,0] op_sel_hi:[0,1,0]
	v_fma_mix_f32 v144, v128, v12, v144 op_sel_hi:[0,1,0]
	v_fma_mix_f32 v145, v129, v12, v145 op_sel:[0,1,0] op_sel_hi:[0,1,0]
	v_fma_mix_f32 v144, v130, v13, v144 op_sel_hi:[0,1,0]
	v_fma_mix_f32 v145, v131, v13, v145 op_sel:[0,1,0] op_sel_hi:[0,1,0]
	v_fma_mix_f32 v144, v132, v14, v144 op_sel_hi:[0,1,0]
	v_fma_mix_f32 v145, v133, v14, v145 op_sel:[0,1,0] op_sel_hi:[0,1,0]
	v_fma_mix_f32 v144, v134, v15, v144 op_sel_hi:[0,1,0]
	v_fma_mix_f32 v145, v135, v15, v145 op_sel:[0,1,0] op_sel_hi:[0,1,0]
	v_fma_mix_f32 v144, v136, v16, v144 op_sel_hi:[0,1,0]
	v_fma_mix_f32 v145, v137, v16, v145 op_sel:[0,1,0] op_sel_hi:[0,1,0]
	v_fma_mix_f32 v144, v138, v17, v144 op_sel_hi:[0,1,0]
	v_fma_mix_f32 v145, v139, v17, v145 op_sel:[0,1,0] op_sel_hi:[0,1,0]
	v_fma_mix_f32 v144, v140, v18, v144 op_sel_hi:[0,1,0]
	v_fma_mix_f32 v145, v141, v18, v145 op_sel:[0,1,0] op_sel_hi:[0,1,0]
	v_fma_mix_f32 v144, v142, v19, v144 op_sel_hi:[0,1,0]
	v_fma_mix_f32 v145, v143, v19, v145 op_sel:[0,1,0] op_sel_hi:[0,1,0]
	v_add_f32_e32 v147, v144, v145
	v_readlane_b32 s29, v37, s28
	s_add_u32 s28, s28, 1
	s_mul_hi_u32 s27, s29, 0x640
	s_mul_i32 s26, s29, 0x640
	s_add_u32 s26, s16, s26
	s_addc_u32 s27, s17, s27
	global_load_dwordx4 v[56:59], v2, s[26:27]
	global_load_dwordx2 v[60:61], v2, s[26:27] offset:16
	global_load_ubyte v62, v3, s[26:27]
	s_waitcnt vmcnt(21)
	v_lshlrev_b32_e32 v192, 23, v70
	v_cvt_scalef32_pk32_f32_fp6 v[112:143], v[64:69], v192
	v_fma_mix_f32 v144, v112, v4, 0 op_sel_hi:[0,1,0]
	v_fma_mix_f32 v145, v113, v4, 0 op_sel:[0,1,0] op_sel_hi:[0,1,0]
	v_fma_mix_f32 v144, v114, v5, v144 op_sel_hi:[0,1,0]
	v_fma_mix_f32 v145, v115, v5, v145 op_sel:[0,1,0] op_sel_hi:[0,1,0]
	v_fma_mix_f32 v144, v116, v6, v144 op_sel_hi:[0,1,0]
	v_fma_mix_f32 v145, v117, v6, v145 op_sel:[0,1,0] op_sel_hi:[0,1,0]
	v_fma_mix_f32 v144, v118, v7, v144 op_sel_hi:[0,1,0]
	v_fma_mix_f32 v145, v119, v7, v145 op_sel:[0,1,0] op_sel_hi:[0,1,0]
	v_fma_mix_f32 v144, v120, v8, v144 op_sel_hi:[0,1,0]
	v_fma_mix_f32 v145, v121, v8, v145 op_sel:[0,1,0] op_sel_hi:[0,1,0]
	v_fma_mix_f32 v144, v122, v9, v144 op_sel_hi:[0,1,0]
	v_fma_mix_f32 v145, v123, v9, v145 op_sel:[0,1,0] op_sel_hi:[0,1,0]
	v_fma_mix_f32 v144, v124, v10, v144 op_sel_hi:[0,1,0]
	v_fma_mix_f32 v145, v125, v10, v145 op_sel:[0,1,0] op_sel_hi:[0,1,0]
	v_fma_mix_f32 v144, v126, v11, v144 op_sel_hi:[0,1,0]
	v_fma_mix_f32 v145, v127, v11, v145 op_sel:[0,1,0] op_sel_hi:[0,1,0]
	v_fma_mix_f32 v144, v128, v12, v144 op_sel_hi:[0,1,0]
	v_fma_mix_f32 v145, v129, v12, v145 op_sel:[0,1,0] op_sel_hi:[0,1,0]
	v_fma_mix_f32 v144, v130, v13, v144 op_sel_hi:[0,1,0]
	v_fma_mix_f32 v145, v131, v13, v145 op_sel:[0,1,0] op_sel_hi:[0,1,0]
	v_fma_mix_f32 v144, v132, v14, v144 op_sel_hi:[0,1,0]
	v_fma_mix_f32 v145, v133, v14, v145 op_sel:[0,1,0] op_sel_hi:[0,1,0]
	v_fma_mix_f32 v144, v134, v15, v144 op_sel_hi:[0,1,0]
	v_fma_mix_f32 v145, v135, v15, v145 op_sel:[0,1,0] op_sel_hi:[0,1,0]
	v_fma_mix_f32 v144, v136, v16, v144 op_sel_hi:[0,1,0]
	v_fma_mix_f32 v145, v137, v16, v145 op_sel:[0,1,0] op_sel_hi:[0,1,0]
	v_fma_mix_f32 v144, v138, v17, v144 op_sel_hi:[0,1,0]
	v_fma_mix_f32 v145, v139, v17, v145 op_sel:[0,1,0] op_sel_hi:[0,1,0]
	v_fma_mix_f32 v144, v140, v18, v144 op_sel_hi:[0,1,0]
	v_fma_mix_f32 v145, v141, v18, v145 op_sel:[0,1,0] op_sel_hi:[0,1,0]
	v_fma_mix_f32 v144, v142, v19, v144 op_sel_hi:[0,1,0]
	v_fma_mix_f32 v145, v143, v19, v145 op_sel:[0,1,0] op_sel_hi:[0,1,0]
	v_add_f32_e32 v148, v144, v145
	v_readlane_b32 s29, v37, s28
	s_add_u32 s28, s28, 1
	s_mul_hi_u32 s27, s29, 0x640
	s_mul_i32 s26, s29, 0x640
	s_add_u32 s26, s16, s26
	s_addc_u32 s27, s17, s27
	global_load_dwordx4 v[64:67], v2, s[26:27]
	global_load_dwordx2 v[68:69], v2, s[26:27] offset:16
	global_load_ubyte v70, v3, s[26:27]
	s_waitcnt vmcnt(21)
; #define PB_FENCE asm volatile("" ::: "memory")
; __device__ __forceinline__ void ph_peer_apply(const Params& P, int layer, float* xlat, float* xctx_in, float* xctx_out, int nrows, bool write_next, char* smem, float* xlat_out = nullptr) {
;     ...
;     constexpr int NG = NSEL / PB_G;
;     PB_LOAD(bufA, tu, 0);
;     for (int gq = 0; gq < NG; gq += 2) {
;       PB_LOAD(bufB, tu, gq + 1); PB_FENCE;
;       PB_DOT(bufA, gq);
;       if (gq + 2 < NG) PB_LOAD(bufA, tu, gq + 2);
;       PB_FENCE;
;       PB_DOT(bufB, gq + 1);
;     }
	v_lshlrev_b32_e32 v192, 23, v78
	v_cvt_scalef32_pk32_f32_fp6 v[112:143], v[72:77], v192
	v_fma_mix_f32 v144, v112, v4, 0 op_sel_hi:[0,1,0]
	v_fma_mix_f32 v145, v113, v4, 0 op_sel:[0,1,0] op_sel_hi:[0,1,0]
	v_fma_mix_f32 v144, v114, v5, v144 op_sel_hi:[0,1,0]
	v_fma_mix_f32 v145, v115, v5, v145 op_sel:[0,1,0] op_sel_hi:[0,1,0]
	v_fma_mix_f32 v144, v116, v6, v144 op_sel_hi:[0,1,0]
	v_fma_mix_f32 v145, v117, v6, v145 op_sel:[0,1,0] op_sel_hi:[0,1,0]
	v_fma_mix_f32 v144, v118, v7, v144 op_sel_hi:[0,1,0]
	v_fma_mix_f32 v145, v119, v7, v145 op_sel:[0,1,0] op_sel_hi:[0,1,0]
	v_fma_mix_f32 v144, v120, v8, v144 op_sel_hi:[0,1,0]
	v_fma_mix_f32 v145, v121, v8, v145 op_sel:[0,1,0] op_sel_hi:[0,1,0]
	v_fma_mix_f32 v144, v122, v9, v144 op_sel_hi:[0,1,0]
	v_fma_mix_f32 v145, v123, v9, v145 op_sel:[0,1,0] op_sel_hi:[0,1,0]
	v_fma_mix_f32 v144, v124, v10, v144 op_sel_hi:[0,1,0]
	v_fma_mix_f32 v145, v125, v10, v145 op_sel:[0,1,0] op_sel_hi:[0,1,0]
	v_fma_mix_f32 v144, v126, v11, v144 op_sel_hi:[0,1,0]
	v_fma_mix_f32 v145, v127, v11, v145 op_sel:[0,1,0] op_sel_hi:[0,1,0]
	v_fma_mix_f32 v144, v128, v12, v144 op_sel_hi:[0,1,0]
	v_fma_mix_f32 v145, v129, v12, v145 op_sel:[0,1,0] op_sel_hi:[0,1,0]
	v_fma_mix_f32 v144, v130, v13, v144 op_sel_hi:[0,1,0]
	v_fma_mix_f32 v145, v131, v13, v145 op_sel:[0,1,0] op_sel_hi:[0,1,0]
	v_fma_mix_f32 v144, v132, v14, v144 op_sel_hi:[0,1,0]
	v_fma_mix_f32 v145, v133, v14, v145 op_sel:[0,1,0] op_sel_hi:[0,1,0]
	v_fma_mix_f32 v144, v134, v15, v144 op_sel_hi:[0,1,0]
	v_fma_mix_f32 v145, v135, v15, v145 op_sel:[0,1,0] op_sel_hi:[0,1,0]
	v_fma_mix_f32 v144, v136, v16, v144 op_sel_hi:[0,1,0]
	v_fma_mix_f32 v145, v137, v16, v145 op_sel:[0,1,0] op_sel_hi:[0,1,0]
	v_fma_mix_f32 v144, v138, v17, v144 op_sel_hi:[0,1,0]
	v_fma_mix_f32 v145, v139, v17, v145 op_sel:[0,1,0] op_sel_hi:[0,1,0]
	v_fma_mix_f32 v144, v140, v18, v144 op_sel_hi:[0,1,0]
	v_fma_mix_f32 v145, v141, v18, v145 op_sel:[0,1,0] op_sel_hi:[0,1,0]
	v_fma_mix_f32 v144, v142, v19, v144 op_sel_hi:[0,1,0]
	v_fma_mix_f32 v145, v143, v19, v145 op_sel:[0,1,0] op_sel_hi:[0,1,0]
	v_add_f32_e32 v149, v144, v145
	v_readlane_b32 s29, v37, s28
	s_add_u32 s28, s28, 1
	s_mul_hi_u32 s27, s29, 0x640
	s_mul_i32 s26, s29, 0x640
	s_add_u32 s26, s16, s26
	s_addc_u32 s27, s17, s27
	global_load_dwordx4 v[72:75], v2, s[26:27]
	global_load_dwordx2 v[76:77], v2, s[26:27] offset:16
	global_load_ubyte v78, v3, s[26:27]
	s_waitcnt vmcnt(21)
	v_lshlrev_b32_e32 v192, 23, v86
	v_cvt_scalef32_pk32_f32_fp6 v[112:143], v[80:85], v192
	v_fma_mix_f32 v144, v112, v4, 0 op_sel_hi:[0,1,0]
	v_fma_mix_f32 v145, v113, v4, 0 op_sel:[0,1,0] op_sel_hi:[0,1,0]
	v_fma_mix_f32 v144, v114, v5, v144 op_sel_hi:[0,1,0]
	v_fma_mix_f32 v145, v115, v5, v145 op_sel:[0,1,0] op_sel_hi:[0,1,0]
	v_fma_mix_f32 v144, v116, v6, v144 op_sel_hi:[0,1,0]
	v_fma_mix_f32 v145, v117, v6, v145 op_sel:[0,1,0] op_sel_hi:[0,1,0]
	v_fma_mix_f32 v144, v118, v7, v144 op_sel_hi:[0,1,0]
	v_fma_mix_f32 v145, v119, v7, v145 op_sel:[0,1,0] op_sel_hi:[0,1,0]
	v_fma_mix_f32 v144, v120, v8, v144 op_sel_hi:[0,1,0]
	v_fma_mix_f32 v145, v121, v8, v145 op_sel:[0,1,0] op_sel_hi:[0,1,0]
	v_fma_mix_f32 v144, v122, v9, v144 op_sel_hi:[0,1,0]
	v_fma_mix_f32 v145, v123, v9, v145 op_sel:[0,1,0] op_sel_hi:[0,1,0]
	v_fma_mix_f32 v144, v124, v10, v144 op_sel_hi:[0,1,0]
	v_fma_mix_f32 v145, v125, v10, v145 op_sel:[0,1,0] op_sel_hi:[0,1,0]
	v_fma_mix_f32 v144, v126, v11, v144 op_sel_hi:[0,1,0]
	v_fma_mix_f32 v145, v127, v11, v145 op_sel:[0,1,0] op_sel_hi:[0,1,0]
	v_fma_mix_f32 v144, v128, v12, v144 op_sel_hi:[0,1,0]
	v_fma_mix_f32 v145, v129, v12, v145 op_sel:[0,1,0] op_sel_hi:[0,1,0]
	v_fma_mix_f32 v144, v130, v13, v144 op_sel_hi:[0,1,0]
	v_fma_mix_f32 v145, v131, v13, v145 op_sel:[0,1,0] op_sel_hi:[0,1,0]
	v_fma_mix_f32 v144, v132, v14, v144 op_sel_hi:[0,1,0]
	v_fma_mix_f32 v145, v133, v14, v145 op_sel:[0,1,0] op_sel_hi:[0,1,0]
	v_fma_mix_f32 v144, v134, v15, v144 op_sel_hi:[0,1,0]
	v_fma_mix_f32 v145, v135, v15, v145 op_sel:[0,1,0] op_sel_hi:[0,1,0]
	v_fma_mix_f32 v144, v136, v16, v144 op_sel_hi:[0,1,0]
	v_fma_mix_f32 v145, v137, v16, v145 op_sel:[0,1,0] op_sel_hi:[0,1,0]
	v_fma_mix_f32 v144, v138, v17, v144 op_sel_hi:[0,1,0]
	v_fma_mix_f32 v145, v139, v17, v145 op_sel:[0,1,0] op_sel_hi:[0,1,0]
	v_fma_mix_f32 v144, v140, v18, v144 op_sel_hi:[0,1,0]
	v_fma_mix_f32 v145, v141, v18, v145 op_sel:[0,1,0] op_sel_hi:[0,1,0]
	v_fma_mix_f32 v144, v142, v19, v144 op_sel_hi:[0,1,0]
	v_fma_mix_f32 v145, v143, v19, v145 op_sel:[0,1,0] op_sel_hi:[0,1,0]
	v_add_f32_e32 v150, v144, v145
	v_readlane_b32 s29, v37, s28
	s_add_u32 s28, s28, 1
	s_mul_hi_u32 s27, s29, 0x640
	s_mul_i32 s26, s29, 0x640
	s_add_u32 s26, s16, s26
	s_addc_u32 s27, s17, s27
	global_load_dwordx4 v[80:83], v2, s[26:27]
	global_load_dwordx2 v[84:85], v2, s[26:27] offset:16
	global_load_ubyte v86, v3, s[26:27]
	s_waitcnt vmcnt(21)
; #define PB_FENCE asm volatile("" ::: "memory")
; __device__ __forceinline__ void ph_peer_apply(const Params& P, int layer, float* xlat, float* xctx_in, float* xctx_out, int nrows, bool write_next, char* smem, float* xlat_out = nullptr) {
;     ...
;     constexpr int NG = NSEL / PB_G;
;     PB_LOAD(bufA, tu, 0);
;     for (int gq = 0; gq < NG; gq += 2) {
;       PB_LOAD(bufB, tu, gq + 1); PB_FENCE;
;       PB_DOT(bufA, gq);
;       if (gq + 2 < NG) PB_LOAD(bufA, tu, gq + 2);
;       PB_FENCE;
;       PB_DOT(bufB, gq + 1);
;     }
	v_lshlrev_b32_e32 v192, 23, v94
	v_cvt_scalef32_pk32_f32_fp6 v[112:143], v[88:93], v192
	v_fma_mix_f32 v144, v112, v4, 0 op_sel_hi:[0,1,0]
	v_fma_mix_f32 v145, v113, v4, 0 op_sel:[0,1,0] op_sel_hi:[0,1,0]
	v_fma_mix_f32 v144, v114, v5, v144 op_sel_hi:[0,1,0]
	v_fma_mix_f32 v145, v115, v5, v145 op_sel:[0,1,0] op_sel_hi:[0,1,0]
	v_fma_mix_f32 v144, v116, v6, v144 op_sel_hi:[0,1,0]
	v_fma_mix_f32 v145, v117, v6, v145 op_sel:[0,1,0] op_sel_hi:[0,1,0]
	v_fma_mix_f32 v144, v118, v7, v144 op_sel_hi:[0,1,0]
	v_fma_mix_f32 v145, v119, v7, v145 op_sel:[0,1,0] op_sel_hi:[0,1,0]
	v_fma_mix_f32 v144, v120, v8, v144 op_sel_hi:[0,1,0]
	v_fma_mix_f32 v145, v121, v8, v145 op_sel:[0,1,0] op_sel_hi:[0,1,0]
	v_fma_mix_f32 v144, v122, v9, v144 op_sel_hi:[0,1,0]
	v_fma_mix_f32 v145, v123, v9, v145 op_sel:[0,1,0] op_sel_hi:[0,1,0]
	v_fma_mix_f32 v144, v124, v10, v144 op_sel_hi:[0,1,0]
	v_fma_mix_f32 v145, v125, v10, v145 op_sel:[0,1,0] op_sel_hi:[0,1,0]
	v_fma_mix_f32 v144, v126, v11, v144 op_sel_hi:[0,1,0]
	v_fma_mix_f32 v145, v127, v11, v145 op_sel:[0,1,0] op_sel_hi:[0,1,0]
	v_fma_mix_f32 v144, v128, v12, v144 op_sel_hi:[0,1,0]
	v_fma_mix_f32 v145, v129, v12, v145 op_sel:[0,1,0] op_sel_hi:[0,1,0]
	v_fma_mix_f32 v144, v130, v13, v144 op_sel_hi:[0,1,0]
	v_fma_mix_f32 v145, v131, v13, v145 op_sel:[0,1,0] op_sel_hi:[0,1,0]
	v_fma_mix_f32 v144, v132, v14, v144 op_sel_hi:[0,1,0]
	v_fma_mix_f32 v145, v133, v14, v145 op_sel:[0,1,0] op_sel_hi:[0,1,0]
	v_fma_mix_f32 v144, v134, v15, v144 op_sel_hi:[0,1,0]
	v_fma_mix_f32 v145, v135, v15, v145 op_sel:[0,1,0] op_sel_hi:[0,1,0]
	v_fma_mix_f32 v144, v136, v16, v144 op_sel_hi:[0,1,0]
	v_fma_mix_f32 v145, v137, v16, v145 op_sel:[0,1,0] op_sel_hi:[0,1,0]
	v_fma_mix_f32 v144, v138, v17, v144 op_sel_hi:[0,1,0]
	v_fma_mix_f32 v145, v139, v17, v145 op_sel:[0,1,0] op_sel_hi:[0,1,0]
	v_fma_mix_f32 v144, v140, v18, v144 op_sel_hi:[0,1,0]
	v_fma_mix_f32 v145, v141, v18, v145 op_sel:[0,1,0] op_sel_hi:[0,1,0]
	v_fma_mix_f32 v144, v142, v19, v144 op_sel_hi:[0,1,0]
	v_fma_mix_f32 v145, v143, v19, v145 op_sel:[0,1,0] op_sel_hi:[0,1,0]
	v_add_f32_e32 v151, v144, v145
	v_readlane_b32 s29, v37, s28
	s_add_u32 s28, s28, 1
	s_mul_hi_u32 s27, s29, 0x640
	s_mul_i32 s26, s29, 0x640
	s_add_u32 s26, s16, s26
	s_addc_u32 s27, s17, s27
	global_load_dwordx4 v[88:91], v2, s[26:27]
	global_load_dwordx2 v[92:93], v2, s[26:27] offset:16
	global_load_ubyte v94, v3, s[26:27]
	s_waitcnt vmcnt(21)
	v_lshlrev_b32_e32 v192, 23, v102
	v_cvt_scalef32_pk32_f32_fp6 v[112:143], v[96:101], v192
	v_fma_mix_f32 v144, v112, v4, 0 op_sel_hi:[0,1,0]
	v_fma_mix_f32 v145, v113, v4, 0 op_sel:[0,1,0] op_sel_hi:[0,1,0]
	v_fma_mix_f32 v144, v114, v5, v144 op_sel_hi:[0,1,0]
	v_fma_mix_f32 v145, v115, v5, v145 op_sel:[0,1,0] op_sel_hi:[0,1,0]
	v_fma_mix_f32 v144, v116, v6, v144 op_sel_hi:[0,1,0]
	v_fma_mix_f32 v145, v117, v6, v145 op_sel:[0,1,0] op_sel_hi:[0,1,0]
	v_fma_mix_f32 v144, v118, v7, v144 op_sel_hi:[0,1,0]
	v_fma_mix_f32 v145, v119, v7, v145 op_sel:[0,1,0] op_sel_hi:[0,1,0]
	v_fma_mix_f32 v144, v120, v8, v144 op_sel_hi:[0,1,0]
	v_fma_mix_f32 v145, v121, v8, v145 op_sel:[0,1,0] op_sel_hi:[0,1,0]
	v_fma_mix_f32 v144, v122, v9, v144 op_sel_hi:[0,1,0]
	v_fma_mix_f32 v145, v123, v9, v145 op_sel:[0,1,0] op_sel_hi:[0,1,0]
	v_fma_mix_f32 v144, v124, v10, v144 op_sel_hi:[0,1,0]
	v_fma_mix_f32 v145, v125, v10, v145 op_sel:[0,1,0] op_sel_hi:[0,1,0]
	v_fma_mix_f32 v144, v126, v11, v144 op_sel_hi:[0,1,0]
	v_fma_mix_f32 v145, v127, v11, v145 op_sel:[0,1,0] op_sel_hi:[0,1,0]
	v_fma_mix_f32 v144, v128, v12, v144 op_sel_hi:[0,1,0]
	v_fma_mix_f32 v145, v129, v12, v145 op_sel:[0,1,0] op_sel_hi:[0,1,0]
	v_fma_mix_f32 v144, v130, v13, v144 op_sel_hi:[0,1,0]
	v_fma_mix_f32 v145, v131, v13, v145 op_sel:[0,1,0] op_sel_hi:[0,1,0]
	v_fma_mix_f32 v144, v132, v14, v144 op_sel_hi:[0,1,0]
	v_fma_mix_f32 v145, v133, v14, v145 op_sel:[0,1,0] op_sel_hi:[0,1,0]
	v_fma_mix_f32 v144, v134, v15, v144 op_sel_hi:[0,1,0]
	v_fma_mix_f32 v145, v135, v15, v145 op_sel:[0,1,0] op_sel_hi:[0,1,0]
	v_fma_mix_f32 v144, v136, v16, v144 op_sel_hi:[0,1,0]
	v_fma_mix_f32 v145, v137, v16, v145 op_sel:[0,1,0] op_sel_hi:[0,1,0]
	v_fma_mix_f32 v144, v138, v17, v144 op_sel_hi:[0,1,0]
	v_fma_mix_f32 v145, v139, v17, v145 op_sel:[0,1,0] op_sel_hi:[0,1,0]
	v_fma_mix_f32 v144, v140, v18, v144 op_sel_hi:[0,1,0]
	v_fma_mix_f32 v145, v141, v18, v145 op_sel:[0,1,0] op_sel_hi:[0,1,0]
	v_fma_mix_f32 v144, v142, v19, v144 op_sel_hi:[0,1,0]
	v_fma_mix_f32 v145, v143, v19, v145 op_sel:[0,1,0] op_sel_hi:[0,1,0]
	v_add_f32_e32 v152, v144, v145
	v_readlane_b32 s29, v37, s28
	s_add_u32 s28, s28, 1
	s_mul_hi_u32 s27, s29, 0x640
	s_mul_i32 s26, s29, 0x640
	s_add_u32 s26, s16, s26
	s_addc_u32 s27, s17, s27
	global_load_dwordx4 v[96:99], v2, s[26:27]
	global_load_dwordx2 v[100:101], v2, s[26:27] offset:16
	global_load_ubyte v102, v3, s[26:27]
	s_waitcnt vmcnt(21)
; __device__ __forceinline__ float row_sum16(float v) { v += __shfl_xor(v, 1); v += __shfl_xor(v, 2); v += __shfl_xor(v, 4); v += __shfl_xor(v, 8); return v; }
; __device__ __forceinline__ float wave_sum(float v) { v = row_sum16(v); v += __shfl_xor(v, 16); v += __shfl_xor(v, 32); return v; }
; #define PB_FENCE asm volatile("" ::: "memory")
; __device__ __forceinline__ float row_sum16(float v) { v += dppf<0xB1>(v); v += dppf<0x4E>(v); v += dppf<0x124>(v); v += dppf<0x128>(v); return v; }
; __device__ __forceinline__ float wave_sum(float v) {
;   v = row_sum16(v);
;   const float r0 = __builtin_bit_cast(float, __builtin_amdgcn_readlane(__builtin_bit_cast(int, v), 0));
;   const float r1 = __builtin_bit_cast(float, __builtin_amdgcn_readlane(__builtin_bit_cast(int, v), 16));
;   const float r2 = __builtin_bit_cast(float, __builtin_amdgcn_readlane(__builtin_bit_cast(int, v), 32));
;   const float r3 = __builtin_bit_cast(float, __builtin_amdgcn_readlane(__builtin_bit_cast(int, v), 48));
;   return (r0 + r1) + (r2 + r3);
; }
; __device__ __forceinline__ void ph_peer_apply(const Params& P, int layer, float* xlat, float* xctx_in, float* xctx_out, int nrows, bool write_next, char* smem, float* xlat_out = nullptr) {
;     ...
;     constexpr int NG = NSEL / PB_G;
;     PB_LOAD(bufA, tu, 0);
;     for (int gq = 0; gq < NG; gq += 2) {
;       PB_LOAD(bufB, tu, gq + 1); PB_FENCE;
;       PB_DOT(bufA, gq);
;       if (gq + 2 < NG) PB_LOAD(bufA, tu, gq + 2);
;       PB_FENCE;
;       PB_DOT(bufB, gq + 1);
;     }
	v_lshlrev_b32_e32 v192, 23, v110
	v_cvt_scalef32_pk32_f32_fp6 v[112:143], v[104:109], v192
	v_fma_mix_f32 v144, v112, v4, 0 op_sel_hi:[0,1,0]
	v_fma_mix_f32 v145, v113, v4, 0 op_sel:[0,1,0] op_sel_hi:[0,1,0]
	v_fma_mix_f32 v144, v114, v5, v144 op_sel_hi:[0,1,0]
	v_fma_mix_f32 v145, v115, v5, v145 op_sel:[0,1,0] op_sel_hi:[0,1,0]
	v_fma_mix_f32 v144, v116, v6, v144 op_sel_hi:[0,1,0]
	v_fma_mix_f32 v145, v117, v6, v145 op_sel:[0,1,0] op_sel_hi:[0,1,0]
	v_fma_mix_f32 v144, v118, v7, v144 op_sel_hi:[0,1,0]
	v_fma_mix_f32 v145, v119, v7, v145 op_sel:[0,1,0] op_sel_hi:[0,1,0]
	v_fma_mix_f32 v144, v120, v8, v144 op_sel_hi:[0,1,0]
	v_fma_mix_f32 v145, v121, v8, v145 op_sel:[0,1,0] op_sel_hi:[0,1,0]
	v_fma_mix_f32 v144, v122, v9, v144 op_sel_hi:[0,1,0]
	v_fma_mix_f32 v145, v123, v9, v145 op_sel:[0,1,0] op_sel_hi:[0,1,0]
	v_fma_mix_f32 v144, v124, v10, v144 op_sel_hi:[0,1,0]
	v_fma_mix_f32 v145, v125, v10, v145 op_sel:[0,1,0] op_sel_hi:[0,1,0]
	v_fma_mix_f32 v144, v126, v11, v144 op_sel_hi:[0,1,0]
	v_fma_mix_f32 v145, v127, v11, v145 op_sel:[0,1,0] op_sel_hi:[0,1,0]
	v_fma_mix_f32 v144, v128, v12, v144 op_sel_hi:[0,1,0]
	v_fma_mix_f32 v145, v129, v12, v145 op_sel:[0,1,0] op_sel_hi:[0,1,0]
	v_fma_mix_f32 v144, v130, v13, v144 op_sel_hi:[0,1,0]
	v_fma_mix_f32 v145, v131, v13, v145 op_sel:[0,1,0] op_sel_hi:[0,1,0]
	v_fma_mix_f32 v144, v132, v14, v144 op_sel_hi:[0,1,0]
	v_fma_mix_f32 v145, v133, v14, v145 op_sel:[0,1,0] op_sel_hi:[0,1,0]
	v_fma_mix_f32 v144, v134, v15, v144 op_sel_hi:[0,1,0]
	v_fma_mix_f32 v145, v135, v15, v145 op_sel:[0,1,0] op_sel_hi:[0,1,0]
	v_fma_mix_f32 v144, v136, v16, v144 op_sel_hi:[0,1,0]
	v_fma_mix_f32 v145, v137, v16, v145 op_sel:[0,1,0] op_sel_hi:[0,1,0]
	v_fma_mix_f32 v144, v138, v17, v144 op_sel_hi:[0,1,0]
	v_fma_mix_f32 v145, v139, v17, v145 op_sel:[0,1,0] op_sel_hi:[0,1,0]
	v_fma_mix_f32 v144, v140, v18, v144 op_sel_hi:[0,1,0]
	v_fma_mix_f32 v145, v141, v18, v145 op_sel:[0,1,0] op_sel_hi:[0,1,0]
	v_fma_mix_f32 v144, v142, v19, v144 op_sel_hi:[0,1,0]
	v_fma_mix_f32 v145, v143, v19, v145 op_sel:[0,1,0] op_sel_hi:[0,1,0]
	v_add_f32_e32 v153, v144, v145
	v_readlane_b32 s29, v37, s28
	s_add_u32 s28, s28, 1
	s_mul_hi_u32 s27, s29, 0x640
	s_mul_i32 s26, s29, 0x640
	s_add_u32 s26, s16, s26
	s_addc_u32 s27, s17, s27
	global_load_dwordx4 v[104:107], v2, s[26:27]
	global_load_dwordx2 v[108:109], v2, s[26:27] offset:16
	global_load_ubyte v110, v3, s[26:27]
	v_add_f32_dpp v146, v146, v146 row_ror:8 row_mask:0xf bank_mask:0xf bound_ctrl:1
	v_add_f32_dpp v147, v147, v147 row_ror:8 row_mask:0xf bank_mask:0xf bound_ctrl:1
	v_add_f32_dpp v148, v148, v148 row_ror:8 row_mask:0xf bank_mask:0xf bound_ctrl:1
	v_add_f32_dpp v149, v149, v149 row_ror:8 row_mask:0xf bank_mask:0xf bound_ctrl:1
	v_add_f32_dpp v146, v150, v150 row_ror:8 row_mask:0xf bank_mask:0xc bound_ctrl:1
	v_add_f32_dpp v147, v151, v151 row_ror:8 row_mask:0xf bank_mask:0xc bound_ctrl:1
	v_add_f32_dpp v148, v152, v152 row_ror:8 row_mask:0xf bank_mask:0xc bound_ctrl:1
	v_add_f32_dpp v149, v153, v153 row_ror:8 row_mask:0xf bank_mask:0xc bound_ctrl:1
	v_add_f32_dpp v146, v146, v146 row_half_mirror row_mask:0xf bank_mask:0xf bound_ctrl:1
	v_add_f32_dpp v147, v147, v147 row_half_mirror row_mask:0xf bank_mask:0xf bound_ctrl:1
	v_add_f32_dpp v146, v148, v148 row_half_mirror row_mask:0xf bank_mask:0xa bound_ctrl:1
	v_add_f32_dpp v147, v149, v149 row_half_mirror row_mask:0xf bank_mask:0xa bound_ctrl:1
	s_nop 1
	v_add_f32_dpp v146, v146, v146 quad_perm:[1,0,3,2] row_mask:0xf bank_mask:0xf bound_ctrl:1
	v_add_f32_dpp v147, v147, v147 quad_perm:[1,0,3,2] row_mask:0xf bank_mask:0xf bound_ctrl:1
	s_nop 0
	v_add_f32_dpp v146, v146, v146 quad_perm:[2,3,0,1] row_mask:0xf bank_mask:0xf bound_ctrl:1
	v_add_f32_dpp v147, v147, v147 quad_perm:[2,3,0,1] row_mask:0xf bank_mask:0xf bound_ctrl:1
	v_mov_b32_e32 v193, v146
	v_mov_b32_e32 v194, v147
	s_nop 1
	v_permlane32_swap_b32_e32 v193, v146
	v_permlane32_swap_b32_e32 v194, v147
	v_add_f32_e32 v146, v146, v193
	v_add_f32_e32 v147, v147, v194
	v_mov_b32_e32 v193, v146
	v_mov_b32_e32 v194, v147
	s_nop 1
	v_permlane16_swap_b32_e32 v193, v146
	v_permlane16_swap_b32_e32 v194, v147
	v_add_f32_e32 v146, v146, v193
	v_add_f32_e32 v147, v147, v194
	v_cndmask_b32_e64 v146, v146, v147, s[34:35]
	s_mov_b64 exec, s[46:47]
	ds_write_b32 v229, v146
	s_mov_b64 exec, -1
	v_add_u32_e32 v229, 32, v229
	s_sub_u32 s30, s30, 1
	s_cmp_lg_u32 s30, 0
	s_cbranch_scc1 .Lap0_s1_loop2
	s_waitcnt vmcnt(21)
	v_lshlrev_b32_e32 v192, 23, v54
	v_cvt_scalef32_pk32_f32_fp6 v[112:143], v[48:53], v192
	v_fma_mix_f32 v144, v112, v4, 0 op_sel_hi:[0,1,0]
	v_fma_mix_f32 v145, v113, v4, 0 op_sel:[0,1,0] op_sel_hi:[0,1,0]
	v_fma_mix_f32 v144, v114, v5, v144 op_sel_hi:[0,1,0]
	v_fma_mix_f32 v145, v115, v5, v145 op_sel:[0,1,0] op_sel_hi:[0,1,0]
	v_fma_mix_f32 v144, v116, v6, v144 op_sel_hi:[0,1,0]
	v_fma_mix_f32 v145, v117, v6, v145 op_sel:[0,1,0] op_sel_hi:[0,1,0]
	v_fma_mix_f32 v144, v118, v7, v144 op_sel_hi:[0,1,0]
	v_fma_mix_f32 v145, v119, v7, v145 op_sel:[0,1,0] op_sel_hi:[0,1,0]
	v_fma_mix_f32 v144, v120, v8, v144 op_sel_hi:[0,1,0]
	v_fma_mix_f32 v145, v121, v8, v145 op_sel:[0,1,0] op_sel_hi:[0,1,0]
	v_fma_mix_f32 v144, v122, v9, v144 op_sel_hi:[0,1,0]
	v_fma_mix_f32 v145, v123, v9, v145 op_sel:[0,1,0] op_sel_hi:[0,1,0]
	v_fma_mix_f32 v144, v124, v10, v144 op_sel_hi:[0,1,0]
	v_fma_mix_f32 v145, v125, v10, v145 op_sel:[0,1,0] op_sel_hi:[0,1,0]
	v_fma_mix_f32 v144, v126, v11, v144 op_sel_hi:[0,1,0]
	v_fma_mix_f32 v145, v127, v11, v145 op_sel:[0,1,0] op_sel_hi:[0,1,0]
	v_fma_mix_f32 v144, v128, v12, v144 op_sel_hi:[0,1,0]
	v_fma_mix_f32 v145, v129, v12, v145 op_sel:[0,1,0] op_sel_hi:[0,1,0]
	v_fma_mix_f32 v144, v130, v13, v144 op_sel_hi:[0,1,0]
	v_fma_mix_f32 v145, v131, v13, v145 op_sel:[0,1,0] op_sel_hi:[0,1,0]
	v_fma_mix_f32 v144, v132, v14, v144 op_sel_hi:[0,1,0]
	v_fma_mix_f32 v145, v133, v14, v145 op_sel:[0,1,0] op_sel_hi:[0,1,0]
	v_fma_mix_f32 v144, v134, v15, v144 op_sel_hi:[0,1,0]
	v_fma_mix_f32 v145, v135, v15, v145 op_sel:[0,1,0] op_sel_hi:[0,1,0]
	v_fma_mix_f32 v144, v136, v16, v144 op_sel_hi:[0,1,0]
	v_fma_mix_f32 v145, v137, v16, v145 op_sel:[0,1,0] op_sel_hi:[0,1,0]
	v_fma_mix_f32 v144, v138, v17, v144 op_sel_hi:[0,1,0]
	v_fma_mix_f32 v145, v139, v17, v145 op_sel:[0,1,0] op_sel_hi:[0,1,0]
	v_fma_mix_f32 v144, v140, v18, v144 op_sel_hi:[0,1,0]
	v_fma_mix_f32 v145, v141, v18, v145 op_sel:[0,1,0] op_sel_hi:[0,1,0]
	v_fma_mix_f32 v144, v142, v19, v144 op_sel_hi:[0,1,0]
	v_fma_mix_f32 v145, v143, v19, v145 op_sel:[0,1,0] op_sel_hi:[0,1,0]
	v_add_f32_e32 v146, v144, v145
	s_waitcnt vmcnt(18)
	v_lshlrev_b32_e32 v192, 23, v62
	v_cvt_scalef32_pk32_f32_fp6 v[112:143], v[56:61], v192
	v_fma_mix_f32 v144, v112, v4, 0 op_sel_hi:[0,1,0]
	v_fma_mix_f32 v145, v113, v4, 0 op_sel:[0,1,0] op_sel_hi:[0,1,0]
	v_fma_mix_f32 v144, v114, v5, v144 op_sel_hi:[0,1,0]
	v_fma_mix_f32 v145, v115, v5, v145 op_sel:[0,1,0] op_sel_hi:[0,1,0]
	v_fma_mix_f32 v144, v116, v6, v144 op_sel_hi:[0,1,0]
	v_fma_mix_f32 v145, v117, v6, v145 op_sel:[0,1,0] op_sel_hi:[0,1,0]
	v_fma_mix_f32 v144, v118, v7, v144 op_sel_hi:[0,1,0]
	v_fma_mix_f32 v145, v119, v7, v145 op_sel:[0,1,0] op_sel_hi:[0,1,0]
	v_fma_mix_f32 v144, v120, v8, v144 op_sel_hi:[0,1,0]
	v_fma_mix_f32 v145, v121, v8, v145 op_sel:[0,1,0] op_sel_hi:[0,1,0]
	v_fma_mix_f32 v144, v122, v9, v144 op_sel_hi:[0,1,0]
	v_fma_mix_f32 v145, v123, v9, v145 op_sel:[0,1,0] op_sel_hi:[0,1,0]
	v_fma_mix_f32 v144, v124, v10, v144 op_sel_hi:[0,1,0]
	v_fma_mix_f32 v145, v125, v10, v145 op_sel:[0,1,0] op_sel_hi:[0,1,0]
	v_fma_mix_f32 v144, v126, v11, v144 op_sel_hi:[0,1,0]
	v_fma_mix_f32 v145, v127, v11, v145 op_sel:[0,1,0] op_sel_hi:[0,1,0]
	v_fma_mix_f32 v144, v128, v12, v144 op_sel_hi:[0,1,0]
	v_fma_mix_f32 v145, v129, v12, v145 op_sel:[0,1,0] op_sel_hi:[0,1,0]
	v_fma_mix_f32 v144, v130, v13, v144 op_sel_hi:[0,1,0]
	v_fma_mix_f32 v145, v131, v13, v145 op_sel:[0,1,0] op_sel_hi:[0,1,0]
	v_fma_mix_f32 v144, v132, v14, v144 op_sel_hi:[0,1,0]
	v_fma_mix_f32 v145, v133, v14, v145 op_sel:[0,1,0] op_sel_hi:[0,1,0]
	v_fma_mix_f32 v144, v134, v15, v144 op_sel_hi:[0,1,0]
	v_fma_mix_f32 v145, v135, v15, v145 op_sel:[0,1,0] op_sel_hi:[0,1,0]
	v_fma_mix_f32 v144, v136, v16, v144 op_sel_hi:[0,1,0]
	v_fma_mix_f32 v145, v137, v16, v145 op_sel:[0,1,0] op_sel_hi:[0,1,0]
	v_fma_mix_f32 v144, v138, v17, v144 op_sel_hi:[0,1,0]
	v_fma_mix_f32 v145, v139, v17, v145 op_sel:[0,1,0] op_sel_hi:[0,1,0]
	v_fma_mix_f32 v144, v140, v18, v144 op_sel_hi:[0,1,0]
	v_fma_mix_f32 v145, v141, v18, v145 op_sel:[0,1,0] op_sel_hi:[0,1,0]
	v_fma_mix_f32 v144, v142, v19, v144 op_sel_hi:[0,1,0]
	v_fma_mix_f32 v145, v143, v19, v145 op_sel:[0,1,0] op_sel_hi:[0,1,0]
	v_add_f32_e32 v147, v144, v145
	s_waitcnt vmcnt(15)
	v_lshlrev_b32_e32 v192, 23, v70
	v_cvt_scalef32_pk32_f32_fp6 v[112:143], v[64:69], v192
	v_fma_mix_f32 v144, v112, v4, 0 op_sel_hi:[0,1,0]
	v_fma_mix_f32 v145, v113, v4, 0 op_sel:[0,1,0] op_sel_hi:[0,1,0]
	v_fma_mix_f32 v144, v114, v5, v144 op_sel_hi:[0,1,0]
	v_fma_mix_f32 v145, v115, v5, v145 op_sel:[0,1,0] op_sel_hi:[0,1,0]
	v_fma_mix_f32 v144, v116, v6, v144 op_sel_hi:[0,1,0]
	v_fma_mix_f32 v145, v117, v6, v145 op_sel:[0,1,0] op_sel_hi:[0,1,0]
	v_fma_mix_f32 v144, v118, v7, v144 op_sel_hi:[0,1,0]
	v_fma_mix_f32 v145, v119, v7, v145 op_sel:[0,1,0] op_sel_hi:[0,1,0]
	v_fma_mix_f32 v144, v120, v8, v144 op_sel_hi:[0,1,0]
	v_fma_mix_f32 v145, v121, v8, v145 op_sel:[0,1,0] op_sel_hi:[0,1,0]
	v_fma_mix_f32 v144, v122, v9, v144 op_sel_hi:[0,1,0]
	v_fma_mix_f32 v145, v123, v9, v145 op_sel:[0,1,0] op_sel_hi:[0,1,0]
	v_fma_mix_f32 v144, v124, v10, v144 op_sel_hi:[0,1,0]
	v_fma_mix_f32 v145, v125, v10, v145 op_sel:[0,1,0] op_sel_hi:[0,1,0]
	v_fma_mix_f32 v144, v126, v11, v144 op_sel_hi:[0,1,0]
	v_fma_mix_f32 v145, v127, v11, v145 op_sel:[0,1,0] op_sel_hi:[0,1,0]
	v_fma_mix_f32 v144, v128, v12, v144 op_sel_hi:[0,1,0]
	v_fma_mix_f32 v145, v129, v12, v145 op_sel:[0,1,0] op_sel_hi:[0,1,0]
	v_fma_mix_f32 v144, v130, v13, v144 op_sel_hi:[0,1,0]
	v_fma_mix_f32 v145, v131, v13, v145 op_sel:[0,1,0] op_sel_hi:[0,1,0]
	v_fma_mix_f32 v144, v132, v14, v144 op_sel_hi:[0,1,0]
	v_fma_mix_f32 v145, v133, v14, v145 op_sel:[0,1,0] op_sel_hi:[0,1,0]
	v_fma_mix_f32 v144, v134, v15, v144 op_sel_hi:[0,1,0]
	v_fma_mix_f32 v145, v135, v15, v145 op_sel:[0,1,0] op_sel_hi:[0,1,0]
	v_fma_mix_f32 v144, v136, v16, v144 op_sel_hi:[0,1,0]
	v_fma_mix_f32 v145, v137, v16, v145 op_sel:[0,1,0] op_sel_hi:[0,1,0]
	v_fma_mix_f32 v144, v138, v17, v144 op_sel_hi:[0,1,0]
	v_fma_mix_f32 v145, v139, v17, v145 op_sel:[0,1,0] op_sel_hi:[0,1,0]
	v_fma_mix_f32 v144, v140, v18, v144 op_sel_hi:[0,1,0]
	v_fma_mix_f32 v145, v141, v18, v145 op_sel:[0,1,0] op_sel_hi:[0,1,0]
	v_fma_mix_f32 v144, v142, v19, v144 op_sel_hi:[0,1,0]
	v_fma_mix_f32 v145, v143, v19, v145 op_sel:[0,1,0] op_sel_hi:[0,1,0]
	v_add_f32_e32 v148, v144, v145
	s_waitcnt vmcnt(12)
; #define PB_FENCE asm volatile("" ::: "memory")
; __device__ __forceinline__ void ph_peer_apply(const Params& P, int layer, float* xlat, float* xctx_in, float* xctx_out, int nrows, bool write_next, char* smem, float* xlat_out = nullptr) {
;     ...
;     constexpr int NG = NSEL / PB_G;
;     PB_LOAD(bufA, tu, 0);
;     for (int gq = 0; gq < NG; gq += 2) {
;       PB_LOAD(bufB, tu, gq + 1); PB_FENCE;
;       PB_DOT(bufA, gq);
;       if (gq + 2 < NG) PB_LOAD(bufA, tu, gq + 2);
;       PB_FENCE;
;       PB_DOT(bufB, gq + 1);
;     }
	v_lshlrev_b32_e32 v192, 23, v78
	v_cvt_scalef32_pk32_f32_fp6 v[112:143], v[72:77], v192
	v_fma_mix_f32 v144, v112, v4, 0 op_sel_hi:[0,1,0]
	v_fma_mix_f32 v145, v113, v4, 0 op_sel:[0,1,0] op_sel_hi:[0,1,0]
	v_fma_mix_f32 v144, v114, v5, v144 op_sel_hi:[0,1,0]
	v_fma_mix_f32 v145, v115, v5, v145 op_sel:[0,1,0] op_sel_hi:[0,1,0]
	v_fma_mix_f32 v144, v116, v6, v144 op_sel_hi:[0,1,0]
	v_fma_mix_f32 v145, v117, v6, v145 op_sel:[0,1,0] op_sel_hi:[0,1,0]
	v_fma_mix_f32 v144, v118, v7, v144 op_sel_hi:[0,1,0]
	v_fma_mix_f32 v145, v119, v7, v145 op_sel:[0,1,0] op_sel_hi:[0,1,0]
	v_fma_mix_f32 v144, v120, v8, v144 op_sel_hi:[0,1,0]
	v_fma_mix_f32 v145, v121, v8, v145 op_sel:[0,1,0] op_sel_hi:[0,1,0]
	v_fma_mix_f32 v144, v122, v9, v144 op_sel_hi:[0,1,0]
	v_fma_mix_f32 v145, v123, v9, v145 op_sel:[0,1,0] op_sel_hi:[0,1,0]
	v_fma_mix_f32 v144, v124, v10, v144 op_sel_hi:[0,1,0]
	v_fma_mix_f32 v145, v125, v10, v145 op_sel:[0,1,0] op_sel_hi:[0,1,0]
	v_fma_mix_f32 v144, v126, v11, v144 op_sel_hi:[0,1,0]
	v_fma_mix_f32 v145, v127, v11, v145 op_sel:[0,1,0] op_sel_hi:[0,1,0]
	v_fma_mix_f32 v144, v128, v12, v144 op_sel_hi:[0,1,0]
	v_fma_mix_f32 v145, v129, v12, v145 op_sel:[0,1,0] op_sel_hi:[0,1,0]
	v_fma_mix_f32 v144, v130, v13, v144 op_sel_hi:[0,1,0]
	v_fma_mix_f32 v145, v131, v13, v145 op_sel:[0,1,0] op_sel_hi:[0,1,0]
	v_fma_mix_f32 v144, v132, v14, v144 op_sel_hi:[0,1,0]
	v_fma_mix_f32 v145, v133, v14, v145 op_sel:[0,1,0] op_sel_hi:[0,1,0]
	v_fma_mix_f32 v144, v134, v15, v144 op_sel_hi:[0,1,0]
	v_fma_mix_f32 v145, v135, v15, v145 op_sel:[0,1,0] op_sel_hi:[0,1,0]
	v_fma_mix_f32 v144, v136, v16, v144 op_sel_hi:[0,1,0]
	v_fma_mix_f32 v145, v137, v16, v145 op_sel:[0,1,0] op_sel_hi:[0,1,0]
	v_fma_mix_f32 v144, v138, v17, v144 op_sel_hi:[0,1,0]
	v_fma_mix_f32 v145, v139, v17, v145 op_sel:[0,1,0] op_sel_hi:[0,1,0]
	v_fma_mix_f32 v144, v140, v18, v144 op_sel_hi:[0,1,0]
	v_fma_mix_f32 v145, v141, v18, v145 op_sel:[0,1,0] op_sel_hi:[0,1,0]
	v_fma_mix_f32 v144, v142, v19, v144 op_sel_hi:[0,1,0]
	v_fma_mix_f32 v145, v143, v19, v145 op_sel:[0,1,0] op_sel_hi:[0,1,0]
	v_add_f32_e32 v149, v144, v145
	s_waitcnt vmcnt(9)
	v_lshlrev_b32_e32 v192, 23, v86
	v_cvt_scalef32_pk32_f32_fp6 v[112:143], v[80:85], v192
	v_fma_mix_f32 v144, v112, v4, 0 op_sel_hi:[0,1,0]
	v_fma_mix_f32 v145, v113, v4, 0 op_sel:[0,1,0] op_sel_hi:[0,1,0]
	v_fma_mix_f32 v144, v114, v5, v144 op_sel_hi:[0,1,0]
	v_fma_mix_f32 v145, v115, v5, v145 op_sel:[0,1,0] op_sel_hi:[0,1,0]
	v_fma_mix_f32 v144, v116, v6, v144 op_sel_hi:[0,1,0]
	v_fma_mix_f32 v145, v117, v6, v145 op_sel:[0,1,0] op_sel_hi:[0,1,0]
	v_fma_mix_f32 v144, v118, v7, v144 op_sel_hi:[0,1,0]
	v_fma_mix_f32 v145, v119, v7, v145 op_sel:[0,1,0] op_sel_hi:[0,1,0]
	v_fma_mix_f32 v144, v120, v8, v144 op_sel_hi:[0,1,0]
	v_fma_mix_f32 v145, v121, v8, v145 op_sel:[0,1,0] op_sel_hi:[0,1,0]
	v_fma_mix_f32 v144, v122, v9, v144 op_sel_hi:[0,1,0]
	v_fma_mix_f32 v145, v123, v9, v145 op_sel:[0,1,0] op_sel_hi:[0,1,0]
	v_fma_mix_f32 v144, v124, v10, v144 op_sel_hi:[0,1,0]
	v_fma_mix_f32 v145, v125, v10, v145 op_sel:[0,1,0] op_sel_hi:[0,1,0]
	v_fma_mix_f32 v144, v126, v11, v144 op_sel_hi:[0,1,0]
	v_fma_mix_f32 v145, v127, v11, v145 op_sel:[0,1,0] op_sel_hi:[0,1,0]
	v_fma_mix_f32 v144, v128, v12, v144 op_sel_hi:[0,1,0]
	v_fma_mix_f32 v145, v129, v12, v145 op_sel:[0,1,0] op_sel_hi:[0,1,0]
	v_fma_mix_f32 v144, v130, v13, v144 op_sel_hi:[0,1,0]
	v_fma_mix_f32 v145, v131, v13, v145 op_sel:[0,1,0] op_sel_hi:[0,1,0]
	v_fma_mix_f32 v144, v132, v14, v144 op_sel_hi:[0,1,0]
	v_fma_mix_f32 v145, v133, v14, v145 op_sel:[0,1,0] op_sel_hi:[0,1,0]
	v_fma_mix_f32 v144, v134, v15, v144 op_sel_hi:[0,1,0]
	v_fma_mix_f32 v145, v135, v15, v145 op_sel:[0,1,0] op_sel_hi:[0,1,0]
	v_fma_mix_f32 v144, v136, v16, v144 op_sel_hi:[0,1,0]
	v_fma_mix_f32 v145, v137, v16, v145 op_sel:[0,1,0] op_sel_hi:[0,1,0]
	v_fma_mix_f32 v144, v138, v17, v144 op_sel_hi:[0,1,0]
	v_fma_mix_f32 v145, v139, v17, v145 op_sel:[0,1,0] op_sel_hi:[0,1,0]
	v_fma_mix_f32 v144, v140, v18, v144 op_sel_hi:[0,1,0]
	v_fma_mix_f32 v145, v141, v18, v145 op_sel:[0,1,0] op_sel_hi:[0,1,0]
	v_fma_mix_f32 v144, v142, v19, v144 op_sel_hi:[0,1,0]
	v_fma_mix_f32 v145, v143, v19, v145 op_sel:[0,1,0] op_sel_hi:[0,1,0]
	v_add_f32_e32 v150, v144, v145
	s_waitcnt vmcnt(6)
	v_lshlrev_b32_e32 v192, 23, v94
	v_cvt_scalef32_pk32_f32_fp6 v[112:143], v[88:93], v192
	v_fma_mix_f32 v144, v112, v4, 0 op_sel_hi:[0,1,0]
	v_fma_mix_f32 v145, v113, v4, 0 op_sel:[0,1,0] op_sel_hi:[0,1,0]
	v_fma_mix_f32 v144, v114, v5, v144 op_sel_hi:[0,1,0]
	v_fma_mix_f32 v145, v115, v5, v145 op_sel:[0,1,0] op_sel_hi:[0,1,0]
	v_fma_mix_f32 v144, v116, v6, v144 op_sel_hi:[0,1,0]
	v_fma_mix_f32 v145, v117, v6, v145 op_sel:[0,1,0] op_sel_hi:[0,1,0]
	v_fma_mix_f32 v144, v118, v7, v144 op_sel_hi:[0,1,0]
	v_fma_mix_f32 v145, v119, v7, v145 op_sel:[0,1,0] op_sel_hi:[0,1,0]
	v_fma_mix_f32 v144, v120, v8, v144 op_sel_hi:[0,1,0]
	v_fma_mix_f32 v145, v121, v8, v145 op_sel:[0,1,0] op_sel_hi:[0,1,0]
	v_fma_mix_f32 v144, v122, v9, v144 op_sel_hi:[0,1,0]
	v_fma_mix_f32 v145, v123, v9, v145 op_sel:[0,1,0] op_sel_hi:[0,1,0]
	v_fma_mix_f32 v144, v124, v10, v144 op_sel_hi:[0,1,0]
	v_fma_mix_f32 v145, v125, v10, v145 op_sel:[0,1,0] op_sel_hi:[0,1,0]
	v_fma_mix_f32 v144, v126, v11, v144 op_sel_hi:[0,1,0]
	v_fma_mix_f32 v145, v127, v11, v145 op_sel:[0,1,0] op_sel_hi:[0,1,0]
	v_fma_mix_f32 v144, v128, v12, v144 op_sel_hi:[0,1,0]
	v_fma_mix_f32 v145, v129, v12, v145 op_sel:[0,1,0] op_sel_hi:[0,1,0]
	v_fma_mix_f32 v144, v130, v13, v144 op_sel_hi:[0,1,0]
	v_fma_mix_f32 v145, v131, v13, v145 op_sel:[0,1,0] op_sel_hi:[0,1,0]
	v_fma_mix_f32 v144, v132, v14, v144 op_sel_hi:[0,1,0]
	v_fma_mix_f32 v145, v133, v14, v145 op_sel:[0,1,0] op_sel_hi:[0,1,0]
	v_fma_mix_f32 v144, v134, v15, v144 op_sel_hi:[0,1,0]
	v_fma_mix_f32 v145, v135, v15, v145 op_sel:[0,1,0] op_sel_hi:[0,1,0]
	v_fma_mix_f32 v144, v136, v16, v144 op_sel_hi:[0,1,0]
	v_fma_mix_f32 v145, v137, v16, v145 op_sel:[0,1,0] op_sel_hi:[0,1,0]
	v_fma_mix_f32 v144, v138, v17, v144 op_sel_hi:[0,1,0]
	v_fma_mix_f32 v145, v139, v17, v145 op_sel:[0,1,0] op_sel_hi:[0,1,0]
	v_fma_mix_f32 v144, v140, v18, v144 op_sel_hi:[0,1,0]
	v_fma_mix_f32 v145, v141, v18, v145 op_sel:[0,1,0] op_sel_hi:[0,1,0]
	v_fma_mix_f32 v144, v142, v19, v144 op_sel_hi:[0,1,0]
	v_fma_mix_f32 v145, v143, v19, v145 op_sel:[0,1,0] op_sel_hi:[0,1,0]
	v_add_f32_e32 v151, v144, v145
	s_waitcnt vmcnt(3)
; __device__ __forceinline__ float row_sum16(float v) { v += __shfl_xor(v, 1); v += __shfl_xor(v, 2); v += __shfl_xor(v, 4); v += __shfl_xor(v, 8); return v; }
; __device__ __forceinline__ float wave_sum(float v) { v = row_sum16(v); v += __shfl_xor(v, 16); v += __shfl_xor(v, 32); return v; }
; __device__ __forceinline__ float row_sum16(float v) { v += dppf<0xB1>(v); v += dppf<0x4E>(v); v += dppf<0x124>(v); v += dppf<0x128>(v); return v; }
; __device__ __forceinline__ float wave_sum(float v) {
;   v = row_sum16(v);
;   const float r0 = __builtin_bit_cast(float, __builtin_amdgcn_readlane(__builtin_bit_cast(int, v), 0));
;   const float r1 = __builtin_bit_cast(float, __builtin_amdgcn_readlane(__builtin_bit_cast(int, v), 16));
;   const float r2 = __builtin_bit_cast(float, __builtin_amdgcn_readlane(__builtin_bit_cast(int, v), 32));
;   const float r3 = __builtin_bit_cast(float, __builtin_amdgcn_readlane(__builtin_bit_cast(int, v), 48));
;   return (r0 + r1) + (r2 + r3);
; }
	v_lshlrev_b32_e32 v192, 23, v102
	v_cvt_scalef32_pk32_f32_fp6 v[112:143], v[96:101], v192
	v_fma_mix_f32 v144, v112, v4, 0 op_sel_hi:[0,1,0]
	v_fma_mix_f32 v145, v113, v4, 0 op_sel:[0,1,0] op_sel_hi:[0,1,0]
	v_fma_mix_f32 v144, v114, v5, v144 op_sel_hi:[0,1,0]
	v_fma_mix_f32 v145, v115, v5, v145 op_sel:[0,1,0] op_sel_hi:[0,1,0]
	v_fma_mix_f32 v144, v116, v6, v144 op_sel_hi:[0,1,0]
	v_fma_mix_f32 v145, v117, v6, v145 op_sel:[0,1,0] op_sel_hi:[0,1,0]
	v_fma_mix_f32 v144, v118, v7, v144 op_sel_hi:[0,1,0]
	v_fma_mix_f32 v145, v119, v7, v145 op_sel:[0,1,0] op_sel_hi:[0,1,0]
	v_fma_mix_f32 v144, v120, v8, v144 op_sel_hi:[0,1,0]
	v_fma_mix_f32 v145, v121, v8, v145 op_sel:[0,1,0] op_sel_hi:[0,1,0]
	v_fma_mix_f32 v144, v122, v9, v144 op_sel_hi:[0,1,0]
	v_fma_mix_f32 v145, v123, v9, v145 op_sel:[0,1,0] op_sel_hi:[0,1,0]
	v_fma_mix_f32 v144, v124, v10, v144 op_sel_hi:[0,1,0]
	v_fma_mix_f32 v145, v125, v10, v145 op_sel:[0,1,0] op_sel_hi:[0,1,0]
	v_fma_mix_f32 v144, v126, v11, v144 op_sel_hi:[0,1,0]
	v_fma_mix_f32 v145, v127, v11, v145 op_sel:[0,1,0] op_sel_hi:[0,1,0]
	v_fma_mix_f32 v144, v128, v12, v144 op_sel_hi:[0,1,0]
	v_fma_mix_f32 v145, v129, v12, v145 op_sel:[0,1,0] op_sel_hi:[0,1,0]
	v_fma_mix_f32 v144, v130, v13, v144 op_sel_hi:[0,1,0]
	v_fma_mix_f32 v145, v131, v13, v145 op_sel:[0,1,0] op_sel_hi:[0,1,0]
	v_fma_mix_f32 v144, v132, v14, v144 op_sel_hi:[0,1,0]
	v_fma_mix_f32 v145, v133, v14, v145 op_sel:[0,1,0] op_sel_hi:[0,1,0]
	v_fma_mix_f32 v144, v134, v15, v144 op_sel_hi:[0,1,0]
	v_fma_mix_f32 v145, v135, v15, v145 op_sel:[0,1,0] op_sel_hi:[0,1,0]
	v_fma_mix_f32 v144, v136, v16, v144 op_sel_hi:[0,1,0]
	v_fma_mix_f32 v145, v137, v16, v145 op_sel:[0,1,0] op_sel_hi:[0,1,0]
	v_fma_mix_f32 v144, v138, v17, v144 op_sel_hi:[0,1,0]
	v_fma_mix_f32 v145, v139, v17, v145 op_sel:[0,1,0] op_sel_hi:[0,1,0]
	v_fma_mix_f32 v144, v140, v18, v144 op_sel_hi:[0,1,0]
	v_fma_mix_f32 v145, v141, v18, v145 op_sel:[0,1,0] op_sel_hi:[0,1,0]
	v_fma_mix_f32 v144, v142, v19, v144 op_sel_hi:[0,1,0]
	v_fma_mix_f32 v145, v143, v19, v145 op_sel:[0,1,0] op_sel_hi:[0,1,0]
	v_add_f32_e32 v152, v144, v145
	s_waitcnt vmcnt(0)
	v_lshlrev_b32_e32 v192, 23, v110
	v_cvt_scalef32_pk32_f32_fp6 v[112:143], v[104:109], v192
	v_fma_mix_f32 v144, v112, v4, 0 op_sel_hi:[0,1,0]
	v_fma_mix_f32 v145, v113, v4, 0 op_sel:[0,1,0] op_sel_hi:[0,1,0]
	v_fma_mix_f32 v144, v114, v5, v144 op_sel_hi:[0,1,0]
	v_fma_mix_f32 v145, v115, v5, v145 op_sel:[0,1,0] op_sel_hi:[0,1,0]
	v_fma_mix_f32 v144, v116, v6, v144 op_sel_hi:[0,1,0]
	v_fma_mix_f32 v145, v117, v6, v145 op_sel:[0,1,0] op_sel_hi:[0,1,0]
	v_fma_mix_f32 v144, v118, v7, v144 op_sel_hi:[0,1,0]
	v_fma_mix_f32 v145, v119, v7, v145 op_sel:[0,1,0] op_sel_hi:[0,1,0]
	v_fma_mix_f32 v144, v120, v8, v144 op_sel_hi:[0,1,0]
	v_fma_mix_f32 v145, v121, v8, v145 op_sel:[0,1,0] op_sel_hi:[0,1,0]
	v_fma_mix_f32 v144, v122, v9, v144 op_sel_hi:[0,1,0]
	v_fma_mix_f32 v145, v123, v9, v145 op_sel:[0,1,0] op_sel_hi:[0,1,0]
	v_fma_mix_f32 v144, v124, v10, v144 op_sel_hi:[0,1,0]
	v_fma_mix_f32 v145, v125, v10, v145 op_sel:[0,1,0] op_sel_hi:[0,1,0]
	v_fma_mix_f32 v144, v126, v11, v144 op_sel_hi:[0,1,0]
	v_fma_mix_f32 v145, v127, v11, v145 op_sel:[0,1,0] op_sel_hi:[0,1,0]
	v_fma_mix_f32 v144, v128, v12, v144 op_sel_hi:[0,1,0]
	v_fma_mix_f32 v145, v129, v12, v145 op_sel:[0,1,0] op_sel_hi:[0,1,0]
	v_fma_mix_f32 v144, v130, v13, v144 op_sel_hi:[0,1,0]
	v_fma_mix_f32 v145, v131, v13, v145 op_sel:[0,1,0] op_sel_hi:[0,1,0]
	v_fma_mix_f32 v144, v132, v14, v144 op_sel_hi:[0,1,0]
	v_fma_mix_f32 v145, v133, v14, v145 op_sel:[0,1,0] op_sel_hi:[0,1,0]
	v_fma_mix_f32 v144, v134, v15, v144 op_sel_hi:[0,1,0]
	v_fma_mix_f32 v145, v135, v15, v145 op_sel:[0,1,0] op_sel_hi:[0,1,0]
	v_fma_mix_f32 v144, v136, v16, v144 op_sel_hi:[0,1,0]
	v_fma_mix_f32 v145, v137, v16, v145 op_sel:[0,1,0] op_sel_hi:[0,1,0]
	v_fma_mix_f32 v144, v138, v17, v144 op_sel_hi:[0,1,0]
	v_fma_mix_f32 v145, v139, v17, v145 op_sel:[0,1,0] op_sel_hi:[0,1,0]
	v_fma_mix_f32 v144, v140, v18, v144 op_sel_hi:[0,1,0]
	v_fma_mix_f32 v145, v141, v18, v145 op_sel:[0,1,0] op_sel_hi:[0,1,0]
	v_fma_mix_f32 v144, v142, v19, v144 op_sel_hi:[0,1,0]
	v_fma_mix_f32 v145, v143, v19, v145 op_sel:[0,1,0] op_sel_hi:[0,1,0]
	v_add_f32_e32 v153, v144, v145
	v_add_f32_dpp v146, v146, v146 row_ror:8 row_mask:0xf bank_mask:0xf bound_ctrl:1
	v_add_f32_dpp v147, v147, v147 row_ror:8 row_mask:0xf bank_mask:0xf bound_ctrl:1
	v_add_f32_dpp v148, v148, v148 row_ror:8 row_mask:0xf bank_mask:0xf bound_ctrl:1
	v_add_f32_dpp v149, v149, v149 row_ror:8 row_mask:0xf bank_mask:0xf bound_ctrl:1
	v_add_f32_dpp v146, v150, v150 row_ror:8 row_mask:0xf bank_mask:0xc bound_ctrl:1
	v_add_f32_dpp v147, v151, v151 row_ror:8 row_mask:0xf bank_mask:0xc bound_ctrl:1
	v_add_f32_dpp v148, v152, v152 row_ror:8 row_mask:0xf bank_mask:0xc bound_ctrl:1
	v_add_f32_dpp v149, v153, v153 row_ror:8 row_mask:0xf bank_mask:0xc bound_ctrl:1
	v_add_f32_dpp v146, v146, v146 row_half_mirror row_mask:0xf bank_mask:0xf bound_ctrl:1
	v_add_f32_dpp v147, v147, v147 row_half_mirror row_mask:0xf bank_mask:0xf bound_ctrl:1
	v_add_f32_dpp v146, v148, v148 row_half_mirror row_mask:0xf bank_mask:0xa bound_ctrl:1
	v_add_f32_dpp v147, v149, v149 row_half_mirror row_mask:0xf bank_mask:0xa bound_ctrl:1
	s_nop 1
	v_add_f32_dpp v146, v146, v146 quad_perm:[1,0,3,2] row_mask:0xf bank_mask:0xf bound_ctrl:1
	v_add_f32_dpp v147, v147, v147 quad_perm:[1,0,3,2] row_mask:0xf bank_mask:0xf bound_ctrl:1
	s_nop 0
	v_add_f32_dpp v146, v146, v146 quad_perm:[2,3,0,1] row_mask:0xf bank_mask:0xf bound_ctrl:1
	v_add_f32_dpp v147, v147, v147 quad_perm:[2,3,0,1] row_mask:0xf bank_mask:0xf bound_ctrl:1
	v_mov_b32_e32 v193, v146
	v_mov_b32_e32 v194, v147
	s_nop 1
	v_permlane32_swap_b32_e32 v193, v146
	v_permlane32_swap_b32_e32 v194, v147
	v_add_f32_e32 v146, v146, v193
	v_add_f32_e32 v147, v147, v194
	v_mov_b32_e32 v193, v146
	v_mov_b32_e32 v194, v147
	s_nop 1
	v_permlane16_swap_b32_e32 v193, v146
	v_permlane16_swap_b32_e32 v194, v147
	v_add_f32_e32 v146, v146, v193
	v_add_f32_e32 v147, v147, v194
	v_cndmask_b32_e64 v146, v146, v147, s[34:35]
	s_mov_b64 exec, s[46:47]
	ds_write_b32 v229, v146
	s_mov_b64 exec, -1
	v_add_u32_e32 v229, 32, v229
	s_lshl_b32 s15, s14, 9
	v_add_u32_e32 v194, s15, v228
	s_waitcnt lgkmcnt(0)
; __device__ __forceinline__ float geluf_(float x) { return 0.5f * x * (1.0f + tanhf(0.7978845608028654f * (x + 0.044715f * x * x * x))); }
; #define PB_FENCE asm volatile("" ::: "memory")
; __device__ __forceinline__ void ph_peer_apply(const Params& P, int layer, float* xlat, float* xctx_in, float* xctx_out, int nrows, bool write_next, char* smem, float* xlat_out = nullptr) {
;     ...
;     a0 = geluf_(a0) * g0; a1 = geluf_(a1) * g1;
;     float o[32];
; #pragma unroll
;     for (int j = 0; j < 32; ++j) o[j] = 0.f;
;     ...
;     PB_LOAD(bufA, tv, 0);
;     for (int gq = 0; gq < NG; gq += 2) {
;       PB_LOAD(bufB, tv, gq + 1); PB_FENCE;
;       PB_ACC(bufA, gq);
;       if (gq + 2 < NG) PB_LOAD(bufA, tv, gq + 2);
;       PB_FENCE;
;       PB_ACC(bufB, gq + 1);
;     }
	ds_read_b32 v195, v194
	ds_read_b32 v196, v194 offset:256
	s_waitcnt lgkmcnt(0)
	v_mul_f32_e32 v199, v195, v195
	v_mul_f32_e32 v199, v199, v195
	v_fmamk_f32 v199, v199, 0x3d372713, v195
	v_mul_f32_e32 v199, 0xc0135761, v199
	v_exp_f32_e32 v199, v199
	s_nop 0
	v_add_f32_e32 v199, 1.0, v199
	v_rcp_f32_e32 v199, v199
	s_nop 0
	v_mul_f32_e32 v199, v199, v195
	v_mul_f32_e32 v197, v199, v40
	v_mul_f32_e32 v199, v196, v196
	v_mul_f32_e32 v199, v199, v196
	v_fmamk_f32 v199, v199, 0x3d372713, v196
	v_mul_f32_e32 v199, 0xc0135761, v199
	v_exp_f32_e32 v199, v199
	s_nop 0
	v_add_f32_e32 v199, 1.0, v199
	v_rcp_f32_e32 v199, v199
	s_nop 0
	v_mul_f32_e32 v199, v199, v196
	v_mul_f32_e32 v198, v199, v41
	ds_write_b32 v194, v197
	ds_write_b32 v194, v198 offset:256
	s_add_u32 s14, s14, 1
	s_add_u32 s45, s45, s44
	s_branch .Lap0_s1_tok
.Lap0_s1_done:
	s_mov_b32 s14, 0
	s_mov_b32 s45, s13
.Lap0_s2_tok:
	s_cmp_ge_u32 s45, 0x8200
	s_cbranch_scc1 .Lap0_done
	s_lshl_b32 s15, s45, 9
	s_add_u32 s22, s4, 0x1404c000
	s_addc_u32 s23, s5, 0
	s_add_u32 s22, s22, s15
	s_addc_u32 s23, s23, 0
	global_load_dword v36, v226, s[22:23]
	global_load_dword v37, v226, s[22:23] offset:256
	s_lshl_b32 s15, s14, 9
	v_add_u32_e32 v194, s15, v228
	s_waitcnt lgkmcnt(0)
	ds_read_b32 v42, v194
	ds_read_b32 v43, v194 offset:256
	v_mov_b32_e32 v160, 0
	v_mov_b32_e32 v161, 0
	v_mov_b32_e32 v162, 0
	v_mov_b32_e32 v163, 0
	v_mov_b32_e32 v164, 0
	v_mov_b32_e32 v165, 0
	v_mov_b32_e32 v166, 0
	v_mov_b32_e32 v167, 0
	v_mov_b32_e32 v168, 0
	v_mov_b32_e32 v169, 0
	v_mov_b32_e32 v170, 0
	v_mov_b32_e32 v171, 0
	v_mov_b32_e32 v172, 0
	v_mov_b32_e32 v173, 0
	v_mov_b32_e32 v174, 0
	v_mov_b32_e32 v175, 0
	v_mov_b32_e32 v176, 0
	v_mov_b32_e32 v177, 0
	v_mov_b32_e32 v178, 0
	v_mov_b32_e32 v179, 0
	v_mov_b32_e32 v180, 0
	v_mov_b32_e32 v181, 0
	v_mov_b32_e32 v182, 0
	v_mov_b32_e32 v183, 0
	v_mov_b32_e32 v184, 0
	v_mov_b32_e32 v185, 0
	v_mov_b32_e32 v186, 0
	v_mov_b32_e32 v187, 0
	v_mov_b32_e32 v188, 0
	v_mov_b32_e32 v189, 0
	v_mov_b32_e32 v190, 0
	v_mov_b32_e32 v191, 0
	s_waitcnt vmcnt(0) lgkmcnt(0)
	s_mov_b32 s28, 0
	s_mov_b32 s37, 0
	v_readlane_b32 s29, v36, s28
	s_add_u32 s28, s28, 1
	s_mul_hi_u32 s27, s29, 0x640
	s_mul_i32 s26, s29, 0x640
	s_add_u32 s26, s18, s26
	s_addc_u32 s27, s19, s27
	global_load_dwordx4 v[48:51], v2, s[26:27]
	global_load_dwordx2 v[52:53], v2, s[26:27] offset:16
	global_load_ubyte v54, v3, s[26:27]
	v_readlane_b32 s29, v36, s28
	s_add_u32 s28, s28, 1
	s_mul_hi_u32 s27, s29, 0x640
	s_mul_i32 s26, s29, 0x640
	s_add_u32 s26, s18, s26
	s_addc_u32 s27, s19, s27
	global_load_dwordx4 v[56:59], v2, s[26:27]
	global_load_dwordx2 v[60:61], v2, s[26:27] offset:16
	global_load_ubyte v62, v3, s[26:27]
	v_readlane_b32 s29, v36, s28
	s_add_u32 s28, s28, 1
	s_mul_hi_u32 s27, s29, 0x640
	s_mul_i32 s26, s29, 0x640
	s_add_u32 s26, s18, s26
	s_addc_u32 s27, s19, s27
	global_load_dwordx4 v[64:67], v2, s[26:27]
	global_load_dwordx2 v[68:69], v2, s[26:27] offset:16
	global_load_ubyte v70, v3, s[26:27]
	v_readlane_b32 s29, v36, s28
	s_add_u32 s28, s28, 1
	s_mul_hi_u32 s27, s29, 0x640
	s_mul_i32 s26, s29, 0x640
	s_add_u32 s26, s18, s26
	s_addc_u32 s27, s19, s27
	global_load_dwordx4 v[72:75], v2, s[26:27]
	global_load_dwordx2 v[76:77], v2, s[26:27] offset:16
	global_load_ubyte v78, v3, s[26:27]
	v_readlane_b32 s29, v36, s28
	s_add_u32 s28, s28, 1
	s_mul_hi_u32 s27, s29, 0x640
	s_mul_i32 s26, s29, 0x640
	s_add_u32 s26, s18, s26
	s_addc_u32 s27, s19, s27
	global_load_dwordx4 v[80:83], v2, s[26:27]
	global_load_dwordx2 v[84:85], v2, s[26:27] offset:16
	global_load_ubyte v86, v3, s[26:27]
	v_readlane_b32 s29, v36, s28
	s_add_u32 s28, s28, 1
	s_mul_hi_u32 s27, s29, 0x640
	s_mul_i32 s26, s29, 0x640
	s_add_u32 s26, s18, s26
	s_addc_u32 s27, s19, s27
	global_load_dwordx4 v[88:91], v2, s[26:27]
	global_load_dwordx2 v[92:93], v2, s[26:27] offset:16
	global_load_ubyte v94, v3, s[26:27]
	v_readlane_b32 s29, v36, s28
	s_add_u32 s28, s28, 1
	s_mul_hi_u32 s27, s29, 0x640
	s_mul_i32 s26, s29, 0x640
	s_add_u32 s26, s18, s26
	s_addc_u32 s27, s19, s27
	global_load_dwordx4 v[96:99], v2, s[26:27]
	global_load_dwordx2 v[100:101], v2, s[26:27] offset:16
	global_load_ubyte v102, v3, s[26:27]
	v_readlane_b32 s29, v36, s28
	s_add_u32 s28, s28, 1
	s_mul_hi_u32 s27, s29, 0x640
	s_mul_i32 s26, s29, 0x640
	s_add_u32 s26, s18, s26
	s_addc_u32 s27, s19, s27
	global_load_dwordx4 v[104:107], v2, s[26:27]
	global_load_dwordx2 v[108:109], v2, s[26:27] offset:16
	global_load_ubyte v110, v3, s[26:27]
	s_mov_b32 s30, 7
; #define PB_FENCE asm volatile("" ::: "memory")
; __device__ __forceinline__ void ph_peer_apply(const Params& P, int layer, float* xlat, float* xctx_in, float* xctx_out, int nrows, bool write_next, char* smem, float* xlat_out = nullptr) {
;     ...
;     PB_LOAD(bufA, tv, 0);
;     for (int gq = 0; gq < NG; gq += 2) {
;       PB_LOAD(bufB, tv, gq + 1); PB_FENCE;
;       PB_ACC(bufA, gq);
;       if (gq + 2 < NG) PB_LOAD(bufA, tv, gq + 2);
;       PB_FENCE;
;       PB_ACC(bufB, gq + 1);
;     }
.Lap0_s2_loop3:
	v_readlane_b32 s36, v42, s37
	s_add_u32 s37, s37, 1
	s_waitcnt vmcnt(21)
	v_lshlrev_b32_e32 v192, 23, v54
	v_cvt_scalef32_pk32_f32_fp6 v[112:143], v[48:53], v192
	v_fmac_f32_e32 v160, s36, v112
	v_fmac_f32_e32 v161, s36, v113
	v_fmac_f32_e32 v162, s36, v114
	v_fmac_f32_e32 v163, s36, v115
	v_fmac_f32_e32 v164, s36, v116
	v_fmac_f32_e32 v165, s36, v117
	v_fmac_f32_e32 v166, s36, v118
	v_fmac_f32_e32 v167, s36, v119
	v_fmac_f32_e32 v168, s36, v120
	v_fmac_f32_e32 v169, s36, v121
	v_fmac_f32_e32 v170, s36, v122
	v_fmac_f32_e32 v171, s36, v123
	v_fmac_f32_e32 v172, s36, v124
	v_fmac_f32_e32 v173, s36, v125
	v_fmac_f32_e32 v174, s36, v126
	v_fmac_f32_e32 v175, s36, v127
	v_fmac_f32_e32 v176, s36, v128
	v_fmac_f32_e32 v177, s36, v129
	v_fmac_f32_e32 v178, s36, v130
	v_fmac_f32_e32 v179, s36, v131
	v_fmac_f32_e32 v180, s36, v132
	v_fmac_f32_e32 v181, s36, v133
	v_fmac_f32_e32 v182, s36, v134
	v_fmac_f32_e32 v183, s36, v135
	v_fmac_f32_e32 v184, s36, v136
	v_fmac_f32_e32 v185, s36, v137
	v_fmac_f32_e32 v186, s36, v138
	v_fmac_f32_e32 v187, s36, v139
	v_fmac_f32_e32 v188, s36, v140
	v_fmac_f32_e32 v189, s36, v141
	v_fmac_f32_e32 v190, s36, v142
	v_fmac_f32_e32 v191, s36, v143
	v_readlane_b32 s29, v36, s28
	s_add_u32 s28, s28, 1
	s_mul_hi_u32 s27, s29, 0x640
	s_mul_i32 s26, s29, 0x640
	s_add_u32 s26, s18, s26
	s_addc_u32 s27, s19, s27
	global_load_dwordx4 v[48:51], v2, s[26:27]
	global_load_dwordx2 v[52:53], v2, s[26:27] offset:16
	global_load_ubyte v54, v3, s[26:27]
	v_readlane_b32 s36, v42, s37
	s_add_u32 s37, s37, 1
	s_waitcnt vmcnt(21)
	v_lshlrev_b32_e32 v192, 23, v62
	v_cvt_scalef32_pk32_f32_fp6 v[112:143], v[56:61], v192
	v_fmac_f32_e32 v160, s36, v112
	v_fmac_f32_e32 v161, s36, v113
	v_fmac_f32_e32 v162, s36, v114
	v_fmac_f32_e32 v163, s36, v115
	v_fmac_f32_e32 v164, s36, v116
	v_fmac_f32_e32 v165, s36, v117
	v_fmac_f32_e32 v166, s36, v118
	v_fmac_f32_e32 v167, s36, v119
	v_fmac_f32_e32 v168, s36, v120
	v_fmac_f32_e32 v169, s36, v121
	v_fmac_f32_e32 v170, s36, v122
	v_fmac_f32_e32 v171, s36, v123
	v_fmac_f32_e32 v172, s36, v124
	v_fmac_f32_e32 v173, s36, v125
	v_fmac_f32_e32 v174, s36, v126
	v_fmac_f32_e32 v175, s36, v127
	v_fmac_f32_e32 v176, s36, v128
	v_fmac_f32_e32 v177, s36, v129
	v_fmac_f32_e32 v178, s36, v130
	v_fmac_f32_e32 v179, s36, v131
	v_fmac_f32_e32 v180, s36, v132
	v_fmac_f32_e32 v181, s36, v133
	v_fmac_f32_e32 v182, s36, v134
	v_fmac_f32_e32 v183, s36, v135
	v_fmac_f32_e32 v184, s36, v136
	v_fmac_f32_e32 v185, s36, v137
	v_fmac_f32_e32 v186, s36, v138
	v_fmac_f32_e32 v187, s36, v139
	v_fmac_f32_e32 v188, s36, v140
	v_fmac_f32_e32 v189, s36, v141
	v_fmac_f32_e32 v190, s36, v142
	v_fmac_f32_e32 v191, s36, v143
	v_readlane_b32 s29, v36, s28
	s_add_u32 s28, s28, 1
	s_mul_hi_u32 s27, s29, 0x640
	s_mul_i32 s26, s29, 0x640
	s_add_u32 s26, s18, s26
	s_addc_u32 s27, s19, s27
	global_load_dwordx4 v[56:59], v2, s[26:27]
	global_load_dwordx2 v[60:61], v2, s[26:27] offset:16
	global_load_ubyte v62, v3, s[26:27]
	v_readlane_b32 s36, v42, s37
	s_add_u32 s37, s37, 1
	s_waitcnt vmcnt(21)
	v_lshlrev_b32_e32 v192, 23, v70
	v_cvt_scalef32_pk32_f32_fp6 v[112:143], v[64:69], v192
	v_fmac_f32_e32 v160, s36, v112
	v_fmac_f32_e32 v161, s36, v113
	v_fmac_f32_e32 v162, s36, v114
	v_fmac_f32_e32 v163, s36, v115
	v_fmac_f32_e32 v164, s36, v116
	v_fmac_f32_e32 v165, s36, v117
	v_fmac_f32_e32 v166, s36, v118
	v_fmac_f32_e32 v167, s36, v119
	v_fmac_f32_e32 v168, s36, v120
	v_fmac_f32_e32 v169, s36, v121
	v_fmac_f32_e32 v170, s36, v122
	v_fmac_f32_e32 v171, s36, v123
	v_fmac_f32_e32 v172, s36, v124
	v_fmac_f32_e32 v173, s36, v125
	v_fmac_f32_e32 v174, s36, v126
	v_fmac_f32_e32 v175, s36, v127
	v_fmac_f32_e32 v176, s36, v128
	v_fmac_f32_e32 v177, s36, v129
	v_fmac_f32_e32 v178, s36, v130
	v_fmac_f32_e32 v179, s36, v131
	v_fmac_f32_e32 v180, s36, v132
	v_fmac_f32_e32 v181, s36, v133
	v_fmac_f32_e32 v182, s36, v134
	v_fmac_f32_e32 v183, s36, v135
	v_fmac_f32_e32 v184, s36, v136
	v_fmac_f32_e32 v185, s36, v137
	v_fmac_f32_e32 v186, s36, v138
	v_fmac_f32_e32 v187, s36, v139
	v_fmac_f32_e32 v188, s36, v140
	v_fmac_f32_e32 v189, s36, v141
	v_fmac_f32_e32 v190, s36, v142
	v_fmac_f32_e32 v191, s36, v143
	v_readlane_b32 s29, v36, s28
	s_add_u32 s28, s28, 1
	s_mul_hi_u32 s27, s29, 0x640
	s_mul_i32 s26, s29, 0x640
	s_add_u32 s26, s18, s26
	s_addc_u32 s27, s19, s27
	global_load_dwordx4 v[64:67], v2, s[26:27]
	global_load_dwordx2 v[68:69], v2, s[26:27] offset:16
	global_load_ubyte v70, v3, s[26:27]
	v_readlane_b32 s36, v42, s37
	s_add_u32 s37, s37, 1
	s_waitcnt vmcnt(21)
	v_lshlrev_b32_e32 v192, 23, v78
	v_cvt_scalef32_pk32_f32_fp6 v[112:143], v[72:77], v192
	v_fmac_f32_e32 v160, s36, v112
	v_fmac_f32_e32 v161, s36, v113
	v_fmac_f32_e32 v162, s36, v114
	v_fmac_f32_e32 v163, s36, v115
	v_fmac_f32_e32 v164, s36, v116
	v_fmac_f32_e32 v165, s36, v117
	v_fmac_f32_e32 v166, s36, v118
	v_fmac_f32_e32 v167, s36, v119
	v_fmac_f32_e32 v168, s36, v120
	v_fmac_f32_e32 v169, s36, v121
	v_fmac_f32_e32 v170, s36, v122
	v_fmac_f32_e32 v171, s36, v123
	v_fmac_f32_e32 v172, s36, v124
	v_fmac_f32_e32 v173, s36, v125
	v_fmac_f32_e32 v174, s36, v126
	v_fmac_f32_e32 v175, s36, v127
	v_fmac_f32_e32 v176, s36, v128
	v_fmac_f32_e32 v177, s36, v129
	v_fmac_f32_e32 v178, s36, v130
	v_fmac_f32_e32 v179, s36, v131
	v_fmac_f32_e32 v180, s36, v132
	v_fmac_f32_e32 v181, s36, v133
	v_fmac_f32_e32 v182, s36, v134
	v_fmac_f32_e32 v183, s36, v135
	v_fmac_f32_e32 v184, s36, v136
	v_fmac_f32_e32 v185, s36, v137
	v_fmac_f32_e32 v186, s36, v138
	v_fmac_f32_e32 v187, s36, v139
	v_fmac_f32_e32 v188, s36, v140
	v_fmac_f32_e32 v189, s36, v141
	v_fmac_f32_e32 v190, s36, v142
	v_fmac_f32_e32 v191, s36, v143
	v_readlane_b32 s29, v36, s28
	s_add_u32 s28, s28, 1
	s_mul_hi_u32 s27, s29, 0x640
	s_mul_i32 s26, s29, 0x640
	s_add_u32 s26, s18, s26
	s_addc_u32 s27, s19, s27
	global_load_dwordx4 v[72:75], v2, s[26:27]
	global_load_dwordx2 v[76:77], v2, s[26:27] offset:16
	global_load_ubyte v78, v3, s[26:27]
	v_readlane_b32 s36, v42, s37
	s_add_u32 s37, s37, 1
	s_waitcnt vmcnt(21)
; #define PB_FENCE asm volatile("" ::: "memory")
; __device__ __forceinline__ void ph_peer_apply(const Params& P, int layer, float* xlat, float* xctx_in, float* xctx_out, int nrows, bool write_next, char* smem, float* xlat_out = nullptr) {
;     ...
;     PB_LOAD(bufA, tv, 0);
;     for (int gq = 0; gq < NG; gq += 2) {
;       PB_LOAD(bufB, tv, gq + 1); PB_FENCE;
;       PB_ACC(bufA, gq);
;       if (gq + 2 < NG) PB_LOAD(bufA, tv, gq + 2);
;       PB_FENCE;
;       PB_ACC(bufB, gq + 1);
;     }
	v_lshlrev_b32_e32 v192, 23, v86
	v_cvt_scalef32_pk32_f32_fp6 v[112:143], v[80:85], v192
	v_fmac_f32_e32 v160, s36, v112
	v_fmac_f32_e32 v161, s36, v113
	v_fmac_f32_e32 v162, s36, v114
	v_fmac_f32_e32 v163, s36, v115
	v_fmac_f32_e32 v164, s36, v116
	v_fmac_f32_e32 v165, s36, v117
	v_fmac_f32_e32 v166, s36, v118
	v_fmac_f32_e32 v167, s36, v119
	v_fmac_f32_e32 v168, s36, v120
	v_fmac_f32_e32 v169, s36, v121
	v_fmac_f32_e32 v170, s36, v122
	v_fmac_f32_e32 v171, s36, v123
	v_fmac_f32_e32 v172, s36, v124
	v_fmac_f32_e32 v173, s36, v125
	v_fmac_f32_e32 v174, s36, v126
	v_fmac_f32_e32 v175, s36, v127
	v_fmac_f32_e32 v176, s36, v128
	v_fmac_f32_e32 v177, s36, v129
	v_fmac_f32_e32 v178, s36, v130
	v_fmac_f32_e32 v179, s36, v131
	v_fmac_f32_e32 v180, s36, v132
	v_fmac_f32_e32 v181, s36, v133
	v_fmac_f32_e32 v182, s36, v134
	v_fmac_f32_e32 v183, s36, v135
	v_fmac_f32_e32 v184, s36, v136
	v_fmac_f32_e32 v185, s36, v137
	v_fmac_f32_e32 v186, s36, v138
	v_fmac_f32_e32 v187, s36, v139
	v_fmac_f32_e32 v188, s36, v140
	v_fmac_f32_e32 v189, s36, v141
	v_fmac_f32_e32 v190, s36, v142
	v_fmac_f32_e32 v191, s36, v143
	v_readlane_b32 s29, v36, s28
	s_add_u32 s28, s28, 1
	s_mul_hi_u32 s27, s29, 0x640
	s_mul_i32 s26, s29, 0x640
	s_add_u32 s26, s18, s26
	s_addc_u32 s27, s19, s27
	global_load_dwordx4 v[80:83], v2, s[26:27]
	global_load_dwordx2 v[84:85], v2, s[26:27] offset:16
	global_load_ubyte v86, v3, s[26:27]
	v_readlane_b32 s36, v42, s37
	s_add_u32 s37, s37, 1
	s_waitcnt vmcnt(21)
	v_lshlrev_b32_e32 v192, 23, v94
	v_cvt_scalef32_pk32_f32_fp6 v[112:143], v[88:93], v192
	v_fmac_f32_e32 v160, s36, v112
	v_fmac_f32_e32 v161, s36, v113
	v_fmac_f32_e32 v162, s36, v114
	v_fmac_f32_e32 v163, s36, v115
	v_fmac_f32_e32 v164, s36, v116
	v_fmac_f32_e32 v165, s36, v117
	v_fmac_f32_e32 v166, s36, v118
	v_fmac_f32_e32 v167, s36, v119
	v_fmac_f32_e32 v168, s36, v120
	v_fmac_f32_e32 v169, s36, v121
	v_fmac_f32_e32 v170, s36, v122
	v_fmac_f32_e32 v171, s36, v123
	v_fmac_f32_e32 v172, s36, v124
	v_fmac_f32_e32 v173, s36, v125
	v_fmac_f32_e32 v174, s36, v126
	v_fmac_f32_e32 v175, s36, v127
	v_fmac_f32_e32 v176, s36, v128
	v_fmac_f32_e32 v177, s36, v129
	v_fmac_f32_e32 v178, s36, v130
	v_fmac_f32_e32 v179, s36, v131
	v_fmac_f32_e32 v180, s36, v132
	v_fmac_f32_e32 v181, s36, v133
	v_fmac_f32_e32 v182, s36, v134
	v_fmac_f32_e32 v183, s36, v135
	v_fmac_f32_e32 v184, s36, v136
	v_fmac_f32_e32 v185, s36, v137
	v_fmac_f32_e32 v186, s36, v138
	v_fmac_f32_e32 v187, s36, v139
	v_fmac_f32_e32 v188, s36, v140
	v_fmac_f32_e32 v189, s36, v141
	v_fmac_f32_e32 v190, s36, v142
	v_fmac_f32_e32 v191, s36, v143
	v_readlane_b32 s29, v36, s28
	s_add_u32 s28, s28, 1
	s_mul_hi_u32 s27, s29, 0x640
	s_mul_i32 s26, s29, 0x640
	s_add_u32 s26, s18, s26
	s_addc_u32 s27, s19, s27
	global_load_dwordx4 v[88:91], v2, s[26:27]
	global_load_dwordx2 v[92:93], v2, s[26:27] offset:16
	global_load_ubyte v94, v3, s[26:27]
	v_readlane_b32 s36, v42, s37
	s_add_u32 s37, s37, 1
	s_waitcnt vmcnt(21)
	v_lshlrev_b32_e32 v192, 23, v102
	v_cvt_scalef32_pk32_f32_fp6 v[112:143], v[96:101], v192
	v_fmac_f32_e32 v160, s36, v112
	v_fmac_f32_e32 v161, s36, v113
	v_fmac_f32_e32 v162, s36, v114
	v_fmac_f32_e32 v163, s36, v115
	v_fmac_f32_e32 v164, s36, v116
	v_fmac_f32_e32 v165, s36, v117
	v_fmac_f32_e32 v166, s36, v118
	v_fmac_f32_e32 v167, s36, v119
	v_fmac_f32_e32 v168, s36, v120
	v_fmac_f32_e32 v169, s36, v121
	v_fmac_f32_e32 v170, s36, v122
	v_fmac_f32_e32 v171, s36, v123
	v_fmac_f32_e32 v172, s36, v124
	v_fmac_f32_e32 v173, s36, v125
	v_fmac_f32_e32 v174, s36, v126
	v_fmac_f32_e32 v175, s36, v127
	v_fmac_f32_e32 v176, s36, v128
	v_fmac_f32_e32 v177, s36, v129
	v_fmac_f32_e32 v178, s36, v130
	v_fmac_f32_e32 v179, s36, v131
	v_fmac_f32_e32 v180, s36, v132
	v_fmac_f32_e32 v181, s36, v133
	v_fmac_f32_e32 v182, s36, v134
	v_fmac_f32_e32 v183, s36, v135
	v_fmac_f32_e32 v184, s36, v136
	v_fmac_f32_e32 v185, s36, v137
	v_fmac_f32_e32 v186, s36, v138
	v_fmac_f32_e32 v187, s36, v139
	v_fmac_f32_e32 v188, s36, v140
	v_fmac_f32_e32 v189, s36, v141
	v_fmac_f32_e32 v190, s36, v142
	v_fmac_f32_e32 v191, s36, v143
	v_readlane_b32 s29, v36, s28
	s_add_u32 s28, s28, 1
	s_mul_hi_u32 s27, s29, 0x640
	s_mul_i32 s26, s29, 0x640
	s_add_u32 s26, s18, s26
	s_addc_u32 s27, s19, s27
	global_load_dwordx4 v[96:99], v2, s[26:27]
	global_load_dwordx2 v[100:101], v2, s[26:27] offset:16
	global_load_ubyte v102, v3, s[26:27]
	v_readlane_b32 s36, v42, s37
	s_add_u32 s37, s37, 1
	s_waitcnt vmcnt(21)
	v_lshlrev_b32_e32 v192, 23, v110
	v_cvt_scalef32_pk32_f32_fp6 v[112:143], v[104:109], v192
	v_fmac_f32_e32 v160, s36, v112
	v_fmac_f32_e32 v161, s36, v113
	v_fmac_f32_e32 v162, s36, v114
	v_fmac_f32_e32 v163, s36, v115
	v_fmac_f32_e32 v164, s36, v116
	v_fmac_f32_e32 v165, s36, v117
	v_fmac_f32_e32 v166, s36, v118
	v_fmac_f32_e32 v167, s36, v119
	v_fmac_f32_e32 v168, s36, v120
	v_fmac_f32_e32 v169, s36, v121
	v_fmac_f32_e32 v170, s36, v122
	v_fmac_f32_e32 v171, s36, v123
	v_fmac_f32_e32 v172, s36, v124
	v_fmac_f32_e32 v173, s36, v125
	v_fmac_f32_e32 v174, s36, v126
	v_fmac_f32_e32 v175, s36, v127
	v_fmac_f32_e32 v176, s36, v128
	v_fmac_f32_e32 v177, s36, v129
	v_fmac_f32_e32 v178, s36, v130
	v_fmac_f32_e32 v179, s36, v131
	v_fmac_f32_e32 v180, s36, v132
	v_fmac_f32_e32 v181, s36, v133
	v_fmac_f32_e32 v182, s36, v134
	v_fmac_f32_e32 v183, s36, v135
	v_fmac_f32_e32 v184, s36, v136
	v_fmac_f32_e32 v185, s36, v137
	v_fmac_f32_e32 v186, s36, v138
	v_fmac_f32_e32 v187, s36, v139
	v_fmac_f32_e32 v188, s36, v140
	v_fmac_f32_e32 v189, s36, v141
	v_fmac_f32_e32 v190, s36, v142
	v_fmac_f32_e32 v191, s36, v143
	v_readlane_b32 s29, v36, s28
	s_add_u32 s28, s28, 1
	s_mul_hi_u32 s27, s29, 0x640
	s_mul_i32 s26, s29, 0x640
	s_add_u32 s26, s18, s26
	s_addc_u32 s27, s19, s27
	global_load_dwordx4 v[104:107], v2, s[26:27]
	global_load_dwordx2 v[108:109], v2, s[26:27] offset:16
	global_load_ubyte v110, v3, s[26:27]
	s_sub_u32 s30, s30, 1
	s_cmp_lg_u32 s30, 0
	s_cbranch_scc1 .Lap0_s2_loop3
; #define PB_FENCE asm volatile("" ::: "memory")
; __device__ __forceinline__ void ph_peer_apply(const Params& P, int layer, float* xlat, float* xctx_in, float* xctx_out, int nrows, bool write_next, char* smem, float* xlat_out = nullptr) {
;     ...
;     PB_LOAD(bufA, tv, 0);
;     for (int gq = 0; gq < NG; gq += 2) {
;       PB_LOAD(bufB, tv, gq + 1); PB_FENCE;
;       PB_ACC(bufA, gq);
;       if (gq + 2 < NG) PB_LOAD(bufA, tv, gq + 2);
;       PB_FENCE;
;       PB_ACC(bufB, gq + 1);
;     }
	v_readlane_b32 s36, v42, s37
	s_add_u32 s37, s37, 1
	s_waitcnt vmcnt(21)
	v_lshlrev_b32_e32 v192, 23, v54
	v_cvt_scalef32_pk32_f32_fp6 v[112:143], v[48:53], v192
	v_fmac_f32_e32 v160, s36, v112
	v_fmac_f32_e32 v161, s36, v113
	v_fmac_f32_e32 v162, s36, v114
	v_fmac_f32_e32 v163, s36, v115
	v_fmac_f32_e32 v164, s36, v116
	v_fmac_f32_e32 v165, s36, v117
	v_fmac_f32_e32 v166, s36, v118
	v_fmac_f32_e32 v167, s36, v119
	v_fmac_f32_e32 v168, s36, v120
	v_fmac_f32_e32 v169, s36, v121
	v_fmac_f32_e32 v170, s36, v122
	v_fmac_f32_e32 v171, s36, v123
	v_fmac_f32_e32 v172, s36, v124
	v_fmac_f32_e32 v173, s36, v125
	v_fmac_f32_e32 v174, s36, v126
	v_fmac_f32_e32 v175, s36, v127
	v_fmac_f32_e32 v176, s36, v128
	v_fmac_f32_e32 v177, s36, v129
	v_fmac_f32_e32 v178, s36, v130
	v_fmac_f32_e32 v179, s36, v131
	v_fmac_f32_e32 v180, s36, v132
	v_fmac_f32_e32 v181, s36, v133
	v_fmac_f32_e32 v182, s36, v134
	v_fmac_f32_e32 v183, s36, v135
	v_fmac_f32_e32 v184, s36, v136
	v_fmac_f32_e32 v185, s36, v137
	v_fmac_f32_e32 v186, s36, v138
	v_fmac_f32_e32 v187, s36, v139
	v_fmac_f32_e32 v188, s36, v140
	v_fmac_f32_e32 v189, s36, v141
	v_fmac_f32_e32 v190, s36, v142
	v_fmac_f32_e32 v191, s36, v143
	v_readlane_b32 s36, v42, s37
	s_add_u32 s37, s37, 1
	s_waitcnt vmcnt(18)
	v_lshlrev_b32_e32 v192, 23, v62
	v_cvt_scalef32_pk32_f32_fp6 v[112:143], v[56:61], v192
	v_fmac_f32_e32 v160, s36, v112
	v_fmac_f32_e32 v161, s36, v113
	v_fmac_f32_e32 v162, s36, v114
	v_fmac_f32_e32 v163, s36, v115
	v_fmac_f32_e32 v164, s36, v116
	v_fmac_f32_e32 v165, s36, v117
	v_fmac_f32_e32 v166, s36, v118
	v_fmac_f32_e32 v167, s36, v119
	v_fmac_f32_e32 v168, s36, v120
	v_fmac_f32_e32 v169, s36, v121
	v_fmac_f32_e32 v170, s36, v122
	v_fmac_f32_e32 v171, s36, v123
	v_fmac_f32_e32 v172, s36, v124
	v_fmac_f32_e32 v173, s36, v125
	v_fmac_f32_e32 v174, s36, v126
	v_fmac_f32_e32 v175, s36, v127
	v_fmac_f32_e32 v176, s36, v128
	v_fmac_f32_e32 v177, s36, v129
	v_fmac_f32_e32 v178, s36, v130
	v_fmac_f32_e32 v179, s36, v131
	v_fmac_f32_e32 v180, s36, v132
	v_fmac_f32_e32 v181, s36, v133
	v_fmac_f32_e32 v182, s36, v134
	v_fmac_f32_e32 v183, s36, v135
	v_fmac_f32_e32 v184, s36, v136
	v_fmac_f32_e32 v185, s36, v137
	v_fmac_f32_e32 v186, s36, v138
	v_fmac_f32_e32 v187, s36, v139
	v_fmac_f32_e32 v188, s36, v140
	v_fmac_f32_e32 v189, s36, v141
	v_fmac_f32_e32 v190, s36, v142
	v_fmac_f32_e32 v191, s36, v143
	v_readlane_b32 s36, v42, s37
	s_add_u32 s37, s37, 1
	s_waitcnt vmcnt(15)
	v_lshlrev_b32_e32 v192, 23, v70
	v_cvt_scalef32_pk32_f32_fp6 v[112:143], v[64:69], v192
	v_fmac_f32_e32 v160, s36, v112
	v_fmac_f32_e32 v161, s36, v113
	v_fmac_f32_e32 v162, s36, v114
	v_fmac_f32_e32 v163, s36, v115
	v_fmac_f32_e32 v164, s36, v116
	v_fmac_f32_e32 v165, s36, v117
	v_fmac_f32_e32 v166, s36, v118
	v_fmac_f32_e32 v167, s36, v119
	v_fmac_f32_e32 v168, s36, v120
	v_fmac_f32_e32 v169, s36, v121
	v_fmac_f32_e32 v170, s36, v122
	v_fmac_f32_e32 v171, s36, v123
	v_fmac_f32_e32 v172, s36, v124
	v_fmac_f32_e32 v173, s36, v125
	v_fmac_f32_e32 v174, s36, v126
	v_fmac_f32_e32 v175, s36, v127
	v_fmac_f32_e32 v176, s36, v128
	v_fmac_f32_e32 v177, s36, v129
	v_fmac_f32_e32 v178, s36, v130
	v_fmac_f32_e32 v179, s36, v131
	v_fmac_f32_e32 v180, s36, v132
	v_fmac_f32_e32 v181, s36, v133
	v_fmac_f32_e32 v182, s36, v134
	v_fmac_f32_e32 v183, s36, v135
	v_fmac_f32_e32 v184, s36, v136
	v_fmac_f32_e32 v185, s36, v137
	v_fmac_f32_e32 v186, s36, v138
	v_fmac_f32_e32 v187, s36, v139
	v_fmac_f32_e32 v188, s36, v140
	v_fmac_f32_e32 v189, s36, v141
	v_fmac_f32_e32 v190, s36, v142
	v_fmac_f32_e32 v191, s36, v143
	v_readlane_b32 s36, v42, s37
	s_add_u32 s37, s37, 1
	s_waitcnt vmcnt(12)
	v_lshlrev_b32_e32 v192, 23, v78
	v_cvt_scalef32_pk32_f32_fp6 v[112:143], v[72:77], v192
	v_fmac_f32_e32 v160, s36, v112
	v_fmac_f32_e32 v161, s36, v113
	v_fmac_f32_e32 v162, s36, v114
	v_fmac_f32_e32 v163, s36, v115
	v_fmac_f32_e32 v164, s36, v116
	v_fmac_f32_e32 v165, s36, v117
	v_fmac_f32_e32 v166, s36, v118
	v_fmac_f32_e32 v167, s36, v119
	v_fmac_f32_e32 v168, s36, v120
	v_fmac_f32_e32 v169, s36, v121
	v_fmac_f32_e32 v170, s36, v122
	v_fmac_f32_e32 v171, s36, v123
	v_fmac_f32_e32 v172, s36, v124
	v_fmac_f32_e32 v173, s36, v125
	v_fmac_f32_e32 v174, s36, v126
	v_fmac_f32_e32 v175, s36, v127
	v_fmac_f32_e32 v176, s36, v128
	v_fmac_f32_e32 v177, s36, v129
	v_fmac_f32_e32 v178, s36, v130
	v_fmac_f32_e32 v179, s36, v131
	v_fmac_f32_e32 v180, s36, v132
	v_fmac_f32_e32 v181, s36, v133
	v_fmac_f32_e32 v182, s36, v134
	v_fmac_f32_e32 v183, s36, v135
	v_fmac_f32_e32 v184, s36, v136
	v_fmac_f32_e32 v185, s36, v137
	v_fmac_f32_e32 v186, s36, v138
	v_fmac_f32_e32 v187, s36, v139
	v_fmac_f32_e32 v188, s36, v140
	v_fmac_f32_e32 v189, s36, v141
	v_fmac_f32_e32 v190, s36, v142
	v_fmac_f32_e32 v191, s36, v143
	v_readlane_b32 s36, v42, s37
	s_add_u32 s37, s37, 1
	s_waitcnt vmcnt(9)
	v_lshlrev_b32_e32 v192, 23, v86
	v_cvt_scalef32_pk32_f32_fp6 v[112:143], v[80:85], v192
	v_fmac_f32_e32 v160, s36, v112
	v_fmac_f32_e32 v161, s36, v113
	v_fmac_f32_e32 v162, s36, v114
	v_fmac_f32_e32 v163, s36, v115
	v_fmac_f32_e32 v164, s36, v116
	v_fmac_f32_e32 v165, s36, v117
	v_fmac_f32_e32 v166, s36, v118
	v_fmac_f32_e32 v167, s36, v119
	v_fmac_f32_e32 v168, s36, v120
	v_fmac_f32_e32 v169, s36, v121
	v_fmac_f32_e32 v170, s36, v122
	v_fmac_f32_e32 v171, s36, v123
	v_fmac_f32_e32 v172, s36, v124
	v_fmac_f32_e32 v173, s36, v125
	v_fmac_f32_e32 v174, s36, v126
	v_fmac_f32_e32 v175, s36, v127
	v_fmac_f32_e32 v176, s36, v128
	v_fmac_f32_e32 v177, s36, v129
	v_fmac_f32_e32 v178, s36, v130
	v_fmac_f32_e32 v179, s36, v131
	v_fmac_f32_e32 v180, s36, v132
	v_fmac_f32_e32 v181, s36, v133
	v_fmac_f32_e32 v182, s36, v134
	v_fmac_f32_e32 v183, s36, v135
	v_fmac_f32_e32 v184, s36, v136
	v_fmac_f32_e32 v185, s36, v137
	v_fmac_f32_e32 v186, s36, v138
	v_fmac_f32_e32 v187, s36, v139
	v_fmac_f32_e32 v188, s36, v140
	v_fmac_f32_e32 v189, s36, v141
	v_fmac_f32_e32 v190, s36, v142
	v_fmac_f32_e32 v191, s36, v143
	v_readlane_b32 s36, v42, s37
	s_add_u32 s37, s37, 1
	s_waitcnt vmcnt(6)
; #define PB_FENCE asm volatile("" ::: "memory")
; __device__ __forceinline__ void ph_peer_apply(const Params& P, int layer, float* xlat, float* xctx_in, float* xctx_out, int nrows, bool write_next, char* smem, float* xlat_out = nullptr) {
;     ...
;     PB_LOAD(bufA, tv, 0);
;     for (int gq = 0; gq < NG; gq += 2) {
;       PB_LOAD(bufB, tv, gq + 1); PB_FENCE;
;       PB_ACC(bufA, gq);
;       if (gq + 2 < NG) PB_LOAD(bufA, tv, gq + 2);
;       PB_FENCE;
;       PB_ACC(bufB, gq + 1);
;     }
	v_lshlrev_b32_e32 v192, 23, v94
	v_cvt_scalef32_pk32_f32_fp6 v[112:143], v[88:93], v192
	v_fmac_f32_e32 v160, s36, v112
	v_fmac_f32_e32 v161, s36, v113
	v_fmac_f32_e32 v162, s36, v114
	v_fmac_f32_e32 v163, s36, v115
	v_fmac_f32_e32 v164, s36, v116
	v_fmac_f32_e32 v165, s36, v117
	v_fmac_f32_e32 v166, s36, v118
	v_fmac_f32_e32 v167, s36, v119
	v_fmac_f32_e32 v168, s36, v120
	v_fmac_f32_e32 v169, s36, v121
	v_fmac_f32_e32 v170, s36, v122
	v_fmac_f32_e32 v171, s36, v123
	v_fmac_f32_e32 v172, s36, v124
	v_fmac_f32_e32 v173, s36, v125
	v_fmac_f32_e32 v174, s36, v126
	v_fmac_f32_e32 v175, s36, v127
	v_fmac_f32_e32 v176, s36, v128
	v_fmac_f32_e32 v177, s36, v129
	v_fmac_f32_e32 v178, s36, v130
	v_fmac_f32_e32 v179, s36, v131
	v_fmac_f32_e32 v180, s36, v132
	v_fmac_f32_e32 v181, s36, v133
	v_fmac_f32_e32 v182, s36, v134
	v_fmac_f32_e32 v183, s36, v135
	v_fmac_f32_e32 v184, s36, v136
	v_fmac_f32_e32 v185, s36, v137
	v_fmac_f32_e32 v186, s36, v138
	v_fmac_f32_e32 v187, s36, v139
	v_fmac_f32_e32 v188, s36, v140
	v_fmac_f32_e32 v189, s36, v141
	v_fmac_f32_e32 v190, s36, v142
	v_fmac_f32_e32 v191, s36, v143
	v_readlane_b32 s36, v42, s37
	s_add_u32 s37, s37, 1
	s_waitcnt vmcnt(3)
	v_lshlrev_b32_e32 v192, 23, v102
	v_cvt_scalef32_pk32_f32_fp6 v[112:143], v[96:101], v192
	v_fmac_f32_e32 v160, s36, v112
	v_fmac_f32_e32 v161, s36, v113
	v_fmac_f32_e32 v162, s36, v114
	v_fmac_f32_e32 v163, s36, v115
	v_fmac_f32_e32 v164, s36, v116
	v_fmac_f32_e32 v165, s36, v117
	v_fmac_f32_e32 v166, s36, v118
	v_fmac_f32_e32 v167, s36, v119
	v_fmac_f32_e32 v168, s36, v120
	v_fmac_f32_e32 v169, s36, v121
	v_fmac_f32_e32 v170, s36, v122
	v_fmac_f32_e32 v171, s36, v123
	v_fmac_f32_e32 v172, s36, v124
	v_fmac_f32_e32 v173, s36, v125
	v_fmac_f32_e32 v174, s36, v126
	v_fmac_f32_e32 v175, s36, v127
	v_fmac_f32_e32 v176, s36, v128
	v_fmac_f32_e32 v177, s36, v129
	v_fmac_f32_e32 v178, s36, v130
	v_fmac_f32_e32 v179, s36, v131
	v_fmac_f32_e32 v180, s36, v132
	v_fmac_f32_e32 v181, s36, v133
	v_fmac_f32_e32 v182, s36, v134
	v_fmac_f32_e32 v183, s36, v135
	v_fmac_f32_e32 v184, s36, v136
	v_fmac_f32_e32 v185, s36, v137
	v_fmac_f32_e32 v186, s36, v138
	v_fmac_f32_e32 v187, s36, v139
	v_fmac_f32_e32 v188, s36, v140
	v_fmac_f32_e32 v189, s36, v141
	v_fmac_f32_e32 v190, s36, v142
	v_fmac_f32_e32 v191, s36, v143
	v_readlane_b32 s36, v42, s37
	s_add_u32 s37, s37, 1
	s_waitcnt vmcnt(0)
	v_lshlrev_b32_e32 v192, 23, v110
	v_cvt_scalef32_pk32_f32_fp6 v[112:143], v[104:109], v192
	v_fmac_f32_e32 v160, s36, v112
	v_fmac_f32_e32 v161, s36, v113
	v_fmac_f32_e32 v162, s36, v114
	v_fmac_f32_e32 v163, s36, v115
	v_fmac_f32_e32 v164, s36, v116
	v_fmac_f32_e32 v165, s36, v117
	v_fmac_f32_e32 v166, s36, v118
	v_fmac_f32_e32 v167, s36, v119
	v_fmac_f32_e32 v168, s36, v120
	v_fmac_f32_e32 v169, s36, v121
	v_fmac_f32_e32 v170, s36, v122
	v_fmac_f32_e32 v171, s36, v123
	v_fmac_f32_e32 v172, s36, v124
	v_fmac_f32_e32 v173, s36, v125
	v_fmac_f32_e32 v174, s36, v126
	v_fmac_f32_e32 v175, s36, v127
	v_fmac_f32_e32 v176, s36, v128
	v_fmac_f32_e32 v177, s36, v129
	v_fmac_f32_e32 v178, s36, v130
	v_fmac_f32_e32 v179, s36, v131
	v_fmac_f32_e32 v180, s36, v132
	v_fmac_f32_e32 v181, s36, v133
	v_fmac_f32_e32 v182, s36, v134
	v_fmac_f32_e32 v183, s36, v135
	v_fmac_f32_e32 v184, s36, v136
	v_fmac_f32_e32 v185, s36, v137
	v_fmac_f32_e32 v186, s36, v138
	v_fmac_f32_e32 v187, s36, v139
	v_fmac_f32_e32 v188, s36, v140
	v_fmac_f32_e32 v189, s36, v141
	v_fmac_f32_e32 v190, s36, v142
	v_fmac_f32_e32 v191, s36, v143
	s_mov_b32 s28, 0
	s_mov_b32 s37, 0
	v_readlane_b32 s29, v37, s28
	s_add_u32 s28, s28, 1
	s_mul_hi_u32 s27, s29, 0x640
	s_mul_i32 s26, s29, 0x640
	s_add_u32 s26, s18, s26
	s_addc_u32 s27, s19, s27
	global_load_dwordx4 v[48:51], v2, s[26:27]
	global_load_dwordx2 v[52:53], v2, s[26:27] offset:16
	global_load_ubyte v54, v3, s[26:27]
	v_readlane_b32 s29, v37, s28
	s_add_u32 s28, s28, 1
	s_mul_hi_u32 s27, s29, 0x640
	s_mul_i32 s26, s29, 0x640
	s_add_u32 s26, s18, s26
	s_addc_u32 s27, s19, s27
	global_load_dwordx4 v[56:59], v2, s[26:27]
	global_load_dwordx2 v[60:61], v2, s[26:27] offset:16
	global_load_ubyte v62, v3, s[26:27]
	v_readlane_b32 s29, v37, s28
	s_add_u32 s28, s28, 1
	s_mul_hi_u32 s27, s29, 0x640
	s_mul_i32 s26, s29, 0x640
	s_add_u32 s26, s18, s26
	s_addc_u32 s27, s19, s27
	global_load_dwordx4 v[64:67], v2, s[26:27]
	global_load_dwordx2 v[68:69], v2, s[26:27] offset:16
	global_load_ubyte v70, v3, s[26:27]
	v_readlane_b32 s29, v37, s28
	s_add_u32 s28, s28, 1
	s_mul_hi_u32 s27, s29, 0x640
	s_mul_i32 s26, s29, 0x640
	s_add_u32 s26, s18, s26
	s_addc_u32 s27, s19, s27
	global_load_dwordx4 v[72:75], v2, s[26:27]
	global_load_dwordx2 v[76:77], v2, s[26:27] offset:16
	global_load_ubyte v78, v3, s[26:27]
	v_readlane_b32 s29, v37, s28
	s_add_u32 s28, s28, 1
	s_mul_hi_u32 s27, s29, 0x640
	s_mul_i32 s26, s29, 0x640
	s_add_u32 s26, s18, s26
	s_addc_u32 s27, s19, s27
	global_load_dwordx4 v[80:83], v2, s[26:27]
	global_load_dwordx2 v[84:85], v2, s[26:27] offset:16
	global_load_ubyte v86, v3, s[26:27]
	v_readlane_b32 s29, v37, s28
	s_add_u32 s28, s28, 1
	s_mul_hi_u32 s27, s29, 0x640
	s_mul_i32 s26, s29, 0x640
	s_add_u32 s26, s18, s26
	s_addc_u32 s27, s19, s27
	global_load_dwordx4 v[88:91], v2, s[26:27]
	global_load_dwordx2 v[92:93], v2, s[26:27] offset:16
	global_load_ubyte v94, v3, s[26:27]
	v_readlane_b32 s29, v37, s28
	s_add_u32 s28, s28, 1
	s_mul_hi_u32 s27, s29, 0x640
	s_mul_i32 s26, s29, 0x640
	s_add_u32 s26, s18, s26
	s_addc_u32 s27, s19, s27
	global_load_dwordx4 v[96:99], v2, s[26:27]
	global_load_dwordx2 v[100:101], v2, s[26:27] offset:16
	global_load_ubyte v102, v3, s[26:27]
	v_readlane_b32 s29, v37, s28
	s_add_u32 s28, s28, 1
	s_mul_hi_u32 s27, s29, 0x640
	s_mul_i32 s26, s29, 0x640
	s_add_u32 s26, s18, s26
	s_addc_u32 s27, s19, s27
	global_load_dwordx4 v[104:107], v2, s[26:27]
	global_load_dwordx2 v[108:109], v2, s[26:27] offset:16
	global_load_ubyte v110, v3, s[26:27]
	s_mov_b32 s30, 7
; #define PB_FENCE asm volatile("" ::: "memory")
; __device__ __forceinline__ void ph_peer_apply(const Params& P, int layer, float* xlat, float* xctx_in, float* xctx_out, int nrows, bool write_next, char* smem, float* xlat_out = nullptr) {
;     ...
;     PB_LOAD(bufA, tv, 0);
;     for (int gq = 0; gq < NG; gq += 2) {
;       PB_LOAD(bufB, tv, gq + 1); PB_FENCE;
;       PB_ACC(bufA, gq);
;       if (gq + 2 < NG) PB_LOAD(bufA, tv, gq + 2);
;       PB_FENCE;
;       PB_ACC(bufB, gq + 1);
;     }
.Lap0_s2_loop4:
	v_readlane_b32 s36, v43, s37
	s_add_u32 s37, s37, 1
	s_waitcnt vmcnt(21)
	v_lshlrev_b32_e32 v192, 23, v54
	v_cvt_scalef32_pk32_f32_fp6 v[112:143], v[48:53], v192
	v_fmac_f32_e32 v160, s36, v112
	v_fmac_f32_e32 v161, s36, v113
	v_fmac_f32_e32 v162, s36, v114
	v_fmac_f32_e32 v163, s36, v115
	v_fmac_f32_e32 v164, s36, v116
	v_fmac_f32_e32 v165, s36, v117
	v_fmac_f32_e32 v166, s36, v118
	v_fmac_f32_e32 v167, s36, v119
	v_fmac_f32_e32 v168, s36, v120
	v_fmac_f32_e32 v169, s36, v121
	v_fmac_f32_e32 v170, s36, v122
	v_fmac_f32_e32 v171, s36, v123
	v_fmac_f32_e32 v172, s36, v124
	v_fmac_f32_e32 v173, s36, v125
	v_fmac_f32_e32 v174, s36, v126
	v_fmac_f32_e32 v175, s36, v127
	v_fmac_f32_e32 v176, s36, v128
	v_fmac_f32_e32 v177, s36, v129
	v_fmac_f32_e32 v178, s36, v130
	v_fmac_f32_e32 v179, s36, v131
	v_fmac_f32_e32 v180, s36, v132
	v_fmac_f32_e32 v181, s36, v133
	v_fmac_f32_e32 v182, s36, v134
	v_fmac_f32_e32 v183, s36, v135
	v_fmac_f32_e32 v184, s36, v136
	v_fmac_f32_e32 v185, s36, v137
	v_fmac_f32_e32 v186, s36, v138
	v_fmac_f32_e32 v187, s36, v139
	v_fmac_f32_e32 v188, s36, v140
	v_fmac_f32_e32 v189, s36, v141
	v_fmac_f32_e32 v190, s36, v142
	v_fmac_f32_e32 v191, s36, v143
	v_readlane_b32 s29, v37, s28
	s_add_u32 s28, s28, 1
	s_mul_hi_u32 s27, s29, 0x640
	s_mul_i32 s26, s29, 0x640
	s_add_u32 s26, s18, s26
	s_addc_u32 s27, s19, s27
	global_load_dwordx4 v[48:51], v2, s[26:27]
	global_load_dwordx2 v[52:53], v2, s[26:27] offset:16
	global_load_ubyte v54, v3, s[26:27]
	v_readlane_b32 s36, v43, s37
	s_add_u32 s37, s37, 1
	s_waitcnt vmcnt(21)
	v_lshlrev_b32_e32 v192, 23, v62
	v_cvt_scalef32_pk32_f32_fp6 v[112:143], v[56:61], v192
	v_fmac_f32_e32 v160, s36, v112
	v_fmac_f32_e32 v161, s36, v113
	v_fmac_f32_e32 v162, s36, v114
	v_fmac_f32_e32 v163, s36, v115
	v_fmac_f32_e32 v164, s36, v116
	v_fmac_f32_e32 v165, s36, v117
	v_fmac_f32_e32 v166, s36, v118
	v_fmac_f32_e32 v167, s36, v119
	v_fmac_f32_e32 v168, s36, v120
	v_fmac_f32_e32 v169, s36, v121
	v_fmac_f32_e32 v170, s36, v122
	v_fmac_f32_e32 v171, s36, v123
	v_fmac_f32_e32 v172, s36, v124
	v_fmac_f32_e32 v173, s36, v125
	v_fmac_f32_e32 v174, s36, v126
	v_fmac_f32_e32 v175, s36, v127
	v_fmac_f32_e32 v176, s36, v128
	v_fmac_f32_e32 v177, s36, v129
	v_fmac_f32_e32 v178, s36, v130
	v_fmac_f32_e32 v179, s36, v131
	v_fmac_f32_e32 v180, s36, v132
	v_fmac_f32_e32 v181, s36, v133
	v_fmac_f32_e32 v182, s36, v134
	v_fmac_f32_e32 v183, s36, v135
	v_fmac_f32_e32 v184, s36, v136
	v_fmac_f32_e32 v185, s36, v137
	v_fmac_f32_e32 v186, s36, v138
	v_fmac_f32_e32 v187, s36, v139
	v_fmac_f32_e32 v188, s36, v140
	v_fmac_f32_e32 v189, s36, v141
	v_fmac_f32_e32 v190, s36, v142
	v_fmac_f32_e32 v191, s36, v143
	v_readlane_b32 s29, v37, s28
	s_add_u32 s28, s28, 1
	s_mul_hi_u32 s27, s29, 0x640
	s_mul_i32 s26, s29, 0x640
	s_add_u32 s26, s18, s26
	s_addc_u32 s27, s19, s27
	global_load_dwordx4 v[56:59], v2, s[26:27]
	global_load_dwordx2 v[60:61], v2, s[26:27] offset:16
	global_load_ubyte v62, v3, s[26:27]
	v_readlane_b32 s36, v43, s37
	s_add_u32 s37, s37, 1
	s_waitcnt vmcnt(21)
	v_lshlrev_b32_e32 v192, 23, v70
	v_cvt_scalef32_pk32_f32_fp6 v[112:143], v[64:69], v192
	v_fmac_f32_e32 v160, s36, v112
	v_fmac_f32_e32 v161, s36, v113
	v_fmac_f32_e32 v162, s36, v114
	v_fmac_f32_e32 v163, s36, v115
	v_fmac_f32_e32 v164, s36, v116
	v_fmac_f32_e32 v165, s36, v117
	v_fmac_f32_e32 v166, s36, v118
	v_fmac_f32_e32 v167, s36, v119
	v_fmac_f32_e32 v168, s36, v120
	v_fmac_f32_e32 v169, s36, v121
	v_fmac_f32_e32 v170, s36, v122
	v_fmac_f32_e32 v171, s36, v123
	v_fmac_f32_e32 v172, s36, v124
	v_fmac_f32_e32 v173, s36, v125
	v_fmac_f32_e32 v174, s36, v126
	v_fmac_f32_e32 v175, s36, v127
	v_fmac_f32_e32 v176, s36, v128
	v_fmac_f32_e32 v177, s36, v129
	v_fmac_f32_e32 v178, s36, v130
	v_fmac_f32_e32 v179, s36, v131
	v_fmac_f32_e32 v180, s36, v132
	v_fmac_f32_e32 v181, s36, v133
	v_fmac_f32_e32 v182, s36, v134
	v_fmac_f32_e32 v183, s36, v135
	v_fmac_f32_e32 v184, s36, v136
	v_fmac_f32_e32 v185, s36, v137
	v_fmac_f32_e32 v186, s36, v138
	v_fmac_f32_e32 v187, s36, v139
	v_fmac_f32_e32 v188, s36, v140
	v_fmac_f32_e32 v189, s36, v141
	v_fmac_f32_e32 v190, s36, v142
	v_fmac_f32_e32 v191, s36, v143
	v_readlane_b32 s29, v37, s28
	s_add_u32 s28, s28, 1
	s_mul_hi_u32 s27, s29, 0x640
	s_mul_i32 s26, s29, 0x640
	s_add_u32 s26, s18, s26
	s_addc_u32 s27, s19, s27
	global_load_dwordx4 v[64:67], v2, s[26:27]
	global_load_dwordx2 v[68:69], v2, s[26:27] offset:16
	global_load_ubyte v70, v3, s[26:27]
	v_readlane_b32 s36, v43, s37
	s_add_u32 s37, s37, 1
	s_waitcnt vmcnt(21)
	v_lshlrev_b32_e32 v192, 23, v78
	v_cvt_scalef32_pk32_f32_fp6 v[112:143], v[72:77], v192
	v_fmac_f32_e32 v160, s36, v112
	v_fmac_f32_e32 v161, s36, v113
	v_fmac_f32_e32 v162, s36, v114
	v_fmac_f32_e32 v163, s36, v115
	v_fmac_f32_e32 v164, s36, v116
	v_fmac_f32_e32 v165, s36, v117
	v_fmac_f32_e32 v166, s36, v118
	v_fmac_f32_e32 v167, s36, v119
	v_fmac_f32_e32 v168, s36, v120
	v_fmac_f32_e32 v169, s36, v121
	v_fmac_f32_e32 v170, s36, v122
	v_fmac_f32_e32 v171, s36, v123
	v_fmac_f32_e32 v172, s36, v124
	v_fmac_f32_e32 v173, s36, v125
	v_fmac_f32_e32 v174, s36, v126
	v_fmac_f32_e32 v175, s36, v127
	v_fmac_f32_e32 v176, s36, v128
	v_fmac_f32_e32 v177, s36, v129
	v_fmac_f32_e32 v178, s36, v130
	v_fmac_f32_e32 v179, s36, v131
	v_fmac_f32_e32 v180, s36, v132
	v_fmac_f32_e32 v181, s36, v133
	v_fmac_f32_e32 v182, s36, v134
	v_fmac_f32_e32 v183, s36, v135
	v_fmac_f32_e32 v184, s36, v136
	v_fmac_f32_e32 v185, s36, v137
	v_fmac_f32_e32 v186, s36, v138
	v_fmac_f32_e32 v187, s36, v139
	v_fmac_f32_e32 v188, s36, v140
	v_fmac_f32_e32 v189, s36, v141
	v_fmac_f32_e32 v190, s36, v142
	v_fmac_f32_e32 v191, s36, v143
	v_readlane_b32 s29, v37, s28
	s_add_u32 s28, s28, 1
	s_mul_hi_u32 s27, s29, 0x640
	s_mul_i32 s26, s29, 0x640
	s_add_u32 s26, s18, s26
	s_addc_u32 s27, s19, s27
	global_load_dwordx4 v[72:75], v2, s[26:27]
	global_load_dwordx2 v[76:77], v2, s[26:27] offset:16
	global_load_ubyte v78, v3, s[26:27]
	v_readlane_b32 s36, v43, s37
	s_add_u32 s37, s37, 1
	s_waitcnt vmcnt(21)
; #define PB_FENCE asm volatile("" ::: "memory")
; __device__ __forceinline__ void ph_peer_apply(const Params& P, int layer, float* xlat, float* xctx_in, float* xctx_out, int nrows, bool write_next, char* smem, float* xlat_out = nullptr) {
;     ...
;     PB_LOAD(bufA, tv, 0);
;     for (int gq = 0; gq < NG; gq += 2) {
;       PB_LOAD(bufB, tv, gq + 1); PB_FENCE;
;       PB_ACC(bufA, gq);
;       if (gq + 2 < NG) PB_LOAD(bufA, tv, gq + 2);
;       PB_FENCE;
;       PB_ACC(bufB, gq + 1);
;     }
	v_lshlrev_b32_e32 v192, 23, v86
	v_cvt_scalef32_pk32_f32_fp6 v[112:143], v[80:85], v192
	v_fmac_f32_e32 v160, s36, v112
	v_fmac_f32_e32 v161, s36, v113
	v_fmac_f32_e32 v162, s36, v114
	v_fmac_f32_e32 v163, s36, v115
	v_fmac_f32_e32 v164, s36, v116
	v_fmac_f32_e32 v165, s36, v117
	v_fmac_f32_e32 v166, s36, v118
	v_fmac_f32_e32 v167, s36, v119
	v_fmac_f32_e32 v168, s36, v120
	v_fmac_f32_e32 v169, s36, v121
	v_fmac_f32_e32 v170, s36, v122
	v_fmac_f32_e32 v171, s36, v123
	v_fmac_f32_e32 v172, s36, v124
	v_fmac_f32_e32 v173, s36, v125
	v_fmac_f32_e32 v174, s36, v126
	v_fmac_f32_e32 v175, s36, v127
	v_fmac_f32_e32 v176, s36, v128
	v_fmac_f32_e32 v177, s36, v129
	v_fmac_f32_e32 v178, s36, v130
	v_fmac_f32_e32 v179, s36, v131
	v_fmac_f32_e32 v180, s36, v132
	v_fmac_f32_e32 v181, s36, v133
	v_fmac_f32_e32 v182, s36, v134
	v_fmac_f32_e32 v183, s36, v135
	v_fmac_f32_e32 v184, s36, v136
	v_fmac_f32_e32 v185, s36, v137
	v_fmac_f32_e32 v186, s36, v138
	v_fmac_f32_e32 v187, s36, v139
	v_fmac_f32_e32 v188, s36, v140
	v_fmac_f32_e32 v189, s36, v141
	v_fmac_f32_e32 v190, s36, v142
	v_fmac_f32_e32 v191, s36, v143
	v_readlane_b32 s29, v37, s28
	s_add_u32 s28, s28, 1
	s_mul_hi_u32 s27, s29, 0x640
	s_mul_i32 s26, s29, 0x640
	s_add_u32 s26, s18, s26
	s_addc_u32 s27, s19, s27
	global_load_dwordx4 v[80:83], v2, s[26:27]
	global_load_dwordx2 v[84:85], v2, s[26:27] offset:16
	global_load_ubyte v86, v3, s[26:27]
	v_readlane_b32 s36, v43, s37
	s_add_u32 s37, s37, 1
	s_waitcnt vmcnt(21)
	v_lshlrev_b32_e32 v192, 23, v94
	v_cvt_scalef32_pk32_f32_fp6 v[112:143], v[88:93], v192
	v_fmac_f32_e32 v160, s36, v112
	v_fmac_f32_e32 v161, s36, v113
	v_fmac_f32_e32 v162, s36, v114
	v_fmac_f32_e32 v163, s36, v115
	v_fmac_f32_e32 v164, s36, v116
	v_fmac_f32_e32 v165, s36, v117
	v_fmac_f32_e32 v166, s36, v118
	v_fmac_f32_e32 v167, s36, v119
	v_fmac_f32_e32 v168, s36, v120
	v_fmac_f32_e32 v169, s36, v121
	v_fmac_f32_e32 v170, s36, v122
	v_fmac_f32_e32 v171, s36, v123
	v_fmac_f32_e32 v172, s36, v124
	v_fmac_f32_e32 v173, s36, v125
	v_fmac_f32_e32 v174, s36, v126
	v_fmac_f32_e32 v175, s36, v127
	v_fmac_f32_e32 v176, s36, v128
	v_fmac_f32_e32 v177, s36, v129
	v_fmac_f32_e32 v178, s36, v130
	v_fmac_f32_e32 v179, s36, v131
	v_fmac_f32_e32 v180, s36, v132
	v_fmac_f32_e32 v181, s36, v133
	v_fmac_f32_e32 v182, s36, v134
	v_fmac_f32_e32 v183, s36, v135
	v_fmac_f32_e32 v184, s36, v136
	v_fmac_f32_e32 v185, s36, v137
	v_fmac_f32_e32 v186, s36, v138
	v_fmac_f32_e32 v187, s36, v139
	v_fmac_f32_e32 v188, s36, v140
	v_fmac_f32_e32 v189, s36, v141
	v_fmac_f32_e32 v190, s36, v142
	v_fmac_f32_e32 v191, s36, v143
	v_readlane_b32 s29, v37, s28
	s_add_u32 s28, s28, 1
	s_mul_hi_u32 s27, s29, 0x640
	s_mul_i32 s26, s29, 0x640
	s_add_u32 s26, s18, s26
	s_addc_u32 s27, s19, s27
	global_load_dwordx4 v[88:91], v2, s[26:27]
	global_load_dwordx2 v[92:93], v2, s[26:27] offset:16
	global_load_ubyte v94, v3, s[26:27]
	v_readlane_b32 s36, v43, s37
	s_add_u32 s37, s37, 1
	s_waitcnt vmcnt(21)
	v_lshlrev_b32_e32 v192, 23, v102
	v_cvt_scalef32_pk32_f32_fp6 v[112:143], v[96:101], v192
	v_fmac_f32_e32 v160, s36, v112
	v_fmac_f32_e32 v161, s36, v113
	v_fmac_f32_e32 v162, s36, v114
	v_fmac_f32_e32 v163, s36, v115
	v_fmac_f32_e32 v164, s36, v116
	v_fmac_f32_e32 v165, s36, v117
	v_fmac_f32_e32 v166, s36, v118
	v_fmac_f32_e32 v167, s36, v119
	v_fmac_f32_e32 v168, s36, v120
	v_fmac_f32_e32 v169, s36, v121
	v_fmac_f32_e32 v170, s36, v122
	v_fmac_f32_e32 v171, s36, v123
	v_fmac_f32_e32 v172, s36, v124
	v_fmac_f32_e32 v173, s36, v125
	v_fmac_f32_e32 v174, s36, v126
	v_fmac_f32_e32 v175, s36, v127
	v_fmac_f32_e32 v176, s36, v128
	v_fmac_f32_e32 v177, s36, v129
	v_fmac_f32_e32 v178, s36, v130
	v_fmac_f32_e32 v179, s36, v131
	v_fmac_f32_e32 v180, s36, v132
	v_fmac_f32_e32 v181, s36, v133
	v_fmac_f32_e32 v182, s36, v134
	v_fmac_f32_e32 v183, s36, v135
	v_fmac_f32_e32 v184, s36, v136
	v_fmac_f32_e32 v185, s36, v137
	v_fmac_f32_e32 v186, s36, v138
	v_fmac_f32_e32 v187, s36, v139
	v_fmac_f32_e32 v188, s36, v140
	v_fmac_f32_e32 v189, s36, v141
	v_fmac_f32_e32 v190, s36, v142
	v_fmac_f32_e32 v191, s36, v143
	v_readlane_b32 s29, v37, s28
	s_add_u32 s28, s28, 1
	s_mul_hi_u32 s27, s29, 0x640
	s_mul_i32 s26, s29, 0x640
	s_add_u32 s26, s18, s26
	s_addc_u32 s27, s19, s27
	global_load_dwordx4 v[96:99], v2, s[26:27]
	global_load_dwordx2 v[100:101], v2, s[26:27] offset:16
	global_load_ubyte v102, v3, s[26:27]
	v_readlane_b32 s36, v43, s37
	s_add_u32 s37, s37, 1
	s_waitcnt vmcnt(21)
	v_lshlrev_b32_e32 v192, 23, v110
	v_cvt_scalef32_pk32_f32_fp6 v[112:143], v[104:109], v192
	v_fmac_f32_e32 v160, s36, v112
	v_fmac_f32_e32 v161, s36, v113
	v_fmac_f32_e32 v162, s36, v114
	v_fmac_f32_e32 v163, s36, v115
	v_fmac_f32_e32 v164, s36, v116
	v_fmac_f32_e32 v165, s36, v117
	v_fmac_f32_e32 v166, s36, v118
	v_fmac_f32_e32 v167, s36, v119
	v_fmac_f32_e32 v168, s36, v120
	v_fmac_f32_e32 v169, s36, v121
	v_fmac_f32_e32 v170, s36, v122
	v_fmac_f32_e32 v171, s36, v123
	v_fmac_f32_e32 v172, s36, v124
	v_fmac_f32_e32 v173, s36, v125
	v_fmac_f32_e32 v174, s36, v126
	v_fmac_f32_e32 v175, s36, v127
	v_fmac_f32_e32 v176, s36, v128
	v_fmac_f32_e32 v177, s36, v129
	v_fmac_f32_e32 v178, s36, v130
	v_fmac_f32_e32 v179, s36, v131
	v_fmac_f32_e32 v180, s36, v132
	v_fmac_f32_e32 v181, s36, v133
	v_fmac_f32_e32 v182, s36, v134
	v_fmac_f32_e32 v183, s36, v135
	v_fmac_f32_e32 v184, s36, v136
	v_fmac_f32_e32 v185, s36, v137
	v_fmac_f32_e32 v186, s36, v138
	v_fmac_f32_e32 v187, s36, v139
	v_fmac_f32_e32 v188, s36, v140
	v_fmac_f32_e32 v189, s36, v141
	v_fmac_f32_e32 v190, s36, v142
	v_fmac_f32_e32 v191, s36, v143
	v_readlane_b32 s29, v37, s28
	s_add_u32 s28, s28, 1
	s_mul_hi_u32 s27, s29, 0x640
	s_mul_i32 s26, s29, 0x640
	s_add_u32 s26, s18, s26
	s_addc_u32 s27, s19, s27
	global_load_dwordx4 v[104:107], v2, s[26:27]
	global_load_dwordx2 v[108:109], v2, s[26:27] offset:16
	global_load_ubyte v110, v3, s[26:27]
	s_sub_u32 s30, s30, 1
	s_cmp_lg_u32 s30, 0
	s_cbranch_scc1 .Lap0_s2_loop4
; #define PB_FENCE asm volatile("" ::: "memory")
; __device__ __forceinline__ void ph_peer_apply(const Params& P, int layer, float* xlat, float* xctx_in, float* xctx_out, int nrows, bool write_next, char* smem, float* xlat_out = nullptr) {
;     ...
;     PB_LOAD(bufA, tv, 0);
;     for (int gq = 0; gq < NG; gq += 2) {
;       PB_LOAD(bufB, tv, gq + 1); PB_FENCE;
;       PB_ACC(bufA, gq);
;       if (gq + 2 < NG) PB_LOAD(bufA, tv, gq + 2);
;       PB_FENCE;
;       PB_ACC(bufB, gq + 1);
;     }
	v_readlane_b32 s36, v43, s37
	s_add_u32 s37, s37, 1
	s_waitcnt vmcnt(21)
	v_lshlrev_b32_e32 v192, 23, v54
	v_cvt_scalef32_pk32_f32_fp6 v[112:143], v[48:53], v192
	v_fmac_f32_e32 v160, s36, v112
	v_fmac_f32_e32 v161, s36, v113
	v_fmac_f32_e32 v162, s36, v114
	v_fmac_f32_e32 v163, s36, v115
	v_fmac_f32_e32 v164, s36, v116
	v_fmac_f32_e32 v165, s36, v117
	v_fmac_f32_e32 v166, s36, v118
	v_fmac_f32_e32 v167, s36, v119
	v_fmac_f32_e32 v168, s36, v120
	v_fmac_f32_e32 v169, s36, v121
	v_fmac_f32_e32 v170, s36, v122
	v_fmac_f32_e32 v171, s36, v123
	v_fmac_f32_e32 v172, s36, v124
	v_fmac_f32_e32 v173, s36, v125
	v_fmac_f32_e32 v174, s36, v126
	v_fmac_f32_e32 v175, s36, v127
	v_fmac_f32_e32 v176, s36, v128
	v_fmac_f32_e32 v177, s36, v129
	v_fmac_f32_e32 v178, s36, v130
	v_fmac_f32_e32 v179, s36, v131
	v_fmac_f32_e32 v180, s36, v132
	v_fmac_f32_e32 v181, s36, v133
	v_fmac_f32_e32 v182, s36, v134
	v_fmac_f32_e32 v183, s36, v135
	v_fmac_f32_e32 v184, s36, v136
	v_fmac_f32_e32 v185, s36, v137
	v_fmac_f32_e32 v186, s36, v138
	v_fmac_f32_e32 v187, s36, v139
	v_fmac_f32_e32 v188, s36, v140
	v_fmac_f32_e32 v189, s36, v141
	v_fmac_f32_e32 v190, s36, v142
	v_fmac_f32_e32 v191, s36, v143
	v_readlane_b32 s36, v43, s37
	s_add_u32 s37, s37, 1
	s_waitcnt vmcnt(18)
	v_lshlrev_b32_e32 v192, 23, v62
	v_cvt_scalef32_pk32_f32_fp6 v[112:143], v[56:61], v192
	v_fmac_f32_e32 v160, s36, v112
	v_fmac_f32_e32 v161, s36, v113
	v_fmac_f32_e32 v162, s36, v114
	v_fmac_f32_e32 v163, s36, v115
	v_fmac_f32_e32 v164, s36, v116
	v_fmac_f32_e32 v165, s36, v117
	v_fmac_f32_e32 v166, s36, v118
	v_fmac_f32_e32 v167, s36, v119
	v_fmac_f32_e32 v168, s36, v120
	v_fmac_f32_e32 v169, s36, v121
	v_fmac_f32_e32 v170, s36, v122
	v_fmac_f32_e32 v171, s36, v123
	v_fmac_f32_e32 v172, s36, v124
	v_fmac_f32_e32 v173, s36, v125
	v_fmac_f32_e32 v174, s36, v126
	v_fmac_f32_e32 v175, s36, v127
	v_fmac_f32_e32 v176, s36, v128
	v_fmac_f32_e32 v177, s36, v129
	v_fmac_f32_e32 v178, s36, v130
	v_fmac_f32_e32 v179, s36, v131
	v_fmac_f32_e32 v180, s36, v132
	v_fmac_f32_e32 v181, s36, v133
	v_fmac_f32_e32 v182, s36, v134
	v_fmac_f32_e32 v183, s36, v135
	v_fmac_f32_e32 v184, s36, v136
	v_fmac_f32_e32 v185, s36, v137
	v_fmac_f32_e32 v186, s36, v138
	v_fmac_f32_e32 v187, s36, v139
	v_fmac_f32_e32 v188, s36, v140
	v_fmac_f32_e32 v189, s36, v141
	v_fmac_f32_e32 v190, s36, v142
	v_fmac_f32_e32 v191, s36, v143
	v_readlane_b32 s36, v43, s37
	s_add_u32 s37, s37, 1
	s_waitcnt vmcnt(15)
	v_lshlrev_b32_e32 v192, 23, v70
	v_cvt_scalef32_pk32_f32_fp6 v[112:143], v[64:69], v192
	v_fmac_f32_e32 v160, s36, v112
	v_fmac_f32_e32 v161, s36, v113
	v_fmac_f32_e32 v162, s36, v114
	v_fmac_f32_e32 v163, s36, v115
	v_fmac_f32_e32 v164, s36, v116
	v_fmac_f32_e32 v165, s36, v117
	v_fmac_f32_e32 v166, s36, v118
	v_fmac_f32_e32 v167, s36, v119
	v_fmac_f32_e32 v168, s36, v120
	v_fmac_f32_e32 v169, s36, v121
	v_fmac_f32_e32 v170, s36, v122
	v_fmac_f32_e32 v171, s36, v123
	v_fmac_f32_e32 v172, s36, v124
	v_fmac_f32_e32 v173, s36, v125
	v_fmac_f32_e32 v174, s36, v126
	v_fmac_f32_e32 v175, s36, v127
	v_fmac_f32_e32 v176, s36, v128
	v_fmac_f32_e32 v177, s36, v129
	v_fmac_f32_e32 v178, s36, v130
	v_fmac_f32_e32 v179, s36, v131
	v_fmac_f32_e32 v180, s36, v132
	v_fmac_f32_e32 v181, s36, v133
	v_fmac_f32_e32 v182, s36, v134
	v_fmac_f32_e32 v183, s36, v135
	v_fmac_f32_e32 v184, s36, v136
	v_fmac_f32_e32 v185, s36, v137
	v_fmac_f32_e32 v186, s36, v138
	v_fmac_f32_e32 v187, s36, v139
	v_fmac_f32_e32 v188, s36, v140
	v_fmac_f32_e32 v189, s36, v141
	v_fmac_f32_e32 v190, s36, v142
	v_fmac_f32_e32 v191, s36, v143
	v_readlane_b32 s36, v43, s37
	s_add_u32 s37, s37, 1
	s_waitcnt vmcnt(12)
	v_lshlrev_b32_e32 v192, 23, v78
	v_cvt_scalef32_pk32_f32_fp6 v[112:143], v[72:77], v192
	v_fmac_f32_e32 v160, s36, v112
	v_fmac_f32_e32 v161, s36, v113
	v_fmac_f32_e32 v162, s36, v114
	v_fmac_f32_e32 v163, s36, v115
	v_fmac_f32_e32 v164, s36, v116
	v_fmac_f32_e32 v165, s36, v117
	v_fmac_f32_e32 v166, s36, v118
	v_fmac_f32_e32 v167, s36, v119
	v_fmac_f32_e32 v168, s36, v120
	v_fmac_f32_e32 v169, s36, v121
	v_fmac_f32_e32 v170, s36, v122
	v_fmac_f32_e32 v171, s36, v123
	v_fmac_f32_e32 v172, s36, v124
	v_fmac_f32_e32 v173, s36, v125
	v_fmac_f32_e32 v174, s36, v126
	v_fmac_f32_e32 v175, s36, v127
	v_fmac_f32_e32 v176, s36, v128
	v_fmac_f32_e32 v177, s36, v129
	v_fmac_f32_e32 v178, s36, v130
	v_fmac_f32_e32 v179, s36, v131
	v_fmac_f32_e32 v180, s36, v132
	v_fmac_f32_e32 v181, s36, v133
	v_fmac_f32_e32 v182, s36, v134
	v_fmac_f32_e32 v183, s36, v135
	v_fmac_f32_e32 v184, s36, v136
	v_fmac_f32_e32 v185, s36, v137
	v_fmac_f32_e32 v186, s36, v138
	v_fmac_f32_e32 v187, s36, v139
	v_fmac_f32_e32 v188, s36, v140
	v_fmac_f32_e32 v189, s36, v141
	v_fmac_f32_e32 v190, s36, v142
	v_fmac_f32_e32 v191, s36, v143
	v_readlane_b32 s36, v43, s37
	s_add_u32 s37, s37, 1
	s_waitcnt vmcnt(9)
	v_lshlrev_b32_e32 v192, 23, v86
	v_cvt_scalef32_pk32_f32_fp6 v[112:143], v[80:85], v192
	v_fmac_f32_e32 v160, s36, v112
	v_fmac_f32_e32 v161, s36, v113
	v_fmac_f32_e32 v162, s36, v114
	v_fmac_f32_e32 v163, s36, v115
	v_fmac_f32_e32 v164, s36, v116
	v_fmac_f32_e32 v165, s36, v117
	v_fmac_f32_e32 v166, s36, v118
	v_fmac_f32_e32 v167, s36, v119
	v_fmac_f32_e32 v168, s36, v120
	v_fmac_f32_e32 v169, s36, v121
	v_fmac_f32_e32 v170, s36, v122
	v_fmac_f32_e32 v171, s36, v123
	v_fmac_f32_e32 v172, s36, v124
	v_fmac_f32_e32 v173, s36, v125
	v_fmac_f32_e32 v174, s36, v126
	v_fmac_f32_e32 v175, s36, v127
	v_fmac_f32_e32 v176, s36, v128
	v_fmac_f32_e32 v177, s36, v129
	v_fmac_f32_e32 v178, s36, v130
	v_fmac_f32_e32 v179, s36, v131
	v_fmac_f32_e32 v180, s36, v132
	v_fmac_f32_e32 v181, s36, v133
	v_fmac_f32_e32 v182, s36, v134
	v_fmac_f32_e32 v183, s36, v135
	v_fmac_f32_e32 v184, s36, v136
	v_fmac_f32_e32 v185, s36, v137
	v_fmac_f32_e32 v186, s36, v138
	v_fmac_f32_e32 v187, s36, v139
	v_fmac_f32_e32 v188, s36, v140
	v_fmac_f32_e32 v189, s36, v141
	v_fmac_f32_e32 v190, s36, v142
	v_fmac_f32_e32 v191, s36, v143
	v_readlane_b32 s36, v43, s37
	s_add_u32 s37, s37, 1
	s_waitcnt vmcnt(6)
; #define PB_FENCE asm volatile("" ::: "memory")
; __device__ __forceinline__ void ph_peer_apply(const Params& P, int layer, float* xlat, float* xctx_in, float* xctx_out, int nrows, bool write_next, char* smem, float* xlat_out = nullptr) {
;     ...
;     PB_LOAD(bufA, tv, 0);
;     for (int gq = 0; gq < NG; gq += 2) {
;       PB_LOAD(bufB, tv, gq + 1); PB_FENCE;
;       PB_ACC(bufA, gq);
;       if (gq + 2 < NG) PB_LOAD(bufA, tv, gq + 2);
;       PB_FENCE;
;       PB_ACC(bufB, gq + 1);
;     }
;     ...
;     const float* xs1 = (row < NL ? xlat + (size_t)row * D : xctx_in + (size_t)(row - NL) * D) + lb * 32;
;     float* xo = (row < NL ? (xlat_out ? xlat_out : xlat) + (size_t)row * D : xctx_out + (size_t)(row - NL) * D) + lb * 32;
;     const float* gt = mod_ptr(P, layer, row, 5) + lb * 32;
;     float s = 0.f;
; #pragma unroll
;     for (int j4 = 0; j4 < 8; ++j4) {
;       float4 xa; const float4 ga = *(const float4*)(gt + j4 * 4);
;       if (row < NL) { const h16x4 xh_ = *(const h16x4*)((const h16*)(xlat + (size_t)row * D) + lb * 32 + j4 * 4); xa = make_float4((float)xh_[0], (float)xh_[1], (float)xh_[2], (float)xh_[3]); }
;       else xa = *(const float4*)(xs1 + j4 * 4);
;       o[j4 * 4 + 0] = ALPHA * xa.x + ga.x * o[j4 * 4 + 0]; o[j4 * 4 + 1] = ALPHA * xa.y + ga.y * o[j4 * 4 + 1];
;       o[j4 * 4 + 2] = ALPHA * xa.z + ga.z * o[j4 * 4 + 2]; o[j4 * 4 + 3] = ALPHA * xa.w + ga.w * o[j4 * 4 + 3];
;       s += (o[j4 * 4 + 0] + o[j4 * 4 + 1]) + (o[j4 * 4 + 2] + o[j4 * 4 + 3]);
	v_lshlrev_b32_e32 v192, 23, v94
	v_cvt_scalef32_pk32_f32_fp6 v[112:143], v[88:93], v192
	v_fmac_f32_e32 v160, s36, v112
	v_fmac_f32_e32 v161, s36, v113
	v_fmac_f32_e32 v162, s36, v114
	v_fmac_f32_e32 v163, s36, v115
	v_fmac_f32_e32 v164, s36, v116
	v_fmac_f32_e32 v165, s36, v117
	v_fmac_f32_e32 v166, s36, v118
	v_fmac_f32_e32 v167, s36, v119
	v_fmac_f32_e32 v168, s36, v120
	v_fmac_f32_e32 v169, s36, v121
	v_fmac_f32_e32 v170, s36, v122
	v_fmac_f32_e32 v171, s36, v123
	v_fmac_f32_e32 v172, s36, v124
	v_fmac_f32_e32 v173, s36, v125
	v_fmac_f32_e32 v174, s36, v126
	v_fmac_f32_e32 v175, s36, v127
	v_fmac_f32_e32 v176, s36, v128
	v_fmac_f32_e32 v177, s36, v129
	v_fmac_f32_e32 v178, s36, v130
	v_fmac_f32_e32 v179, s36, v131
	v_fmac_f32_e32 v180, s36, v132
	v_fmac_f32_e32 v181, s36, v133
	v_fmac_f32_e32 v182, s36, v134
	v_fmac_f32_e32 v183, s36, v135
	v_fmac_f32_e32 v184, s36, v136
	v_fmac_f32_e32 v185, s36, v137
	v_fmac_f32_e32 v186, s36, v138
	v_fmac_f32_e32 v187, s36, v139
	v_fmac_f32_e32 v188, s36, v140
	v_fmac_f32_e32 v189, s36, v141
	v_fmac_f32_e32 v190, s36, v142
	v_fmac_f32_e32 v191, s36, v143
	v_readlane_b32 s36, v43, s37
	s_add_u32 s37, s37, 1
	s_waitcnt vmcnt(3)
	v_lshlrev_b32_e32 v192, 23, v102
	v_cvt_scalef32_pk32_f32_fp6 v[112:143], v[96:101], v192
	v_fmac_f32_e32 v160, s36, v112
	v_fmac_f32_e32 v161, s36, v113
	v_fmac_f32_e32 v162, s36, v114
	v_fmac_f32_e32 v163, s36, v115
	v_fmac_f32_e32 v164, s36, v116
	v_fmac_f32_e32 v165, s36, v117
	v_fmac_f32_e32 v166, s36, v118
	v_fmac_f32_e32 v167, s36, v119
	v_fmac_f32_e32 v168, s36, v120
	v_fmac_f32_e32 v169, s36, v121
	v_fmac_f32_e32 v170, s36, v122
	v_fmac_f32_e32 v171, s36, v123
	v_fmac_f32_e32 v172, s36, v124
	v_fmac_f32_e32 v173, s36, v125
	v_fmac_f32_e32 v174, s36, v126
	v_fmac_f32_e32 v175, s36, v127
	v_fmac_f32_e32 v176, s36, v128
	v_fmac_f32_e32 v177, s36, v129
	v_fmac_f32_e32 v178, s36, v130
	v_fmac_f32_e32 v179, s36, v131
	v_fmac_f32_e32 v180, s36, v132
	v_fmac_f32_e32 v181, s36, v133
	v_fmac_f32_e32 v182, s36, v134
	v_fmac_f32_e32 v183, s36, v135
	v_fmac_f32_e32 v184, s36, v136
	v_fmac_f32_e32 v185, s36, v137
	v_fmac_f32_e32 v186, s36, v138
	v_fmac_f32_e32 v187, s36, v139
	v_fmac_f32_e32 v188, s36, v140
	v_fmac_f32_e32 v189, s36, v141
	v_fmac_f32_e32 v190, s36, v142
	v_fmac_f32_e32 v191, s36, v143
	v_readlane_b32 s36, v43, s37
	s_add_u32 s37, s37, 1
	s_waitcnt vmcnt(0)
	v_lshlrev_b32_e32 v192, 23, v110
	v_cvt_scalef32_pk32_f32_fp6 v[112:143], v[104:109], v192
	v_fmac_f32_e32 v160, s36, v112
	v_fmac_f32_e32 v161, s36, v113
	v_fmac_f32_e32 v162, s36, v114
	v_fmac_f32_e32 v163, s36, v115
	v_fmac_f32_e32 v164, s36, v116
	v_fmac_f32_e32 v165, s36, v117
	v_fmac_f32_e32 v166, s36, v118
	v_fmac_f32_e32 v167, s36, v119
	v_fmac_f32_e32 v168, s36, v120
	v_fmac_f32_e32 v169, s36, v121
	v_fmac_f32_e32 v170, s36, v122
	v_fmac_f32_e32 v171, s36, v123
	v_fmac_f32_e32 v172, s36, v124
	v_fmac_f32_e32 v173, s36, v125
	v_fmac_f32_e32 v174, s36, v126
	v_fmac_f32_e32 v175, s36, v127
	v_fmac_f32_e32 v176, s36, v128
	v_fmac_f32_e32 v177, s36, v129
	v_fmac_f32_e32 v178, s36, v130
	v_fmac_f32_e32 v179, s36, v131
	v_fmac_f32_e32 v180, s36, v132
	v_fmac_f32_e32 v181, s36, v133
	v_fmac_f32_e32 v182, s36, v134
	v_fmac_f32_e32 v183, s36, v135
	v_fmac_f32_e32 v184, s36, v136
	v_fmac_f32_e32 v185, s36, v137
	v_fmac_f32_e32 v186, s36, v138
	v_fmac_f32_e32 v187, s36, v139
	v_fmac_f32_e32 v188, s36, v140
	v_fmac_f32_e32 v189, s36, v141
	v_fmac_f32_e32 v190, s36, v142
	v_fmac_f32_e32 v191, s36, v143
	s_cmp_ge_u32 s45, 0x8000
	s_cselect_b32 s48, 1, 0
	s_lshr_b32 s49, s45, 14
	s_cmp_lg_u32 s48, 0
	s_cselect_b32 s49, 2, s49
	s_sub_u32 s50, s45, 0x8000
	s_lshl_b32 s15, s45, 13
	s_lshr_b32 s31, s45, 19
	s_add_u32 s40, s6, s15
	s_addc_u32 s41, s7, s31
	s_add_u32 s15, s49, 0
	s_mul_i32 s15, s15, 6
	s_add_u32 s15, s15, 5
	s_lshl_b32 s15, s15, 13
	s_add_u32 s42, s4, 0x4000
	s_addc_u32 s43, s5, 0
	s_add_u32 s42, s42, s15
	s_addc_u32 s43, s43, 0
	global_load_dwordx4 v[112:115], v225, s[42:43]
	global_load_dwordx4 v[116:119], v225, s[42:43] offset:16
	global_load_dwordx4 v[120:123], v225, s[42:43] offset:32
	global_load_dwordx4 v[124:127], v225, s[42:43] offset:48
	global_load_dwordx4 v[128:131], v225, s[42:43] offset:64
	global_load_dwordx4 v[132:135], v225, s[42:43] offset:80
	global_load_dwordx4 v[136:139], v225, s[42:43] offset:96
	global_load_dwordx4 v[140:143], v225, s[42:43] offset:112
	s_mov_b32 s15, 0x3fb504f3
	s_cmp_lg_u32 s48, 0
	s_cbranch_scc1 .Lap0_res_ctx
; __device__ __forceinline__ void ph_peer_apply(const Params& P, int layer, float* xlat, float* xctx_in, float* xctx_out, int nrows, bool write_next, char* smem, float* xlat_out = nullptr) {
;     ...
;     const float* xs1 = (row < NL ? xlat + (size_t)row * D : xctx_in + (size_t)(row - NL) * D) + lb * 32;
;     float* xo = (row < NL ? (xlat_out ? xlat_out : xlat) + (size_t)row * D : xctx_out + (size_t)(row - NL) * D) + lb * 32;
;     const float* gt = mod_ptr(P, layer, row, 5) + lb * 32;
;     float s = 0.f;
; #pragma unroll
;     for (int j4 = 0; j4 < 8; ++j4) {
;       float4 xa; const float4 ga = *(const float4*)(gt + j4 * 4);
;       if (row < NL) { const h16x4 xh_ = *(const h16x4*)((const h16*)(xlat + (size_t)row * D) + lb * 32 + j4 * 4); xa = make_float4((float)xh_[0], (float)xh_[1], (float)xh_[2], (float)xh_[3]); }
;       else xa = *(const float4*)(xs1 + j4 * 4);
;       o[j4 * 4 + 0] = ALPHA * xa.x + ga.x * o[j4 * 4 + 0]; o[j4 * 4 + 1] = ALPHA * xa.y + ga.y * o[j4 * 4 + 1];
;       o[j4 * 4 + 2] = ALPHA * xa.z + ga.z * o[j4 * 4 + 2]; o[j4 * 4 + 3] = ALPHA * xa.w + ga.w * o[j4 * 4 + 3];
;       s += (o[j4 * 4 + 0] + o[j4 * 4 + 1]) + (o[j4 * 4 + 2] + o[j4 * 4 + 3]);
	global_load_dwordx4 v[192:195], v224, s[40:41]
	global_load_dwordx4 v[196:199], v224, s[40:41] offset:16
	global_load_dwordx4 v[200:203], v224, s[40:41] offset:32
	global_load_dwordx4 v[204:207], v224, s[40:41] offset:48
	s_waitcnt vmcnt(0)
	v_mul_f32_e32 v160, v112, v160
	v_mul_f32_e32 v161, v113, v161
	v_mul_f32_e32 v162, v114, v162
	v_mul_f32_e32 v163, v115, v163
	v_mul_f32_e32 v164, v116, v164
	v_mul_f32_e32 v165, v117, v165
	v_mul_f32_e32 v166, v118, v166
	v_mul_f32_e32 v167, v119, v167
	v_mul_f32_e32 v168, v120, v168
	v_mul_f32_e32 v169, v121, v169
	v_mul_f32_e32 v170, v122, v170
	v_mul_f32_e32 v171, v123, v171
	v_mul_f32_e32 v172, v124, v172
	v_mul_f32_e32 v173, v125, v173
	v_mul_f32_e32 v174, v126, v174
	v_mul_f32_e32 v175, v127, v175
	v_mul_f32_e32 v176, v128, v176
	v_mul_f32_e32 v177, v129, v177
	v_mul_f32_e32 v178, v130, v178
	v_mul_f32_e32 v179, v131, v179
	v_mul_f32_e32 v180, v132, v180
	v_mul_f32_e32 v181, v133, v181
	v_mul_f32_e32 v182, v134, v182
	v_mul_f32_e32 v183, v135, v183
	v_mul_f32_e32 v184, v136, v184
	v_mul_f32_e32 v185, v137, v185
	v_mul_f32_e32 v186, v138, v186
	v_mul_f32_e32 v187, v139, v187
	v_mul_f32_e32 v188, v140, v188
	v_mul_f32_e32 v189, v141, v189
	v_mul_f32_e32 v190, v142, v190
	v_mul_f32_e32 v191, v143, v191
	v_fma_mix_f32 v160, s15, v192, v160 op_sel_hi:[0,1,0]
	v_fma_mix_f32 v161, s15, v192, v161 op_sel:[0,1,0] op_sel_hi:[0,1,0]
	v_fma_mix_f32 v162, s15, v193, v162 op_sel_hi:[0,1,0]
	v_fma_mix_f32 v163, s15, v193, v163 op_sel:[0,1,0] op_sel_hi:[0,1,0]
	v_fma_mix_f32 v164, s15, v194, v164 op_sel_hi:[0,1,0]
	v_fma_mix_f32 v165, s15, v194, v165 op_sel:[0,1,0] op_sel_hi:[0,1,0]
	v_fma_mix_f32 v166, s15, v195, v166 op_sel_hi:[0,1,0]
	v_fma_mix_f32 v167, s15, v195, v167 op_sel:[0,1,0] op_sel_hi:[0,1,0]
	v_fma_mix_f32 v168, s15, v196, v168 op_sel_hi:[0,1,0]
	v_fma_mix_f32 v169, s15, v196, v169 op_sel:[0,1,0] op_sel_hi:[0,1,0]
	v_fma_mix_f32 v170, s15, v197, v170 op_sel_hi:[0,1,0]
	v_fma_mix_f32 v171, s15, v197, v171 op_sel:[0,1,0] op_sel_hi:[0,1,0]
	v_fma_mix_f32 v172, s15, v198, v172 op_sel_hi:[0,1,0]
	v_fma_mix_f32 v173, s15, v198, v173 op_sel:[0,1,0] op_sel_hi:[0,1,0]
	v_fma_mix_f32 v174, s15, v199, v174 op_sel_hi:[0,1,0]
	v_fma_mix_f32 v175, s15, v199, v175 op_sel:[0,1,0] op_sel_hi:[0,1,0]
	v_fma_mix_f32 v176, s15, v200, v176 op_sel_hi:[0,1,0]
	v_fma_mix_f32 v177, s15, v200, v177 op_sel:[0,1,0] op_sel_hi:[0,1,0]
	v_fma_mix_f32 v178, s15, v201, v178 op_sel_hi:[0,1,0]
	v_fma_mix_f32 v179, s15, v201, v179 op_sel:[0,1,0] op_sel_hi:[0,1,0]
	v_fma_mix_f32 v180, s15, v202, v180 op_sel_hi:[0,1,0]
	v_fma_mix_f32 v181, s15, v202, v181 op_sel:[0,1,0] op_sel_hi:[0,1,0]
	v_fma_mix_f32 v182, s15, v203, v182 op_sel_hi:[0,1,0]
	v_fma_mix_f32 v183, s15, v203, v183 op_sel:[0,1,0] op_sel_hi:[0,1,0]
	v_fma_mix_f32 v184, s15, v204, v184 op_sel_hi:[0,1,0]
	v_fma_mix_f32 v185, s15, v204, v185 op_sel:[0,1,0] op_sel_hi:[0,1,0]
	v_fma_mix_f32 v186, s15, v205, v186 op_sel_hi:[0,1,0]
	v_fma_mix_f32 v187, s15, v205, v187 op_sel:[0,1,0] op_sel_hi:[0,1,0]
	v_fma_mix_f32 v188, s15, v206, v188 op_sel_hi:[0,1,0]
	v_fma_mix_f32 v189, s15, v206, v189 op_sel:[0,1,0] op_sel_hi:[0,1,0]
	v_fma_mix_f32 v190, s15, v207, v190 op_sel_hi:[0,1,0]
	v_fma_mix_f32 v191, s15, v207, v191 op_sel:[0,1,0] op_sel_hi:[0,1,0]
	s_branch .Lap0_res_done
.Lap0_res_ctx:
	s_lshl_b32 s31, s50, 13
	s_add_u32 s26, s4, 0x87c000
	s_addc_u32 s27, s5, 0
	s_add_u32 s26, s26, s31
	s_addc_u32 s27, s27, 0
	global_load_dwordx4 v[192:195], v225, s[26:27]
	global_load_dwordx4 v[196:199], v225, s[26:27] offset:16
	global_load_dwordx4 v[200:203], v225, s[26:27] offset:32
	global_load_dwordx4 v[204:207], v225, s[26:27] offset:48
	global_load_dwordx4 v[208:211], v225, s[26:27] offset:64
	global_load_dwordx4 v[212:215], v225, s[26:27] offset:80
	global_load_dwordx4 v[216:219], v225, s[26:27] offset:96
	global_load_dwordx4 v[220:223], v225, s[26:27] offset:112
	s_waitcnt vmcnt(0)
	v_mul_f32_e32 v160, v112, v160
	v_mul_f32_e32 v161, v113, v161
	v_mul_f32_e32 v162, v114, v162
	v_mul_f32_e32 v163, v115, v163
	v_mul_f32_e32 v164, v116, v164
	v_mul_f32_e32 v165, v117, v165
	v_mul_f32_e32 v166, v118, v166
	v_mul_f32_e32 v167, v119, v167
	v_mul_f32_e32 v168, v120, v168
	v_mul_f32_e32 v169, v121, v169
	v_mul_f32_e32 v170, v122, v170
	v_mul_f32_e32 v171, v123, v171
	v_mul_f32_e32 v172, v124, v172
	v_mul_f32_e32 v173, v125, v173
	v_mul_f32_e32 v174, v126, v174
	v_mul_f32_e32 v175, v127, v175
	v_mul_f32_e32 v176, v128, v176
	v_mul_f32_e32 v177, v129, v177
	v_mul_f32_e32 v178, v130, v178
	v_mul_f32_e32 v179, v131, v179
	v_mul_f32_e32 v180, v132, v180
	v_mul_f32_e32 v181, v133, v181
	v_mul_f32_e32 v182, v134, v182
	v_mul_f32_e32 v183, v135, v183
	v_mul_f32_e32 v184, v136, v184
	v_mul_f32_e32 v185, v137, v185
	v_mul_f32_e32 v186, v138, v186
	v_mul_f32_e32 v187, v139, v187
	v_mul_f32_e32 v188, v140, v188
	v_mul_f32_e32 v189, v141, v189
	v_mul_f32_e32 v190, v142, v190
	v_mul_f32_e32 v191, v143, v191
	v_fmac_f32_e32 v160, s15, v192
	v_fmac_f32_e32 v161, s15, v193
	v_fmac_f32_e32 v162, s15, v194
	v_fmac_f32_e32 v163, s15, v195
	v_fmac_f32_e32 v164, s15, v196
	v_fmac_f32_e32 v165, s15, v197
	v_fmac_f32_e32 v166, s15, v198
	v_fmac_f32_e32 v167, s15, v199
	v_fmac_f32_e32 v168, s15, v200
	v_fmac_f32_e32 v169, s15, v201
	v_fmac_f32_e32 v170, s15, v202
	v_fmac_f32_e32 v171, s15, v203
	v_fmac_f32_e32 v172, s15, v204
	v_fmac_f32_e32 v173, s15, v205
	v_fmac_f32_e32 v174, s15, v206
	v_fmac_f32_e32 v175, s15, v207
	v_fmac_f32_e32 v176, s15, v208
	v_fmac_f32_e32 v177, s15, v209
	v_fmac_f32_e32 v178, s15, v210
	v_fmac_f32_e32 v179, s15, v211
	v_fmac_f32_e32 v180, s15, v212
	v_fmac_f32_e32 v181, s15, v213
	v_fmac_f32_e32 v182, s15, v214
	v_fmac_f32_e32 v183, s15, v215
	v_fmac_f32_e32 v184, s15, v216
	v_fmac_f32_e32 v185, s15, v217
	v_fmac_f32_e32 v186, s15, v218
	v_fmac_f32_e32 v187, s15, v219
	v_fmac_f32_e32 v188, s15, v220
	v_fmac_f32_e32 v189, s15, v221
	v_fmac_f32_e32 v190, s15, v222
	v_fmac_f32_e32 v191, s15, v223
; __device__ __forceinline__ float wave_sum(float v) { v = row_sum16(v); v += __shfl_xor(v, 16); v += __shfl_xor(v, 32); return v; }
; __device__ __forceinline__ void ph_peer_apply(const Params& P, int layer, float* xlat, float* xctx_in, float* xctx_out, int nrows, bool write_next, char* smem, float* xlat_out = nullptr) {
;     ...
;     s = wave_sum(lact ? s : 0.f);
;     const float mu = s / (float)D;
;     float s2 = 0.f;
; #pragma unroll
;     for (int j = 0; j < 32; ++j) { const float dd = o[j] - mu; s2 += dd * dd; }
;     s2 = wave_sum(lact ? s2 : 0.f);
;     const float rstd = rsqrtf(s2 / (float)D + LN_EPS);
;     const float* gp = g + lb * 32; const float* bp = bb + lb * 32;
;     const float* sh1n = mod_ptr(P, 1, row, 0) + lb * 32;
;     const float* sc1n = mod_ptr(P, 1, row, 1) + lb * 32;
;     if (lact) {
; #pragma unroll
;       for (int j4 = 0; j4 < 8; ++j4) {
;         const float4 gv = *(const float4*)(gp + j4 * 4), bv = *(const float4*)(bp + j4 * 4);
.Lap0_res_done:
	v_add_f32_e32 v208, v160, v161
	v_add_f32_e32 v208, v208, v162
	v_add_f32_e32 v208, v208, v163
	v_add_f32_e32 v208, v208, v164
	v_add_f32_e32 v208, v208, v165
	v_add_f32_e32 v208, v208, v166
	v_add_f32_e32 v208, v208, v167
	v_add_f32_e32 v208, v208, v168
	v_add_f32_e32 v208, v208, v169
	v_add_f32_e32 v208, v208, v170
	v_add_f32_e32 v208, v208, v171
	v_add_f32_e32 v208, v208, v172
	v_add_f32_e32 v208, v208, v173
	v_add_f32_e32 v208, v208, v174
	v_add_f32_e32 v208, v208, v175
	v_add_f32_e32 v208, v208, v176
	v_add_f32_e32 v208, v208, v177
	v_add_f32_e32 v208, v208, v178
	v_add_f32_e32 v208, v208, v179
	v_add_f32_e32 v208, v208, v180
	v_add_f32_e32 v208, v208, v181
	v_add_f32_e32 v208, v208, v182
	v_add_f32_e32 v208, v208, v183
	v_add_f32_e32 v208, v208, v184
	v_add_f32_e32 v208, v208, v185
	v_add_f32_e32 v208, v208, v186
	v_add_f32_e32 v208, v208, v187
	v_add_f32_e32 v208, v208, v188
	v_add_f32_e32 v208, v208, v189
	v_add_f32_e32 v208, v208, v190
	v_add_f32_e32 v208, v208, v191
	s_nop 1
	v_add_f32_dpp v208, v208, v208 quad_perm:[1,0,3,2] row_mask:0xf bank_mask:0xf bound_ctrl:1
	s_nop 1
	v_add_f32_dpp v208, v208, v208 quad_perm:[2,3,0,1] row_mask:0xf bank_mask:0xf bound_ctrl:1
	s_nop 1
	v_add_f32_dpp v208, v208, v208 row_ror:4 row_mask:0xf bank_mask:0xf bound_ctrl:1
	s_nop 1
	v_add_f32_dpp v208, v208, v208 row_ror:8 row_mask:0xf bank_mask:0xf bound_ctrl:1
	v_mov_b32_e32 v193, v208
	s_nop 1
	v_permlane32_swap_b32_e32 v193, v208
	v_add_f32_e32 v208, v208, v193
	v_mov_b32_e32 v193, v208
	s_nop 1
	v_permlane16_swap_b32_e32 v193, v208
	v_add_f32_e32 v208, v208, v193
	v_mul_f32_e32 v210, 0x3a000000, v208
	v_sub_f32_e32 v160, v160, v210
	v_sub_f32_e32 v161, v161, v210
	v_sub_f32_e32 v162, v162, v210
	v_sub_f32_e32 v163, v163, v210
	v_sub_f32_e32 v164, v164, v210
	v_sub_f32_e32 v165, v165, v210
	v_sub_f32_e32 v166, v166, v210
	v_sub_f32_e32 v167, v167, v210
	v_sub_f32_e32 v168, v168, v210
	v_sub_f32_e32 v169, v169, v210
	v_sub_f32_e32 v170, v170, v210
	v_sub_f32_e32 v171, v171, v210
	v_sub_f32_e32 v172, v172, v210
	v_sub_f32_e32 v173, v173, v210
	v_sub_f32_e32 v174, v174, v210
	v_sub_f32_e32 v175, v175, v210
	v_sub_f32_e32 v176, v176, v210
	v_sub_f32_e32 v177, v177, v210
	v_sub_f32_e32 v178, v178, v210
	v_sub_f32_e32 v179, v179, v210
	v_sub_f32_e32 v180, v180, v210
	v_sub_f32_e32 v181, v181, v210
	v_sub_f32_e32 v182, v182, v210
	v_sub_f32_e32 v183, v183, v210
	v_sub_f32_e32 v184, v184, v210
	v_sub_f32_e32 v185, v185, v210
	v_sub_f32_e32 v186, v186, v210
	v_sub_f32_e32 v187, v187, v210
	v_sub_f32_e32 v188, v188, v210
	v_sub_f32_e32 v189, v189, v210
	v_sub_f32_e32 v190, v190, v210
	v_sub_f32_e32 v191, v191, v210
	v_mul_f32_e32 v209, v160, v160
	v_fmac_f32_e32 v209, v161, v161
	v_fmac_f32_e32 v209, v162, v162
	v_fmac_f32_e32 v209, v163, v163
	v_fmac_f32_e32 v209, v164, v164
	v_fmac_f32_e32 v209, v165, v165
	v_fmac_f32_e32 v209, v166, v166
	v_fmac_f32_e32 v209, v167, v167
	v_fmac_f32_e32 v209, v168, v168
	v_fmac_f32_e32 v209, v169, v169
	v_fmac_f32_e32 v209, v170, v170
	v_fmac_f32_e32 v209, v171, v171
	v_fmac_f32_e32 v209, v172, v172
	v_fmac_f32_e32 v209, v173, v173
	v_fmac_f32_e32 v209, v174, v174
	v_fmac_f32_e32 v209, v175, v175
	v_fmac_f32_e32 v209, v176, v176
	v_fmac_f32_e32 v209, v177, v177
	v_fmac_f32_e32 v209, v178, v178
	v_fmac_f32_e32 v209, v179, v179
	v_fmac_f32_e32 v209, v180, v180
	v_fmac_f32_e32 v209, v181, v181
	v_fmac_f32_e32 v209, v182, v182
	v_fmac_f32_e32 v209, v183, v183
	v_fmac_f32_e32 v209, v184, v184
	v_fmac_f32_e32 v209, v185, v185
	v_fmac_f32_e32 v209, v186, v186
	v_fmac_f32_e32 v209, v187, v187
	v_fmac_f32_e32 v209, v188, v188
	v_fmac_f32_e32 v209, v189, v189
	v_fmac_f32_e32 v209, v190, v190
	v_fmac_f32_e32 v209, v191, v191
	s_nop 1
	v_add_f32_dpp v209, v209, v209 quad_perm:[1,0,3,2] row_mask:0xf bank_mask:0xf bound_ctrl:1
	s_nop 1
	v_add_f32_dpp v209, v209, v209 quad_perm:[2,3,0,1] row_mask:0xf bank_mask:0xf bound_ctrl:1
	s_nop 1
	v_add_f32_dpp v209, v209, v209 row_ror:4 row_mask:0xf bank_mask:0xf bound_ctrl:1
	s_nop 1
	v_add_f32_dpp v209, v209, v209 row_ror:8 row_mask:0xf bank_mask:0xf bound_ctrl:1
	v_mov_b32_e32 v193, v209
	s_nop 1
	v_permlane32_swap_b32_e32 v193, v209
	v_add_f32_e32 v209, v209, v193
	v_mov_b32_e32 v193, v209
	s_nop 1
	v_permlane16_swap_b32_e32 v193, v209
	v_add_f32_e32 v209, v209, v193
	v_mov_b32_e32 v211, 0x3727c5ac
	v_fmac_f32_e32 v211, 0x3a000000, v209
	v_rsq_f32_e32 v211, v211
	s_add_u32 s26, s8, 0x2000
	s_addc_u32 s27, s9, 0
	global_load_dwordx4 v[112:115], v225, s[26:27]
	global_load_dwordx4 v[116:119], v225, s[26:27] offset:16
	global_load_dwordx4 v[120:123], v225, s[26:27] offset:32
	global_load_dwordx4 v[124:127], v225, s[26:27] offset:48
	global_load_dwordx4 v[128:131], v225, s[26:27] offset:64
	global_load_dwordx4 v[132:135], v225, s[26:27] offset:80
	global_load_dwordx4 v[136:139], v225, s[26:27] offset:96
	global_load_dwordx4 v[140:143], v225, s[26:27] offset:112
	s_add_u32 s26, s10, 0x2000
	s_addc_u32 s27, s11, 0
	global_load_dwordx4 v[192:195], v225, s[26:27]
	global_load_dwordx4 v[196:199], v225, s[26:27] offset:16
	global_load_dwordx4 v[200:203], v225, s[26:27] offset:32
	global_load_dwordx4 v[204:207], v225, s[26:27] offset:48
	s_waitcnt vmcnt(4)
; __device__ __forceinline__ void ph_peer_apply(const Params& P, int layer, float* xlat, float* xctx_in, float* xctx_out, int nrows, bool write_next, char* smem, float* xlat_out = nullptr) {
;     ...
;     if (lact) {
; #pragma unroll
;       for (int j4 = 0; j4 < 8; ++j4) {
;         const float4 gv = *(const float4*)(gp + j4 * 4), bv = *(const float4*)(bp + j4 * 4);
;         float4 ov;
;         ov.x = (o[j4 * 4 + 0] - mu) * rstd * gv.x + bv.x; ov.y = (o[j4 * 4 + 1] - mu) * rstd * gv.y + bv.y;
;         ov.z = (o[j4 * 4 + 2] - mu) * rstd * gv.z + bv.z; ov.w = (o[j4 * 4 + 3] - mu) * rstd * gv.w + bv.w;
;         if (row < NL && write_next) { h16x4 oh_; oh_[0] = (h16)ov.x; oh_[1] = (h16)ov.y; oh_[2] = (h16)ov.z; oh_[3] = (h16)ov.w; *(h16x4*)((h16*)((xlat_out ? xlat_out : xlat) + (size_t)row * D) + lb * 32 + j4 * 4) = oh_; }
;         else *(float4*)(xo + j4 * 4) = ov;
	v_mul_f32_e32 v160, v160, v211
	v_mul_f32_e32 v161, v161, v211
	v_mul_f32_e32 v162, v162, v211
	v_mul_f32_e32 v163, v163, v211
	v_mul_f32_e32 v164, v164, v211
	v_mul_f32_e32 v165, v165, v211
	v_mul_f32_e32 v166, v166, v211
	v_mul_f32_e32 v167, v167, v211
	v_mul_f32_e32 v168, v168, v211
	v_mul_f32_e32 v169, v169, v211
	v_mul_f32_e32 v170, v170, v211
	v_mul_f32_e32 v171, v171, v211
	v_mul_f32_e32 v172, v172, v211
	v_mul_f32_e32 v173, v173, v211
	v_mul_f32_e32 v174, v174, v211
	v_mul_f32_e32 v175, v175, v211
	v_mul_f32_e32 v176, v176, v211
	v_mul_f32_e32 v177, v177, v211
	v_mul_f32_e32 v178, v178, v211
	v_mul_f32_e32 v179, v179, v211
	v_mul_f32_e32 v180, v180, v211
	v_mul_f32_e32 v181, v181, v211
	v_mul_f32_e32 v182, v182, v211
	v_mul_f32_e32 v183, v183, v211
	v_mul_f32_e32 v184, v184, v211
	v_mul_f32_e32 v185, v185, v211
	v_mul_f32_e32 v186, v186, v211
	v_mul_f32_e32 v187, v187, v211
	v_mul_f32_e32 v188, v188, v211
	v_mul_f32_e32 v189, v189, v211
	v_mul_f32_e32 v190, v190, v211
	v_mul_f32_e32 v191, v191, v211
	v_mul_f32_e32 v160, v160, v112
	v_mul_f32_e32 v161, v161, v113
	v_mul_f32_e32 v162, v162, v114
	v_mul_f32_e32 v163, v163, v115
	v_mul_f32_e32 v164, v164, v116
	v_mul_f32_e32 v165, v165, v117
	v_mul_f32_e32 v166, v166, v118
	v_mul_f32_e32 v167, v167, v119
	v_mul_f32_e32 v168, v168, v120
	v_mul_f32_e32 v169, v169, v121
	v_mul_f32_e32 v170, v170, v122
	v_mul_f32_e32 v171, v171, v123
	v_mul_f32_e32 v172, v172, v124
	v_mul_f32_e32 v173, v173, v125
	v_mul_f32_e32 v174, v174, v126
	v_mul_f32_e32 v175, v175, v127
	v_mul_f32_e32 v176, v176, v128
	v_mul_f32_e32 v177, v177, v129
	v_mul_f32_e32 v178, v178, v130
	v_mul_f32_e32 v179, v179, v131
	v_mul_f32_e32 v180, v180, v132
	v_mul_f32_e32 v181, v181, v133
	v_mul_f32_e32 v182, v182, v134
	v_mul_f32_e32 v183, v183, v135
	v_mul_f32_e32 v184, v184, v136
	v_mul_f32_e32 v185, v185, v137
	v_mul_f32_e32 v186, v186, v138
	v_mul_f32_e32 v187, v187, v139
	v_mul_f32_e32 v188, v188, v140
	v_mul_f32_e32 v189, v189, v141
	v_mul_f32_e32 v190, v190, v142
	v_mul_f32_e32 v191, v191, v143
	s_waitcnt vmcnt(0)
	v_add_f32_e32 v160, v160, v192
	v_add_f32_e32 v161, v161, v193
	v_add_f32_e32 v162, v162, v194
	v_add_f32_e32 v163, v163, v195
	v_add_f32_e32 v164, v164, v196
	v_add_f32_e32 v165, v165, v197
	v_add_f32_e32 v166, v166, v198
	v_add_f32_e32 v167, v167, v199
	v_add_f32_e32 v168, v168, v200
	v_add_f32_e32 v169, v169, v201
	v_add_f32_e32 v170, v170, v202
	v_add_f32_e32 v171, v171, v203
	v_add_f32_e32 v172, v172, v204
	v_add_f32_e32 v173, v173, v205
	v_add_f32_e32 v174, v174, v206
	v_add_f32_e32 v175, v175, v207
	global_load_dwordx4 v[192:195], v225, s[26:27] offset:64
	global_load_dwordx4 v[196:199], v225, s[26:27] offset:80
	global_load_dwordx4 v[200:203], v225, s[26:27] offset:96
	global_load_dwordx4 v[204:207], v225, s[26:27] offset:112
	s_waitcnt vmcnt(0)
	v_add_f32_e32 v176, v176, v192
	v_add_f32_e32 v177, v177, v193
	v_add_f32_e32 v178, v178, v194
	v_add_f32_e32 v179, v179, v195
	v_add_f32_e32 v180, v180, v196
	v_add_f32_e32 v181, v181, v197
	v_add_f32_e32 v182, v182, v198
	v_add_f32_e32 v183, v183, v199
	v_add_f32_e32 v184, v184, v200
	v_add_f32_e32 v185, v185, v201
	v_add_f32_e32 v186, v186, v202
	v_add_f32_e32 v187, v187, v203
	v_add_f32_e32 v188, v188, v204
	v_add_f32_e32 v189, v189, v205
	v_add_f32_e32 v190, v190, v206
	v_add_f32_e32 v191, v191, v207
	s_cmp_lg_u32 s48, 0
	s_cbranch_scc1 .Lap0_out_ctx
	v_cvt_pk_f16_f32 v192, v160, v161
	v_cvt_pk_f16_f32 v193, v162, v163
	v_cvt_pk_f16_f32 v194, v164, v165
	v_cvt_pk_f16_f32 v195, v166, v167
	v_cvt_pk_f16_f32 v196, v168, v169
	v_cvt_pk_f16_f32 v197, v170, v171
	v_cvt_pk_f16_f32 v198, v172, v173
	v_cvt_pk_f16_f32 v199, v174, v175
	v_cvt_pk_f16_f32 v200, v176, v177
	v_cvt_pk_f16_f32 v201, v178, v179
	v_cvt_pk_f16_f32 v202, v180, v181
	v_cvt_pk_f16_f32 v203, v182, v183
	v_cvt_pk_f16_f32 v204, v184, v185
	v_cvt_pk_f16_f32 v205, v186, v187
	v_cvt_pk_f16_f32 v206, v188, v189
	v_cvt_pk_f16_f32 v207, v190, v191
	global_store_dwordx4 v224, v[192:195], s[40:41]
	global_store_dwordx4 v224, v[196:199], s[40:41] offset:16
	global_store_dwordx4 v224, v[200:203], s[40:41] offset:32
	global_store_dwordx4 v224, v[204:207], s[40:41] offset:48
	s_branch .Lap0_out_done
.Lap0_out_ctx:
	s_lshl_b32 s31, s50, 13
	s_add_u32 s26, s4, 0xc7c000
	s_addc_u32 s27, s5, 0
	s_add_u32 s26, s26, s31
	s_addc_u32 s27, s27, 0
	global_store_dwordx4 v225, v[160:163], s[26:27]
	global_store_dwordx4 v225, v[164:167], s[26:27] offset:16
	global_store_dwordx4 v225, v[168:171], s[26:27] offset:32
	global_store_dwordx4 v225, v[172:175], s[26:27] offset:48
	global_store_dwordx4 v225, v[176:179], s[26:27] offset:64
	global_store_dwordx4 v225, v[180:183], s[26:27] offset:80
	global_store_dwordx4 v225, v[184:187], s[26:27] offset:96
	global_store_dwordx4 v225, v[188:191], s[26:27] offset:112
; __device__ __forceinline__ void ph_peer_apply(const Params& P, int layer, float* xlat, float* xctx_in, float* xctx_out, int nrows, bool write_next, char* smem, float* xlat_out = nullptr) {
;     ...
;         if (write_next) {
;           const float4 sv = *(const float4*)(sc1n + j4 * 4), hv = *(const float4*)(sh1n + j4 * 4);
;           h16x4 nx;
;           nx[0] = (h16)(ov.x * (1.f + sv.x) + hv.x); nx[1] = (h16)(ov.y * (1.f + sv.y) + hv.y);
;           nx[2] = (h16)(ov.z * (1.f + sv.z) + hv.z); nx[3] = (h16)(ov.w * (1.f + sv.w) + hv.w);
;           *(h16x4*)(xq + (size_t)row * D + lb * 32 + j4 * 4) = nx;
;         }
.Lap0_out_done:
	s_add_u32 s15, s49, 3
	s_mul_i32 s15, s15, 6
	s_lshl_b32 s15, s15, 13
	s_add_u32 s42, s4, 0x4000
	s_addc_u32 s43, s5, 0
	s_add_u32 s42, s42, s15
	s_addc_u32 s43, s43, 0
	s_add_u32 s26, s42, 0x2000
	s_addc_u32 s27, s43, 0
	global_load_dwordx4 v[112:115], v225, s[26:27]
	global_load_dwordx4 v[116:119], v225, s[26:27] offset:16
	global_load_dwordx4 v[120:123], v225, s[26:27] offset:32
	global_load_dwordx4 v[124:127], v225, s[26:27] offset:48
	global_load_dwordx4 v[128:131], v225, s[26:27] offset:64
	global_load_dwordx4 v[132:135], v225, s[26:27] offset:80
	global_load_dwordx4 v[136:139], v225, s[26:27] offset:96
	global_load_dwordx4 v[140:143], v225, s[26:27] offset:112
	global_load_dwordx4 v[192:195], v225, s[42:43]
	global_load_dwordx4 v[196:199], v225, s[42:43] offset:16
	global_load_dwordx4 v[200:203], v225, s[42:43] offset:32
	global_load_dwordx4 v[204:207], v225, s[42:43] offset:48
	global_load_dwordx4 v[208:211], v225, s[42:43] offset:64
	global_load_dwordx4 v[212:215], v225, s[42:43] offset:80
	global_load_dwordx4 v[216:219], v225, s[42:43] offset:96
	global_load_dwordx4 v[220:223], v225, s[42:43] offset:112
	s_lshl_b32 s15, s45, 12
	s_lshr_b32 s31, s45, 20
	s_add_u32 s20, s4, 0xbe4c000
	s_addc_u32 s21, s5, 0
	s_add_u32 s20, s20, s15
	s_addc_u32 s21, s21, s31
	s_waitcnt vmcnt(0)
	v_fma_f32 v160, v160, v112, v160
	v_fma_f32 v161, v161, v113, v161
	v_fma_f32 v162, v162, v114, v162
	v_fma_f32 v163, v163, v115, v163
	v_fma_f32 v164, v164, v116, v164
	v_fma_f32 v165, v165, v117, v165
	v_fma_f32 v166, v166, v118, v166
	v_fma_f32 v167, v167, v119, v167
	v_fma_f32 v168, v168, v120, v168
	v_fma_f32 v169, v169, v121, v169
	v_fma_f32 v170, v170, v122, v170
	v_fma_f32 v171, v171, v123, v171
	v_fma_f32 v172, v172, v124, v172
	v_fma_f32 v173, v173, v125, v173
	v_fma_f32 v174, v174, v126, v174
	v_fma_f32 v175, v175, v127, v175
	v_fma_f32 v176, v176, v128, v176
	v_fma_f32 v177, v177, v129, v177
	v_fma_f32 v178, v178, v130, v178
	v_fma_f32 v179, v179, v131, v179
	v_fma_f32 v180, v180, v132, v180
	v_fma_f32 v181, v181, v133, v181
	v_fma_f32 v182, v182, v134, v182
	v_fma_f32 v183, v183, v135, v183
	v_fma_f32 v184, v184, v136, v184
	v_fma_f32 v185, v185, v137, v185
	v_fma_f32 v186, v186, v138, v186
	v_fma_f32 v187, v187, v139, v187
	v_fma_f32 v188, v188, v140, v188
	v_fma_f32 v189, v189, v141, v189
	v_fma_f32 v190, v190, v142, v190
	v_fma_f32 v191, v191, v143, v191
	v_add_f32_e32 v160, v160, v192
	v_add_f32_e32 v161, v161, v193
	v_add_f32_e32 v162, v162, v194
	v_add_f32_e32 v163, v163, v195
	v_add_f32_e32 v164, v164, v196
	v_add_f32_e32 v165, v165, v197
	v_add_f32_e32 v166, v166, v198
	v_add_f32_e32 v167, v167, v199
	v_add_f32_e32 v168, v168, v200
	v_add_f32_e32 v169, v169, v201
	v_add_f32_e32 v170, v170, v202
	v_add_f32_e32 v171, v171, v203
	v_add_f32_e32 v172, v172, v204
	v_add_f32_e32 v173, v173, v205
	v_add_f32_e32 v174, v174, v206
	v_add_f32_e32 v175, v175, v207
	v_add_f32_e32 v176, v176, v208
	v_add_f32_e32 v177, v177, v209
	v_add_f32_e32 v178, v178, v210
	v_add_f32_e32 v179, v179, v211
	v_add_f32_e32 v180, v180, v212
	v_add_f32_e32 v181, v181, v213
	v_add_f32_e32 v182, v182, v214
	v_add_f32_e32 v183, v183, v215
	v_add_f32_e32 v184, v184, v216
	v_add_f32_e32 v185, v185, v217
	v_add_f32_e32 v186, v186, v218
	v_add_f32_e32 v187, v187, v219
	v_add_f32_e32 v188, v188, v220
	v_add_f32_e32 v189, v189, v221
	v_add_f32_e32 v190, v190, v222
	v_add_f32_e32 v191, v191, v223
	v_cvt_pk_f16_f32 v192, v160, v161
	v_cvt_pk_f16_f32 v193, v162, v163
	v_cvt_pk_f16_f32 v194, v164, v165
	v_cvt_pk_f16_f32 v195, v166, v167
	v_cvt_pk_f16_f32 v196, v168, v169
	v_cvt_pk_f16_f32 v197, v170, v171
	v_cvt_pk_f16_f32 v198, v172, v173
	v_cvt_pk_f16_f32 v199, v174, v175
	v_cvt_pk_f16_f32 v200, v176, v177
	v_cvt_pk_f16_f32 v201, v178, v179
	v_cvt_pk_f16_f32 v202, v180, v181
	v_cvt_pk_f16_f32 v203, v182, v183
	v_cvt_pk_f16_f32 v204, v184, v185
	v_cvt_pk_f16_f32 v205, v186, v187
	v_cvt_pk_f16_f32 v206, v188, v189
	v_cvt_pk_f16_f32 v207, v190, v191
	global_store_dwordx4 v224, v[192:195], s[20:21]
	global_store_dwordx4 v224, v[196:199], s[20:21] offset:16
	global_store_dwordx4 v224, v[200:203], s[20:21] offset:32
	global_store_dwordx4 v224, v[204:207], s[20:21] offset:48
	s_add_u32 s14, s14, 1
	s_add_u32 s45, s45, s44
	s_branch .Lap0_s2_tok
.Lap0_done:
.LBB0_2078:
	s_or_b64 exec, exec, s[16:17]
	s_waitcnt vmcnt(0)
	s_barrier
	s_mov_b64 s[6:7], exec
	v_readlane_b32 s0, v254, 0
	v_readlane_b32 s1, v254, 1
	s_and_b64 s[0:1], s[6:7], s[0:1]
	s_mov_b64 exec, s[0:1]
	s_cbranch_execz .LBB0_2130
	s_add_i32 s0, 0, 0x20200
	v_mov_b32_e32 v1, s0
	s_waitcnt vmcnt(0) expcnt(0) lgkmcnt(0)
	ds_read_b32 v3, v1
	s_add_i32 s0, 0, 0x20204
	v_mov_b32_e32 v1, s0
	ds_read_b32 v1, v1
	s_waitcnt lgkmcnt(1)
	v_cmp_ne_u32_e32 vcc, 0, v3
	s_cbranch_vccnz .LBB0_2094
	v_readlane_b32 s4, v254, 5
	v_readlane_b32 s5, v254, 6
	s_add_u32 s8, s78, 0x1000
	s_load_dwordx2 s[0:1], s[4:5], 0x4
	s_addc_u32 s9, s79, 0
	s_add_u32 s10, s78, 0x1100
	s_addc_u32 s11, s79, 0
	s_add_u32 s12, s78, 0x1200
	s_addc_u32 s13, s79, 0
	s_waitcnt lgkmcnt(0)
	s_mul_i32 s0, s0, s84
	s_add_u32 s14, s78, 0x1300
	s_mul_i32 s0, s0, s1
	s_addc_u32 s15, s79, 0
	s_mov_b32 s1, 1
	v_mov_b32_e32 v17, 0
	s_branch .LBB0_2082

; #define TIDX tid_fn()
; __device__ __forceinline__ void ph_peer_apply(const Params& P, int layer, float* xlat, float* xctx_in, float* xctx_out, int nrows, bool write_next, char* smem, float* xlat_out = nullptr) {
;   (void)smem;
;   h16* xq = (h16*)(P.ws + O_ABUF);
;   const unsigned char* tu = (const unsigned char*)(P.ws + O_TABU);
;   const unsigned char* tv = (const unsigned char*)(P.ws + O_TABV);
;   const int* seli = (const int*)(P.ws + O_SELI);
;   const float* selg = (const float*)(P.ws + O_SELG);
;   const float* g = P.ln_g + (size_t)(layer * 2 + 1) * D;
;   const float* bb = P.ln_b + (size_t)(layer * 2 + 1) * D;
;   const int tid = TIDX, wave = tid >> 6, lane = tid & 63;
;   const bool lact = lane < P6_NB;
;   const int lb = lact ? lane : 0;
;   for (int row = blockIdx.x * (NTHR / 64) + wave; row < nrows; row += gridDim.x * (NTHR / 64)) {
;     float xv[32];
; #pragma unroll
;     for (int j8 = 0; j8 < 4; ++j8) {
;       const h16x8 t = *(const h16x8*)(xq + (size_t)row * D + lb * 32 + j8 * 8);
; #pragma unroll
;       for (int j = 0; j < 8; ++j) xv[j8 * 8 + j] = lact ? (float)t[j] : 0.f;
;     }
;     const int id0 = seli[(size_t)row * NSEL + lane], id1 = seli[(size_t)row * NSEL + 64 + lane];
;     const float g0 = selg[(size_t)row * NSEL + lane], g1 = selg[(size_t)row * NSEL + 64 + lane];
.LBB0_3667:
	s_or_b64 exec, exec, s[2:3]
	s_waitcnt lgkmcnt(0)
	s_barrier
	s_load_dwordx4 s[4:7], s[96:97], 0x170
	s_load_dwordx4 s[8:11], s[96:97], 0x30
	v_readfirstlane_b32 s12, v0
	s_lshr_b32 s12, s12, 6
	v_and_b32_e32 v1, 63, v0
	v_mul_u32_u24_e32 v2, 24, v1
	v_add_u32_e32 v3, 0x600, v1
	v_lshlrev_b32_e32 v224, 6, v1
	v_lshlrev_b32_e32 v225, 7, v1
	v_lshlrev_b32_e32 v226, 2, v1
	v_lshrrev_b32_e32 v192, 2, v1
	v_and_b32_e32 v193, 1, v1
	v_lshl_add_u32 v192, v192, 1, v193
	v_lshlrev_b32_e32 v227, 2, v192
	s_mul_i32 s15, s12, 0x2800
	v_add_u32_e32 v228, s15, v226
	v_add_u32_e32 v227, s15, v227
	s_mov_b32 s46, 0x3333
	s_mov_b32 s47, 0
	s_mov_b32 s34, 0x22222222
	s_mov_b32 s35, 0x22222222
	s_waitcnt lgkmcnt(0)
	s_mov_b64 s[40:41], s[4:5]
	s_mov_b64 s[4:5], s[6:7]
	s_mov_b64 s[6:7], s[40:41]
	s_add_u32 s16, s4, 0x3c7c000
	s_addc_u32 s17, s5, 0
	s_add_u32 s18, s4, 0x7c7c000
	s_addc_u32 s19, s5, 0
	s_add_u32 s13, s60, s12
	s_lshl_b32 s44, s84, 3
	s_mov_b32 s14, 0
	s_mov_b32 s45, s13
.Lap1_s1_tok:
	s_cmp_ge_u32 s45, 0x8000
	s_cbranch_scc1 .Lap1_s1_done
	s_lshl_b32 s15, s45, 12
	s_lshr_b32 s31, s45, 20
	s_add_u32 s20, s4, 0xbe4c000
	s_addc_u32 s21, s5, 0
	s_add_u32 s20, s20, s15
	s_addc_u32 s21, s21, s31
	s_lshl_b32 s15, s45, 9
	s_add_u32 s22, s4, 0x1404c000
	s_addc_u32 s23, s5, 0
	s_add_u32 s22, s22, s15
	s_addc_u32 s23, s23, 0
	s_add_u32 s24, s4, 0x1508c000
	s_addc_u32 s25, s5, 0
	s_add_u32 s24, s24, s15
	s_addc_u32 s25, s25, 0
	global_load_dwordx4 v[4:7], v224, s[20:21]
	global_load_dwordx4 v[8:11], v224, s[20:21] offset:16
	global_load_dwordx4 v[12:15], v224, s[20:21] offset:32
	global_load_dwordx4 v[16:19], v224, s[20:21] offset:48
	global_load_dword v36, v226, s[22:23]
	global_load_dword v37, v226, s[22:23] offset:256
	global_load_dword v40, v226, s[24:25]
	global_load_dword v41, v226, s[24:25] offset:256
	s_lshl_b32 s15, s14, 9
	v_add_u32_e32 v229, s15, v227
	s_waitcnt vmcnt(0)
	s_mov_b32 s28, 0
	v_readlane_b32 s29, v36, s28
	s_add_u32 s28, s28, 1
	s_mul_hi_u32 s27, s29, 0x640
	s_mul_i32 s26, s29, 0x640
	s_add_u32 s26, s16, s26
	s_addc_u32 s27, s17, s27
	global_load_dwordx4 v[48:51], v2, s[26:27]
	global_load_dwordx2 v[52:53], v2, s[26:27] offset:16
	global_load_ubyte v54, v3, s[26:27]
	v_readlane_b32 s29, v36, s28
	s_add_u32 s28, s28, 1
	s_mul_hi_u32 s27, s29, 0x640
	s_mul_i32 s26, s29, 0x640
	s_add_u32 s26, s16, s26
	s_addc_u32 s27, s17, s27
	global_load_dwordx4 v[56:59], v2, s[26:27]
	global_load_dwordx2 v[60:61], v2, s[26:27] offset:16
	global_load_ubyte v62, v3, s[26:27]
	v_readlane_b32 s29, v36, s28
	s_add_u32 s28, s28, 1
	s_mul_hi_u32 s27, s29, 0x640
	s_mul_i32 s26, s29, 0x640
	s_add_u32 s26, s16, s26
	s_addc_u32 s27, s17, s27
	global_load_dwordx4 v[64:67], v2, s[26:27]
	global_load_dwordx2 v[68:69], v2, s[26:27] offset:16
	global_load_ubyte v70, v3, s[26:27]
	v_readlane_b32 s29, v36, s28
	s_add_u32 s28, s28, 1
	s_mul_hi_u32 s27, s29, 0x640
	s_mul_i32 s26, s29, 0x640
	s_add_u32 s26, s16, s26
	s_addc_u32 s27, s17, s27
	global_load_dwordx4 v[72:75], v2, s[26:27]
	global_load_dwordx2 v[76:77], v2, s[26:27] offset:16
	global_load_ubyte v78, v3, s[26:27]
	v_readlane_b32 s29, v36, s28
	s_add_u32 s28, s28, 1
	s_mul_hi_u32 s27, s29, 0x640
	s_mul_i32 s26, s29, 0x640
	s_add_u32 s26, s16, s26
	s_addc_u32 s27, s17, s27
	global_load_dwordx4 v[80:83], v2, s[26:27]
	global_load_dwordx2 v[84:85], v2, s[26:27] offset:16
	global_load_ubyte v86, v3, s[26:27]
	v_readlane_b32 s29, v36, s28
	s_add_u32 s28, s28, 1
	s_mul_hi_u32 s27, s29, 0x640
	s_mul_i32 s26, s29, 0x640
	s_add_u32 s26, s16, s26
	s_addc_u32 s27, s17, s27
	global_load_dwordx4 v[88:91], v2, s[26:27]
	global_load_dwordx2 v[92:93], v2, s[26:27] offset:16
	global_load_ubyte v94, v3, s[26:27]
	v_readlane_b32 s29, v36, s28
	s_add_u32 s28, s28, 1
	s_mul_hi_u32 s27, s29, 0x640
	s_mul_i32 s26, s29, 0x640
	s_add_u32 s26, s16, s26
	s_addc_u32 s27, s17, s27
	global_load_dwordx4 v[96:99], v2, s[26:27]
	global_load_dwordx2 v[100:101], v2, s[26:27] offset:16
	global_load_ubyte v102, v3, s[26:27]
	v_readlane_b32 s29, v36, s28
	s_add_u32 s28, s28, 1
	s_mul_hi_u32 s27, s29, 0x640
	s_mul_i32 s26, s29, 0x640
	s_add_u32 s26, s16, s26
	s_addc_u32 s27, s17, s27
	global_load_dwordx4 v[104:107], v2, s[26:27]
	global_load_dwordx2 v[108:109], v2, s[26:27] offset:16
	global_load_ubyte v110, v3, s[26:27]
	s_mov_b32 s30, 7

; #define PB_FENCE asm volatile("" ::: "memory")
; __device__ __forceinline__ void ph_peer_apply(const Params& P, int layer, float* xlat, float* xctx_in, float* xctx_out, int nrows, bool write_next, char* smem, float* xlat_out = nullptr) {
;     ...
;     float o[32];
; #pragma unroll
;     for (int j = 0; j < 32; ++j) o[j] = 0.f;
;     ...
;     PB_LOAD(bufA, tv, 0);
;     for (int gq = 0; gq < NG; gq += 2) {
;       PB_LOAD(bufB, tv, gq + 1); PB_FENCE;
;       PB_ACC(bufA, gq);
;       if (gq + 2 < NG) PB_LOAD(bufA, tv, gq + 2);
;       PB_FENCE;
;       PB_ACC(bufB, gq + 1);
;     }
.Lap1_s2_tok:
	s_cmp_ge_u32 s45, 0x8000
	s_cbranch_scc1 .Lap1_done
	s_lshl_b32 s15, s45, 9
	s_add_u32 s22, s4, 0x1404c000
	s_addc_u32 s23, s5, 0
	s_add_u32 s22, s22, s15
	s_addc_u32 s23, s23, 0
	global_load_dword v36, v226, s[22:23]
	global_load_dword v37, v226, s[22:23] offset:256
	s_lshl_b32 s15, s14, 9
	v_add_u32_e32 v194, s15, v228
	s_waitcnt lgkmcnt(0)
	ds_read_b32 v42, v194
	ds_read_b32 v43, v194 offset:256
	v_mov_b32_e32 v160, 0
	v_mov_b32_e32 v161, 0
	v_mov_b32_e32 v162, 0
	v_mov_b32_e32 v163, 0
	v_mov_b32_e32 v164, 0
	v_mov_b32_e32 v165, 0
	v_mov_b32_e32 v166, 0
	v_mov_b32_e32 v167, 0
	v_mov_b32_e32 v168, 0
	v_mov_b32_e32 v169, 0
	v_mov_b32_e32 v170, 0
	v_mov_b32_e32 v171, 0
	v_mov_b32_e32 v172, 0
	v_mov_b32_e32 v173, 0
	v_mov_b32_e32 v174, 0
	v_mov_b32_e32 v175, 0
	v_mov_b32_e32 v176, 0
	v_mov_b32_e32 v177, 0
	v_mov_b32_e32 v178, 0
	v_mov_b32_e32 v179, 0
	v_mov_b32_e32 v180, 0
	v_mov_b32_e32 v181, 0
	v_mov_b32_e32 v182, 0
	v_mov_b32_e32 v183, 0
	v_mov_b32_e32 v184, 0
	v_mov_b32_e32 v185, 0
	v_mov_b32_e32 v186, 0
	v_mov_b32_e32 v187, 0
	v_mov_b32_e32 v188, 0
	v_mov_b32_e32 v189, 0
	v_mov_b32_e32 v190, 0
	v_mov_b32_e32 v191, 0
	s_waitcnt vmcnt(0) lgkmcnt(0)
	s_mov_b32 s28, 0
	s_mov_b32 s37, 0
	v_readlane_b32 s29, v36, s28
	s_add_u32 s28, s28, 1
	s_mul_hi_u32 s27, s29, 0x640
	s_mul_i32 s26, s29, 0x640
	s_add_u32 s26, s18, s26
	s_addc_u32 s27, s19, s27
	global_load_dwordx4 v[48:51], v2, s[26:27]
	global_load_dwordx2 v[52:53], v2, s[26:27] offset:16
	global_load_ubyte v54, v3, s[26:27]
	v_readlane_b32 s29, v36, s28
	s_add_u32 s28, s28, 1
	s_mul_hi_u32 s27, s29, 0x640
	s_mul_i32 s26, s29, 0x640
	s_add_u32 s26, s18, s26
	s_addc_u32 s27, s19, s27
	global_load_dwordx4 v[56:59], v2, s[26:27]
	global_load_dwordx2 v[60:61], v2, s[26:27] offset:16
	global_load_ubyte v62, v3, s[26:27]
	v_readlane_b32 s29, v36, s28
	s_add_u32 s28, s28, 1
	s_mul_hi_u32 s27, s29, 0x640
	s_mul_i32 s26, s29, 0x640
	s_add_u32 s26, s18, s26
	s_addc_u32 s27, s19, s27
	global_load_dwordx4 v[64:67], v2, s[26:27]
	global_load_dwordx2 v[68:69], v2, s[26:27] offset:16
	global_load_ubyte v70, v3, s[26:27]
	v_readlane_b32 s29, v36, s28
	s_add_u32 s28, s28, 1
	s_mul_hi_u32 s27, s29, 0x640
	s_mul_i32 s26, s29, 0x640
	s_add_u32 s26, s18, s26
	s_addc_u32 s27, s19, s27
	global_load_dwordx4 v[72:75], v2, s[26:27]
	global_load_dwordx2 v[76:77], v2, s[26:27] offset:16
	global_load_ubyte v78, v3, s[26:27]
	v_readlane_b32 s29, v36, s28
	s_add_u32 s28, s28, 1
	s_mul_hi_u32 s27, s29, 0x640
	s_mul_i32 s26, s29, 0x640
	s_add_u32 s26, s18, s26
	s_addc_u32 s27, s19, s27
	global_load_dwordx4 v[80:83], v2, s[26:27]
	global_load_dwordx2 v[84:85], v2, s[26:27] offset:16
	global_load_ubyte v86, v3, s[26:27]
	v_readlane_b32 s29, v36, s28
	s_add_u32 s28, s28, 1
	s_mul_hi_u32 s27, s29, 0x640
	s_mul_i32 s26, s29, 0x640
	s_add_u32 s26, s18, s26
	s_addc_u32 s27, s19, s27
	global_load_dwordx4 v[88:91], v2, s[26:27]
	global_load_dwordx2 v[92:93], v2, s[26:27] offset:16
	global_load_ubyte v94, v3, s[26:27]
	v_readlane_b32 s29, v36, s28
	s_add_u32 s28, s28, 1
	s_mul_hi_u32 s27, s29, 0x640
	s_mul_i32 s26, s29, 0x640
	s_add_u32 s26, s18, s26
	s_addc_u32 s27, s19, s27
	global_load_dwordx4 v[96:99], v2, s[26:27]
	global_load_dwordx2 v[100:101], v2, s[26:27] offset:16
	global_load_ubyte v102, v3, s[26:27]
	v_readlane_b32 s29, v36, s28
	s_add_u32 s28, s28, 1
	s_mul_hi_u32 s27, s29, 0x640
	s_mul_i32 s26, s29, 0x640
	s_add_u32 s26, s18, s26
	s_addc_u32 s27, s19, s27
	global_load_dwordx4 v[104:107], v2, s[26:27]
	global_load_dwordx2 v[108:109], v2, s[26:27] offset:16
	global_load_ubyte v110, v3, s[26:27]
	s_mov_b32 s30, 7

; #define PB_FENCE asm volatile("" ::: "memory")
; __device__ __forceinline__ void ph_peer_apply(const Params& P, int layer, float* xlat, float* xctx_in, float* xctx_out, int nrows, bool write_next, char* smem, float* xlat_out = nullptr) {
;     ...
;     PB_LOAD(bufA, tv, 0);
;     for (int gq = 0; gq < NG; gq += 2) {
;       PB_LOAD(bufB, tv, gq + 1); PB_FENCE;
;       PB_ACC(bufA, gq);
;       if (gq + 2 < NG) PB_LOAD(bufA, tv, gq + 2);
;       PB_FENCE;
;       PB_ACC(bufB, gq + 1);
;     }
.Lap1_s2_loop4:
	v_readlane_b32 s36, v43, s37
	s_add_u32 s37, s37, 1
	s_waitcnt vmcnt(21)
	v_lshlrev_b32_e32 v192, 23, v54
	v_cvt_scalef32_pk32_f32_fp6 v[112:143], v[48:53], v192
	v_fmac_f32_e32 v160, s36, v112
	v_fmac_f32_e32 v161, s36, v113
	v_fmac_f32_e32 v162, s36, v114
	v_fmac_f32_e32 v163, s36, v115
	v_fmac_f32_e32 v164, s36, v116
	v_fmac_f32_e32 v165, s36, v117
	v_fmac_f32_e32 v166, s36, v118
	v_fmac_f32_e32 v167, s36, v119
	v_fmac_f32_e32 v168, s36, v120
	v_fmac_f32_e32 v169, s36, v121
	v_fmac_f32_e32 v170, s36, v122
	v_fmac_f32_e32 v171, s36, v123
	v_fmac_f32_e32 v172, s36, v124
	v_fmac_f32_e32 v173, s36, v125
	v_fmac_f32_e32 v174, s36, v126
	v_fmac_f32_e32 v175, s36, v127
	v_fmac_f32_e32 v176, s36, v128
	v_fmac_f32_e32 v177, s36, v129
	v_fmac_f32_e32 v178, s36, v130
	v_fmac_f32_e32 v179, s36, v131
	v_fmac_f32_e32 v180, s36, v132
	v_fmac_f32_e32 v181, s36, v133
	v_fmac_f32_e32 v182, s36, v134
	v_fmac_f32_e32 v183, s36, v135
	v_fmac_f32_e32 v184, s36, v136
	v_fmac_f32_e32 v185, s36, v137
	v_fmac_f32_e32 v186, s36, v138
	v_fmac_f32_e32 v187, s36, v139
	v_fmac_f32_e32 v188, s36, v140
	v_fmac_f32_e32 v189, s36, v141
	v_fmac_f32_e32 v190, s36, v142
	v_fmac_f32_e32 v191, s36, v143
	v_readlane_b32 s29, v37, s28
	s_add_u32 s28, s28, 1
	s_mul_hi_u32 s27, s29, 0x640
	s_mul_i32 s26, s29, 0x640
	s_add_u32 s26, s18, s26
	s_addc_u32 s27, s19, s27
	global_load_dwordx4 v[48:51], v2, s[26:27]
	global_load_dwordx2 v[52:53], v2, s[26:27] offset:16
	global_load_ubyte v54, v3, s[26:27]
	v_readlane_b32 s36, v43, s37
	s_add_u32 s37, s37, 1
	s_waitcnt vmcnt(21)
	v_lshlrev_b32_e32 v192, 23, v62
	v_cvt_scalef32_pk32_f32_fp6 v[112:143], v[56:61], v192
	v_fmac_f32_e32 v160, s36, v112
	v_fmac_f32_e32 v161, s36, v113
	v_fmac_f32_e32 v162, s36, v114
	v_fmac_f32_e32 v163, s36, v115
	v_fmac_f32_e32 v164, s36, v116
	v_fmac_f32_e32 v165, s36, v117
	v_fmac_f32_e32 v166, s36, v118
	v_fmac_f32_e32 v167, s36, v119
	v_fmac_f32_e32 v168, s36, v120
	v_fmac_f32_e32 v169, s36, v121
	v_fmac_f32_e32 v170, s36, v122
	v_fmac_f32_e32 v171, s36, v123
	v_fmac_f32_e32 v172, s36, v124
	v_fmac_f32_e32 v173, s36, v125
	v_fmac_f32_e32 v174, s36, v126
	v_fmac_f32_e32 v175, s36, v127
	v_fmac_f32_e32 v176, s36, v128
	v_fmac_f32_e32 v177, s36, v129
	v_fmac_f32_e32 v178, s36, v130
	v_fmac_f32_e32 v179, s36, v131
	v_fmac_f32_e32 v180, s36, v132
	v_fmac_f32_e32 v181, s36, v133
	v_fmac_f32_e32 v182, s36, v134
	v_fmac_f32_e32 v183, s36, v135
	v_fmac_f32_e32 v184, s36, v136
	v_fmac_f32_e32 v185, s36, v137
	v_fmac_f32_e32 v186, s36, v138
	v_fmac_f32_e32 v187, s36, v139
	v_fmac_f32_e32 v188, s36, v140
	v_fmac_f32_e32 v189, s36, v141
	v_fmac_f32_e32 v190, s36, v142
	v_fmac_f32_e32 v191, s36, v143
	v_readlane_b32 s29, v37, s28
	s_add_u32 s28, s28, 1
	s_mul_hi_u32 s27, s29, 0x640
	s_mul_i32 s26, s29, 0x640
	s_add_u32 s26, s18, s26
	s_addc_u32 s27, s19, s27
	global_load_dwordx4 v[56:59], v2, s[26:27]
	global_load_dwordx2 v[60:61], v2, s[26:27] offset:16
	global_load_ubyte v62, v3, s[26:27]
	v_readlane_b32 s36, v43, s37
	s_add_u32 s37, s37, 1
	s_waitcnt vmcnt(21)
	v_lshlrev_b32_e32 v192, 23, v70
	v_cvt_scalef32_pk32_f32_fp6 v[112:143], v[64:69], v192
	v_fmac_f32_e32 v160, s36, v112
	v_fmac_f32_e32 v161, s36, v113
	v_fmac_f32_e32 v162, s36, v114
	v_fmac_f32_e32 v163, s36, v115
	v_fmac_f32_e32 v164, s36, v116
	v_fmac_f32_e32 v165, s36, v117
	v_fmac_f32_e32 v166, s36, v118
	v_fmac_f32_e32 v167, s36, v119
	v_fmac_f32_e32 v168, s36, v120
	v_fmac_f32_e32 v169, s36, v121
	v_fmac_f32_e32 v170, s36, v122
	v_fmac_f32_e32 v171, s36, v123
	v_fmac_f32_e32 v172, s36, v124
	v_fmac_f32_e32 v173, s36, v125
	v_fmac_f32_e32 v174, s36, v126
	v_fmac_f32_e32 v175, s36, v127
	v_fmac_f32_e32 v176, s36, v128
	v_fmac_f32_e32 v177, s36, v129
	v_fmac_f32_e32 v178, s36, v130
	v_fmac_f32_e32 v179, s36, v131
	v_fmac_f32_e32 v180, s36, v132
	v_fmac_f32_e32 v181, s36, v133
	v_fmac_f32_e32 v182, s36, v134
	v_fmac_f32_e32 v183, s36, v135
	v_fmac_f32_e32 v184, s36, v136
	v_fmac_f32_e32 v185, s36, v137
	v_fmac_f32_e32 v186, s36, v138
	v_fmac_f32_e32 v187, s36, v139
	v_fmac_f32_e32 v188, s36, v140
	v_fmac_f32_e32 v189, s36, v141
	v_fmac_f32_e32 v190, s36, v142
	v_fmac_f32_e32 v191, s36, v143
	v_readlane_b32 s29, v37, s28
	s_add_u32 s28, s28, 1
	s_mul_hi_u32 s27, s29, 0x640
	s_mul_i32 s26, s29, 0x640
	s_add_u32 s26, s18, s26
	s_addc_u32 s27, s19, s27
	global_load_dwordx4 v[64:67], v2, s[26:27]
	global_load_dwordx2 v[68:69], v2, s[26:27] offset:16
	global_load_ubyte v70, v3, s[26:27]
	v_readlane_b32 s36, v43, s37
	s_add_u32 s37, s37, 1
	s_waitcnt vmcnt(21)
	v_lshlrev_b32_e32 v192, 23, v78
	v_cvt_scalef32_pk32_f32_fp6 v[112:143], v[72:77], v192
	v_fmac_f32_e32 v160, s36, v112
	v_fmac_f32_e32 v161, s36, v113
	v_fmac_f32_e32 v162, s36, v114
	v_fmac_f32_e32 v163, s36, v115
	v_fmac_f32_e32 v164, s36, v116
	v_fmac_f32_e32 v165, s36, v117
	v_fmac_f32_e32 v166, s36, v118
	v_fmac_f32_e32 v167, s36, v119
	v_fmac_f32_e32 v168, s36, v120
	v_fmac_f32_e32 v169, s36, v121
	v_fmac_f32_e32 v170, s36, v122
	v_fmac_f32_e32 v171, s36, v123
	v_fmac_f32_e32 v172, s36, v124
	v_fmac_f32_e32 v173, s36, v125
	v_fmac_f32_e32 v174, s36, v126
	v_fmac_f32_e32 v175, s36, v127
	v_fmac_f32_e32 v176, s36, v128
	v_fmac_f32_e32 v177, s36, v129
	v_fmac_f32_e32 v178, s36, v130
	v_fmac_f32_e32 v179, s36, v131
	v_fmac_f32_e32 v180, s36, v132
	v_fmac_f32_e32 v181, s36, v133
	v_fmac_f32_e32 v182, s36, v134
	v_fmac_f32_e32 v183, s36, v135
	v_fmac_f32_e32 v184, s36, v136
	v_fmac_f32_e32 v185, s36, v137
	v_fmac_f32_e32 v186, s36, v138
	v_fmac_f32_e32 v187, s36, v139
	v_fmac_f32_e32 v188, s36, v140
	v_fmac_f32_e32 v189, s36, v141
	v_fmac_f32_e32 v190, s36, v142
	v_fmac_f32_e32 v191, s36, v143
	v_readlane_b32 s29, v37, s28
	s_add_u32 s28, s28, 1
	s_mul_hi_u32 s27, s29, 0x640
	s_mul_i32 s26, s29, 0x640
	s_add_u32 s26, s18, s26
	s_addc_u32 s27, s19, s27
	global_load_dwordx4 v[72:75], v2, s[26:27]
	global_load_dwordx2 v[76:77], v2, s[26:27] offset:16
	global_load_ubyte v78, v3, s[26:27]
	v_readlane_b32 s36, v43, s37
	s_add_u32 s37, s37, 1
	s_waitcnt vmcnt(21)
; #define PB_FENCE asm volatile("" ::: "memory")
; __device__ __forceinline__ void ph_peer_apply(const Params& P, int layer, float* xlat, float* xctx_in, float* xctx_out, int nrows, bool write_next, char* smem, float* xlat_out = nullptr) {
;     ...
;     PB_LOAD(bufA, tv, 0);
;     for (int gq = 0; gq < NG; gq += 2) {
;       PB_LOAD(bufB, tv, gq + 1); PB_FENCE;
;       PB_ACC(bufA, gq);
;       if (gq + 2 < NG) PB_LOAD(bufA, tv, gq + 2);
;       PB_FENCE;
;       PB_ACC(bufB, gq + 1);
;     }
	v_lshlrev_b32_e32 v192, 23, v86
	v_cvt_scalef32_pk32_f32_fp6 v[112:143], v[80:85], v192
	v_fmac_f32_e32 v160, s36, v112
	v_fmac_f32_e32 v161, s36, v113
	v_fmac_f32_e32 v162, s36, v114
	v_fmac_f32_e32 v163, s36, v115
	v_fmac_f32_e32 v164, s36, v116
	v_fmac_f32_e32 v165, s36, v117
	v_fmac_f32_e32 v166, s36, v118
	v_fmac_f32_e32 v167, s36, v119
	v_fmac_f32_e32 v168, s36, v120
	v_fmac_f32_e32 v169, s36, v121
	v_fmac_f32_e32 v170, s36, v122
	v_fmac_f32_e32 v171, s36, v123
	v_fmac_f32_e32 v172, s36, v124
	v_fmac_f32_e32 v173, s36, v125
	v_fmac_f32_e32 v174, s36, v126
	v_fmac_f32_e32 v175, s36, v127
	v_fmac_f32_e32 v176, s36, v128
	v_fmac_f32_e32 v177, s36, v129
	v_fmac_f32_e32 v178, s36, v130
	v_fmac_f32_e32 v179, s36, v131
	v_fmac_f32_e32 v180, s36, v132
	v_fmac_f32_e32 v181, s36, v133
	v_fmac_f32_e32 v182, s36, v134
	v_fmac_f32_e32 v183, s36, v135
	v_fmac_f32_e32 v184, s36, v136
	v_fmac_f32_e32 v185, s36, v137
	v_fmac_f32_e32 v186, s36, v138
	v_fmac_f32_e32 v187, s36, v139
	v_fmac_f32_e32 v188, s36, v140
	v_fmac_f32_e32 v189, s36, v141
	v_fmac_f32_e32 v190, s36, v142
	v_fmac_f32_e32 v191, s36, v143
	v_readlane_b32 s29, v37, s28
	s_add_u32 s28, s28, 1
	s_mul_hi_u32 s27, s29, 0x640
	s_mul_i32 s26, s29, 0x640
	s_add_u32 s26, s18, s26
	s_addc_u32 s27, s19, s27
	global_load_dwordx4 v[80:83], v2, s[26:27]
	global_load_dwordx2 v[84:85], v2, s[26:27] offset:16
	global_load_ubyte v86, v3, s[26:27]
	v_readlane_b32 s36, v43, s37
	s_add_u32 s37, s37, 1
	s_waitcnt vmcnt(21)
	v_lshlrev_b32_e32 v192, 23, v94
	v_cvt_scalef32_pk32_f32_fp6 v[112:143], v[88:93], v192
	v_fmac_f32_e32 v160, s36, v112
	v_fmac_f32_e32 v161, s36, v113
	v_fmac_f32_e32 v162, s36, v114
	v_fmac_f32_e32 v163, s36, v115
	v_fmac_f32_e32 v164, s36, v116
	v_fmac_f32_e32 v165, s36, v117
	v_fmac_f32_e32 v166, s36, v118
	v_fmac_f32_e32 v167, s36, v119
	v_fmac_f32_e32 v168, s36, v120
	v_fmac_f32_e32 v169, s36, v121
	v_fmac_f32_e32 v170, s36, v122
	v_fmac_f32_e32 v171, s36, v123
	v_fmac_f32_e32 v172, s36, v124
	v_fmac_f32_e32 v173, s36, v125
	v_fmac_f32_e32 v174, s36, v126
	v_fmac_f32_e32 v175, s36, v127
	v_fmac_f32_e32 v176, s36, v128
	v_fmac_f32_e32 v177, s36, v129
	v_fmac_f32_e32 v178, s36, v130
	v_fmac_f32_e32 v179, s36, v131
	v_fmac_f32_e32 v180, s36, v132
	v_fmac_f32_e32 v181, s36, v133
	v_fmac_f32_e32 v182, s36, v134
	v_fmac_f32_e32 v183, s36, v135
	v_fmac_f32_e32 v184, s36, v136
	v_fmac_f32_e32 v185, s36, v137
	v_fmac_f32_e32 v186, s36, v138
	v_fmac_f32_e32 v187, s36, v139
	v_fmac_f32_e32 v188, s36, v140
	v_fmac_f32_e32 v189, s36, v141
	v_fmac_f32_e32 v190, s36, v142
	v_fmac_f32_e32 v191, s36, v143
	v_readlane_b32 s29, v37, s28
	s_add_u32 s28, s28, 1
	s_mul_hi_u32 s27, s29, 0x640
	s_mul_i32 s26, s29, 0x640
	s_add_u32 s26, s18, s26
	s_addc_u32 s27, s19, s27
	global_load_dwordx4 v[88:91], v2, s[26:27]
	global_load_dwordx2 v[92:93], v2, s[26:27] offset:16
	global_load_ubyte v94, v3, s[26:27]
	v_readlane_b32 s36, v43, s37
	s_add_u32 s37, s37, 1
	s_waitcnt vmcnt(21)
	v_lshlrev_b32_e32 v192, 23, v102
	v_cvt_scalef32_pk32_f32_fp6 v[112:143], v[96:101], v192
	v_fmac_f32_e32 v160, s36, v112
	v_fmac_f32_e32 v161, s36, v113
	v_fmac_f32_e32 v162, s36, v114
	v_fmac_f32_e32 v163, s36, v115
	v_fmac_f32_e32 v164, s36, v116
	v_fmac_f32_e32 v165, s36, v117
	v_fmac_f32_e32 v166, s36, v118
	v_fmac_f32_e32 v167, s36, v119
	v_fmac_f32_e32 v168, s36, v120
	v_fmac_f32_e32 v169, s36, v121
	v_fmac_f32_e32 v170, s36, v122
	v_fmac_f32_e32 v171, s36, v123
	v_fmac_f32_e32 v172, s36, v124
	v_fmac_f32_e32 v173, s36, v125
	v_fmac_f32_e32 v174, s36, v126
	v_fmac_f32_e32 v175, s36, v127
	v_fmac_f32_e32 v176, s36, v128
	v_fmac_f32_e32 v177, s36, v129
	v_fmac_f32_e32 v178, s36, v130
	v_fmac_f32_e32 v179, s36, v131
	v_fmac_f32_e32 v180, s36, v132
	v_fmac_f32_e32 v181, s36, v133
	v_fmac_f32_e32 v182, s36, v134
	v_fmac_f32_e32 v183, s36, v135
	v_fmac_f32_e32 v184, s36, v136
	v_fmac_f32_e32 v185, s36, v137
	v_fmac_f32_e32 v186, s36, v138
	v_fmac_f32_e32 v187, s36, v139
	v_fmac_f32_e32 v188, s36, v140
	v_fmac_f32_e32 v189, s36, v141
	v_fmac_f32_e32 v190, s36, v142
	v_fmac_f32_e32 v191, s36, v143
	v_readlane_b32 s29, v37, s28
	s_add_u32 s28, s28, 1
	s_mul_hi_u32 s27, s29, 0x640
	s_mul_i32 s26, s29, 0x640
	s_add_u32 s26, s18, s26
	s_addc_u32 s27, s19, s27
	global_load_dwordx4 v[96:99], v2, s[26:27]
	global_load_dwordx2 v[100:101], v2, s[26:27] offset:16
	global_load_ubyte v102, v3, s[26:27]
	v_readlane_b32 s36, v43, s37
	s_add_u32 s37, s37, 1
	s_waitcnt vmcnt(21)
	v_lshlrev_b32_e32 v192, 23, v110
	v_cvt_scalef32_pk32_f32_fp6 v[112:143], v[104:109], v192
	v_fmac_f32_e32 v160, s36, v112
	v_fmac_f32_e32 v161, s36, v113
	v_fmac_f32_e32 v162, s36, v114
	v_fmac_f32_e32 v163, s36, v115
	v_fmac_f32_e32 v164, s36, v116
	v_fmac_f32_e32 v165, s36, v117
	v_fmac_f32_e32 v166, s36, v118
	v_fmac_f32_e32 v167, s36, v119
	v_fmac_f32_e32 v168, s36, v120
	v_fmac_f32_e32 v169, s36, v121
	v_fmac_f32_e32 v170, s36, v122
	v_fmac_f32_e32 v171, s36, v123
	v_fmac_f32_e32 v172, s36, v124
	v_fmac_f32_e32 v173, s36, v125
	v_fmac_f32_e32 v174, s36, v126
	v_fmac_f32_e32 v175, s36, v127
	v_fmac_f32_e32 v176, s36, v128
	v_fmac_f32_e32 v177, s36, v129
	v_fmac_f32_e32 v178, s36, v130
	v_fmac_f32_e32 v179, s36, v131
	v_fmac_f32_e32 v180, s36, v132
	v_fmac_f32_e32 v181, s36, v133
	v_fmac_f32_e32 v182, s36, v134
	v_fmac_f32_e32 v183, s36, v135
	v_fmac_f32_e32 v184, s36, v136
	v_fmac_f32_e32 v185, s36, v137
	v_fmac_f32_e32 v186, s36, v138
	v_fmac_f32_e32 v187, s36, v139
	v_fmac_f32_e32 v188, s36, v140
	v_fmac_f32_e32 v189, s36, v141
	v_fmac_f32_e32 v190, s36, v142
	v_fmac_f32_e32 v191, s36, v143
	v_readlane_b32 s29, v37, s28
	s_add_u32 s28, s28, 1
	s_mul_hi_u32 s27, s29, 0x640
	s_mul_i32 s26, s29, 0x640
	s_add_u32 s26, s18, s26
	s_addc_u32 s27, s19, s27
	global_load_dwordx4 v[104:107], v2, s[26:27]
	global_load_dwordx2 v[108:109], v2, s[26:27] offset:16
	global_load_ubyte v110, v3, s[26:27]
	s_sub_u32 s30, s30, 1
	s_cmp_lg_u32 s30, 0
	s_cbranch_scc1 .Lap1_s2_loop4
; #define PB_FENCE asm volatile("" ::: "memory")
; __device__ __forceinline__ void ph_peer_apply(const Params& P, int layer, float* xlat, float* xctx_in, float* xctx_out, int nrows, bool write_next, char* smem, float* xlat_out = nullptr) {
;     ...
;     PB_LOAD(bufA, tv, 0);
;     for (int gq = 0; gq < NG; gq += 2) {
;       PB_LOAD(bufB, tv, gq + 1); PB_FENCE;
;       PB_ACC(bufA, gq);
;       if (gq + 2 < NG) PB_LOAD(bufA, tv, gq + 2);
;       PB_FENCE;
;       PB_ACC(bufB, gq + 1);
;     }
	v_readlane_b32 s36, v43, s37
	s_add_u32 s37, s37, 1
	s_waitcnt vmcnt(21)
	v_lshlrev_b32_e32 v192, 23, v54
	v_cvt_scalef32_pk32_f32_fp6 v[112:143], v[48:53], v192
	v_fmac_f32_e32 v160, s36, v112
	v_fmac_f32_e32 v161, s36, v113
	v_fmac_f32_e32 v162, s36, v114
	v_fmac_f32_e32 v163, s36, v115
	v_fmac_f32_e32 v164, s36, v116
	v_fmac_f32_e32 v165, s36, v117
	v_fmac_f32_e32 v166, s36, v118
	v_fmac_f32_e32 v167, s36, v119
	v_fmac_f32_e32 v168, s36, v120
	v_fmac_f32_e32 v169, s36, v121
	v_fmac_f32_e32 v170, s36, v122
	v_fmac_f32_e32 v171, s36, v123
	v_fmac_f32_e32 v172, s36, v124
	v_fmac_f32_e32 v173, s36, v125
	v_fmac_f32_e32 v174, s36, v126
	v_fmac_f32_e32 v175, s36, v127
	v_fmac_f32_e32 v176, s36, v128
	v_fmac_f32_e32 v177, s36, v129
	v_fmac_f32_e32 v178, s36, v130
	v_fmac_f32_e32 v179, s36, v131
	v_fmac_f32_e32 v180, s36, v132
	v_fmac_f32_e32 v181, s36, v133
	v_fmac_f32_e32 v182, s36, v134
	v_fmac_f32_e32 v183, s36, v135
	v_fmac_f32_e32 v184, s36, v136
	v_fmac_f32_e32 v185, s36, v137
	v_fmac_f32_e32 v186, s36, v138
	v_fmac_f32_e32 v187, s36, v139
	v_fmac_f32_e32 v188, s36, v140
	v_fmac_f32_e32 v189, s36, v141
	v_fmac_f32_e32 v190, s36, v142
	v_fmac_f32_e32 v191, s36, v143
	v_readlane_b32 s36, v43, s37
	s_add_u32 s37, s37, 1
	s_waitcnt vmcnt(18)
	v_lshlrev_b32_e32 v192, 23, v62
	v_cvt_scalef32_pk32_f32_fp6 v[112:143], v[56:61], v192
	v_fmac_f32_e32 v160, s36, v112
	v_fmac_f32_e32 v161, s36, v113
	v_fmac_f32_e32 v162, s36, v114
	v_fmac_f32_e32 v163, s36, v115
	v_fmac_f32_e32 v164, s36, v116
	v_fmac_f32_e32 v165, s36, v117
	v_fmac_f32_e32 v166, s36, v118
	v_fmac_f32_e32 v167, s36, v119
	v_fmac_f32_e32 v168, s36, v120
	v_fmac_f32_e32 v169, s36, v121
	v_fmac_f32_e32 v170, s36, v122
	v_fmac_f32_e32 v171, s36, v123
	v_fmac_f32_e32 v172, s36, v124
	v_fmac_f32_e32 v173, s36, v125
	v_fmac_f32_e32 v174, s36, v126
	v_fmac_f32_e32 v175, s36, v127
	v_fmac_f32_e32 v176, s36, v128
	v_fmac_f32_e32 v177, s36, v129
	v_fmac_f32_e32 v178, s36, v130
	v_fmac_f32_e32 v179, s36, v131
	v_fmac_f32_e32 v180, s36, v132
	v_fmac_f32_e32 v181, s36, v133
	v_fmac_f32_e32 v182, s36, v134
	v_fmac_f32_e32 v183, s36, v135
	v_fmac_f32_e32 v184, s36, v136
	v_fmac_f32_e32 v185, s36, v137
	v_fmac_f32_e32 v186, s36, v138
	v_fmac_f32_e32 v187, s36, v139
	v_fmac_f32_e32 v188, s36, v140
	v_fmac_f32_e32 v189, s36, v141
	v_fmac_f32_e32 v190, s36, v142
	v_fmac_f32_e32 v191, s36, v143
	v_readlane_b32 s36, v43, s37
	s_add_u32 s37, s37, 1
	s_waitcnt vmcnt(15)
	v_lshlrev_b32_e32 v192, 23, v70
	v_cvt_scalef32_pk32_f32_fp6 v[112:143], v[64:69], v192
	v_fmac_f32_e32 v160, s36, v112
	v_fmac_f32_e32 v161, s36, v113
	v_fmac_f32_e32 v162, s36, v114
	v_fmac_f32_e32 v163, s36, v115
	v_fmac_f32_e32 v164, s36, v116
	v_fmac_f32_e32 v165, s36, v117
	v_fmac_f32_e32 v166, s36, v118
	v_fmac_f32_e32 v167, s36, v119
	v_fmac_f32_e32 v168, s36, v120
	v_fmac_f32_e32 v169, s36, v121
	v_fmac_f32_e32 v170, s36, v122
	v_fmac_f32_e32 v171, s36, v123
	v_fmac_f32_e32 v172, s36, v124
	v_fmac_f32_e32 v173, s36, v125
	v_fmac_f32_e32 v174, s36, v126
	v_fmac_f32_e32 v175, s36, v127
	v_fmac_f32_e32 v176, s36, v128
	v_fmac_f32_e32 v177, s36, v129
	v_fmac_f32_e32 v178, s36, v130
	v_fmac_f32_e32 v179, s36, v131
	v_fmac_f32_e32 v180, s36, v132
	v_fmac_f32_e32 v181, s36, v133
	v_fmac_f32_e32 v182, s36, v134
	v_fmac_f32_e32 v183, s36, v135
	v_fmac_f32_e32 v184, s36, v136
	v_fmac_f32_e32 v185, s36, v137
	v_fmac_f32_e32 v186, s36, v138
	v_fmac_f32_e32 v187, s36, v139
	v_fmac_f32_e32 v188, s36, v140
	v_fmac_f32_e32 v189, s36, v141
	v_fmac_f32_e32 v190, s36, v142
	v_fmac_f32_e32 v191, s36, v143
	v_readlane_b32 s36, v43, s37
	s_add_u32 s37, s37, 1
	s_waitcnt vmcnt(12)
	v_lshlrev_b32_e32 v192, 23, v78
	v_cvt_scalef32_pk32_f32_fp6 v[112:143], v[72:77], v192
	v_fmac_f32_e32 v160, s36, v112
	v_fmac_f32_e32 v161, s36, v113
	v_fmac_f32_e32 v162, s36, v114
	v_fmac_f32_e32 v163, s36, v115
	v_fmac_f32_e32 v164, s36, v116
	v_fmac_f32_e32 v165, s36, v117
	v_fmac_f32_e32 v166, s36, v118
	v_fmac_f32_e32 v167, s36, v119
	v_fmac_f32_e32 v168, s36, v120
	v_fmac_f32_e32 v169, s36, v121
	v_fmac_f32_e32 v170, s36, v122
	v_fmac_f32_e32 v171, s36, v123
	v_fmac_f32_e32 v172, s36, v124
	v_fmac_f32_e32 v173, s36, v125
	v_fmac_f32_e32 v174, s36, v126
	v_fmac_f32_e32 v175, s36, v127
	v_fmac_f32_e32 v176, s36, v128
	v_fmac_f32_e32 v177, s36, v129
	v_fmac_f32_e32 v178, s36, v130
	v_fmac_f32_e32 v179, s36, v131
	v_fmac_f32_e32 v180, s36, v132
	v_fmac_f32_e32 v181, s36, v133
	v_fmac_f32_e32 v182, s36, v134
	v_fmac_f32_e32 v183, s36, v135
	v_fmac_f32_e32 v184, s36, v136
	v_fmac_f32_e32 v185, s36, v137
	v_fmac_f32_e32 v186, s36, v138
	v_fmac_f32_e32 v187, s36, v139
	v_fmac_f32_e32 v188, s36, v140
	v_fmac_f32_e32 v189, s36, v141
	v_fmac_f32_e32 v190, s36, v142
	v_fmac_f32_e32 v191, s36, v143
	v_readlane_b32 s36, v43, s37
	s_add_u32 s37, s37, 1
	s_waitcnt vmcnt(9)
	v_lshlrev_b32_e32 v192, 23, v86
	v_cvt_scalef32_pk32_f32_fp6 v[112:143], v[80:85], v192
	v_fmac_f32_e32 v160, s36, v112
	v_fmac_f32_e32 v161, s36, v113
	v_fmac_f32_e32 v162, s36, v114
	v_fmac_f32_e32 v163, s36, v115
	v_fmac_f32_e32 v164, s36, v116
	v_fmac_f32_e32 v165, s36, v117
	v_fmac_f32_e32 v166, s36, v118
	v_fmac_f32_e32 v167, s36, v119
	v_fmac_f32_e32 v168, s36, v120
	v_fmac_f32_e32 v169, s36, v121
	v_fmac_f32_e32 v170, s36, v122
	v_fmac_f32_e32 v171, s36, v123
	v_fmac_f32_e32 v172, s36, v124
	v_fmac_f32_e32 v173, s36, v125
	v_fmac_f32_e32 v174, s36, v126
	v_fmac_f32_e32 v175, s36, v127
	v_fmac_f32_e32 v176, s36, v128
	v_fmac_f32_e32 v177, s36, v129
	v_fmac_f32_e32 v178, s36, v130
	v_fmac_f32_e32 v179, s36, v131
	v_fmac_f32_e32 v180, s36, v132
	v_fmac_f32_e32 v181, s36, v133
	v_fmac_f32_e32 v182, s36, v134
	v_fmac_f32_e32 v183, s36, v135
	v_fmac_f32_e32 v184, s36, v136
	v_fmac_f32_e32 v185, s36, v137
	v_fmac_f32_e32 v186, s36, v138
	v_fmac_f32_e32 v187, s36, v139
	v_fmac_f32_e32 v188, s36, v140
	v_fmac_f32_e32 v189, s36, v141
	v_fmac_f32_e32 v190, s36, v142
	v_fmac_f32_e32 v191, s36, v143
	v_readlane_b32 s36, v43, s37
	s_add_u32 s37, s37, 1
	s_waitcnt vmcnt(6)
; __device__ __forceinline__ void ph_peer_apply(const Params& P, int layer, float* xlat, float* xctx_in, float* xctx_out, int nrows, bool write_next, char* smem, float* xlat_out = nullptr) {
;     ...
;     const float* xs1 = (row < NL ? xlat + (size_t)row * D : xctx_in + (size_t)(row - NL) * D) + lb * 32;
;     float* xo = (row < NL ? (xlat_out ? xlat_out : xlat) + (size_t)row * D : xctx_out + (size_t)(row - NL) * D) + lb * 32;
;     const float* gt = mod_ptr(P, layer, row, 5) + lb * 32;
;     float s = 0.f;
; #pragma unroll
;     for (int j4 = 0; j4 < 8; ++j4) {
;       float4 xa; const float4 ga = *(const float4*)(gt + j4 * 4);
;       if (row < NL) { const h16x4 xh_ = *(const h16x4*)((const h16*)(xlat + (size_t)row * D) + lb * 32 + j4 * 4); xa = make_float4((float)xh_[0], (float)xh_[1], (float)xh_[2], (float)xh_[3]); }
;       else xa = *(const float4*)(xs1 + j4 * 4);
	v_lshlrev_b32_e32 v192, 23, v94
	v_cvt_scalef32_pk32_f32_fp6 v[112:143], v[88:93], v192
	v_fmac_f32_e32 v160, s36, v112
	v_fmac_f32_e32 v161, s36, v113
	v_fmac_f32_e32 v162, s36, v114
	v_fmac_f32_e32 v163, s36, v115
	v_fmac_f32_e32 v164, s36, v116
	v_fmac_f32_e32 v165, s36, v117
	v_fmac_f32_e32 v166, s36, v118
	v_fmac_f32_e32 v167, s36, v119
	v_fmac_f32_e32 v168, s36, v120
	v_fmac_f32_e32 v169, s36, v121
	v_fmac_f32_e32 v170, s36, v122
	v_fmac_f32_e32 v171, s36, v123
	v_fmac_f32_e32 v172, s36, v124
	v_fmac_f32_e32 v173, s36, v125
	v_fmac_f32_e32 v174, s36, v126
	v_fmac_f32_e32 v175, s36, v127
	v_fmac_f32_e32 v176, s36, v128
	v_fmac_f32_e32 v177, s36, v129
	v_fmac_f32_e32 v178, s36, v130
	v_fmac_f32_e32 v179, s36, v131
	v_fmac_f32_e32 v180, s36, v132
	v_fmac_f32_e32 v181, s36, v133
	v_fmac_f32_e32 v182, s36, v134
	v_fmac_f32_e32 v183, s36, v135
	v_fmac_f32_e32 v184, s36, v136
	v_fmac_f32_e32 v185, s36, v137
	v_fmac_f32_e32 v186, s36, v138
	v_fmac_f32_e32 v187, s36, v139
	v_fmac_f32_e32 v188, s36, v140
	v_fmac_f32_e32 v189, s36, v141
	v_fmac_f32_e32 v190, s36, v142
	v_fmac_f32_e32 v191, s36, v143
	v_readlane_b32 s36, v43, s37
	s_add_u32 s37, s37, 1
	s_waitcnt vmcnt(3)
	v_lshlrev_b32_e32 v192, 23, v102
	v_cvt_scalef32_pk32_f32_fp6 v[112:143], v[96:101], v192
	v_fmac_f32_e32 v160, s36, v112
	v_fmac_f32_e32 v161, s36, v113
	v_fmac_f32_e32 v162, s36, v114
	v_fmac_f32_e32 v163, s36, v115
	v_fmac_f32_e32 v164, s36, v116
	v_fmac_f32_e32 v165, s36, v117
	v_fmac_f32_e32 v166, s36, v118
	v_fmac_f32_e32 v167, s36, v119
	v_fmac_f32_e32 v168, s36, v120
	v_fmac_f32_e32 v169, s36, v121
	v_fmac_f32_e32 v170, s36, v122
	v_fmac_f32_e32 v171, s36, v123
	v_fmac_f32_e32 v172, s36, v124
	v_fmac_f32_e32 v173, s36, v125
	v_fmac_f32_e32 v174, s36, v126
	v_fmac_f32_e32 v175, s36, v127
	v_fmac_f32_e32 v176, s36, v128
	v_fmac_f32_e32 v177, s36, v129
	v_fmac_f32_e32 v178, s36, v130
	v_fmac_f32_e32 v179, s36, v131
	v_fmac_f32_e32 v180, s36, v132
	v_fmac_f32_e32 v181, s36, v133
	v_fmac_f32_e32 v182, s36, v134
	v_fmac_f32_e32 v183, s36, v135
	v_fmac_f32_e32 v184, s36, v136
	v_fmac_f32_e32 v185, s36, v137
	v_fmac_f32_e32 v186, s36, v138
	v_fmac_f32_e32 v187, s36, v139
	v_fmac_f32_e32 v188, s36, v140
	v_fmac_f32_e32 v189, s36, v141
	v_fmac_f32_e32 v190, s36, v142
	v_fmac_f32_e32 v191, s36, v143
	v_readlane_b32 s36, v43, s37
	s_add_u32 s37, s37, 1
	s_waitcnt vmcnt(0)
	v_lshlrev_b32_e32 v192, 23, v110
	v_cvt_scalef32_pk32_f32_fp6 v[112:143], v[104:109], v192
	v_fmac_f32_e32 v160, s36, v112
	v_fmac_f32_e32 v161, s36, v113
	v_fmac_f32_e32 v162, s36, v114
	v_fmac_f32_e32 v163, s36, v115
	v_fmac_f32_e32 v164, s36, v116
	v_fmac_f32_e32 v165, s36, v117
	v_fmac_f32_e32 v166, s36, v118
	v_fmac_f32_e32 v167, s36, v119
	v_fmac_f32_e32 v168, s36, v120
	v_fmac_f32_e32 v169, s36, v121
	v_fmac_f32_e32 v170, s36, v122
	v_fmac_f32_e32 v171, s36, v123
	v_fmac_f32_e32 v172, s36, v124
	v_fmac_f32_e32 v173, s36, v125
	v_fmac_f32_e32 v174, s36, v126
	v_fmac_f32_e32 v175, s36, v127
	v_fmac_f32_e32 v176, s36, v128
	v_fmac_f32_e32 v177, s36, v129
	v_fmac_f32_e32 v178, s36, v130
	v_fmac_f32_e32 v179, s36, v131
	v_fmac_f32_e32 v180, s36, v132
	v_fmac_f32_e32 v181, s36, v133
	v_fmac_f32_e32 v182, s36, v134
	v_fmac_f32_e32 v183, s36, v135
	v_fmac_f32_e32 v184, s36, v136
	v_fmac_f32_e32 v185, s36, v137
	v_fmac_f32_e32 v186, s36, v138
	v_fmac_f32_e32 v187, s36, v139
	v_fmac_f32_e32 v188, s36, v140
	v_fmac_f32_e32 v189, s36, v141
	v_fmac_f32_e32 v190, s36, v142
	v_fmac_f32_e32 v191, s36, v143
	s_cmp_ge_u32 s45, 0x8000
	s_cselect_b32 s48, 1, 0
	s_lshr_b32 s49, s45, 14
	s_cmp_lg_u32 s48, 0
	s_cselect_b32 s49, 2, s49
	s_sub_u32 s50, s45, 0x8000
	s_lshl_b32 s15, s45, 13
	s_lshr_b32 s31, s45, 19
	s_add_u32 s40, s6, s15
	s_addc_u32 s41, s7, s31
	s_add_u32 s15, s49, 3
	s_mul_i32 s15, s15, 6
	s_add_u32 s15, s15, 5
	s_lshl_b32 s15, s15, 13
	s_add_u32 s42, s4, 0x4000
	s_addc_u32 s43, s5, 0
	s_add_u32 s42, s42, s15
	s_addc_u32 s43, s43, 0
	global_load_dwordx4 v[112:115], v225, s[42:43]
	global_load_dwordx4 v[116:119], v225, s[42:43] offset:16
	global_load_dwordx4 v[120:123], v225, s[42:43] offset:32
	global_load_dwordx4 v[124:127], v225, s[42:43] offset:48
	global_load_dwordx4 v[128:131], v225, s[42:43] offset:64
	global_load_dwordx4 v[132:135], v225, s[42:43] offset:80
	global_load_dwordx4 v[136:139], v225, s[42:43] offset:96
	global_load_dwordx4 v[140:143], v225, s[42:43] offset:112
	s_mov_b32 s15, 0x3fb504f3
	global_load_dwordx4 v[192:195], v224, s[40:41]
	global_load_dwordx4 v[196:199], v224, s[40:41] offset:16
	global_load_dwordx4 v[200:203], v224, s[40:41] offset:32
	global_load_dwordx4 v[204:207], v224, s[40:41] offset:48
	s_waitcnt vmcnt(0)
; __device__ __forceinline__ float wave_sum(float v) { v = row_sum16(v); v += __shfl_xor(v, 16); v += __shfl_xor(v, 32); return v; }
; __device__ __forceinline__ void ph_peer_apply(const Params& P, int layer, float* xlat, float* xctx_in, float* xctx_out, int nrows, bool write_next, char* smem, float* xlat_out = nullptr) {
;     ...
;     for (int j4 = 0; j4 < 8; ++j4) {
;       float4 xa; const float4 ga = *(const float4*)(gt + j4 * 4);
;       if (row < NL) { const h16x4 xh_ = *(const h16x4*)((const h16*)(xlat + (size_t)row * D) + lb * 32 + j4 * 4); xa = make_float4((float)xh_[0], (float)xh_[1], (float)xh_[2], (float)xh_[3]); }
;       else xa = *(const float4*)(xs1 + j4 * 4);
;       o[j4 * 4 + 0] = ALPHA * xa.x + ga.x * o[j4 * 4 + 0]; o[j4 * 4 + 1] = ALPHA * xa.y + ga.y * o[j4 * 4 + 1];
;       o[j4 * 4 + 2] = ALPHA * xa.z + ga.z * o[j4 * 4 + 2]; o[j4 * 4 + 3] = ALPHA * xa.w + ga.w * o[j4 * 4 + 3];
;       s += (o[j4 * 4 + 0] + o[j4 * 4 + 1]) + (o[j4 * 4 + 2] + o[j4 * 4 + 3]);
;     }
;     s = wave_sum(lact ? s : 0.f);
;     const float mu = s / (float)D;
	v_mul_f32_e32 v160, v112, v160
	v_mul_f32_e32 v161, v113, v161
	v_mul_f32_e32 v162, v114, v162
	v_mul_f32_e32 v163, v115, v163
	v_mul_f32_e32 v164, v116, v164
	v_mul_f32_e32 v165, v117, v165
	v_mul_f32_e32 v166, v118, v166
	v_mul_f32_e32 v167, v119, v167
	v_mul_f32_e32 v168, v120, v168
	v_mul_f32_e32 v169, v121, v169
	v_mul_f32_e32 v170, v122, v170
	v_mul_f32_e32 v171, v123, v171
	v_mul_f32_e32 v172, v124, v172
	v_mul_f32_e32 v173, v125, v173
	v_mul_f32_e32 v174, v126, v174
	v_mul_f32_e32 v175, v127, v175
	v_mul_f32_e32 v176, v128, v176
	v_mul_f32_e32 v177, v129, v177
	v_mul_f32_e32 v178, v130, v178
	v_mul_f32_e32 v179, v131, v179
	v_mul_f32_e32 v180, v132, v180
	v_mul_f32_e32 v181, v133, v181
	v_mul_f32_e32 v182, v134, v182
	v_mul_f32_e32 v183, v135, v183
	v_mul_f32_e32 v184, v136, v184
	v_mul_f32_e32 v185, v137, v185
	v_mul_f32_e32 v186, v138, v186
	v_mul_f32_e32 v187, v139, v187
	v_mul_f32_e32 v188, v140, v188
	v_mul_f32_e32 v189, v141, v189
	v_mul_f32_e32 v190, v142, v190
	v_mul_f32_e32 v191, v143, v191
	v_fma_mix_f32 v160, s15, v192, v160 op_sel_hi:[0,1,0]
	v_fma_mix_f32 v161, s15, v192, v161 op_sel:[0,1,0] op_sel_hi:[0,1,0]
	v_fma_mix_f32 v162, s15, v193, v162 op_sel_hi:[0,1,0]
	v_fma_mix_f32 v163, s15, v193, v163 op_sel:[0,1,0] op_sel_hi:[0,1,0]
	v_fma_mix_f32 v164, s15, v194, v164 op_sel_hi:[0,1,0]
	v_fma_mix_f32 v165, s15, v194, v165 op_sel:[0,1,0] op_sel_hi:[0,1,0]
	v_fma_mix_f32 v166, s15, v195, v166 op_sel_hi:[0,1,0]
	v_fma_mix_f32 v167, s15, v195, v167 op_sel:[0,1,0] op_sel_hi:[0,1,0]
	v_fma_mix_f32 v168, s15, v196, v168 op_sel_hi:[0,1,0]
	v_fma_mix_f32 v169, s15, v196, v169 op_sel:[0,1,0] op_sel_hi:[0,1,0]
	v_fma_mix_f32 v170, s15, v197, v170 op_sel_hi:[0,1,0]
	v_fma_mix_f32 v171, s15, v197, v171 op_sel:[0,1,0] op_sel_hi:[0,1,0]
	v_fma_mix_f32 v172, s15, v198, v172 op_sel_hi:[0,1,0]
	v_fma_mix_f32 v173, s15, v198, v173 op_sel:[0,1,0] op_sel_hi:[0,1,0]
	v_fma_mix_f32 v174, s15, v199, v174 op_sel_hi:[0,1,0]
	v_fma_mix_f32 v175, s15, v199, v175 op_sel:[0,1,0] op_sel_hi:[0,1,0]
	v_fma_mix_f32 v176, s15, v200, v176 op_sel_hi:[0,1,0]
	v_fma_mix_f32 v177, s15, v200, v177 op_sel:[0,1,0] op_sel_hi:[0,1,0]
	v_fma_mix_f32 v178, s15, v201, v178 op_sel_hi:[0,1,0]
	v_fma_mix_f32 v179, s15, v201, v179 op_sel:[0,1,0] op_sel_hi:[0,1,0]
	v_fma_mix_f32 v180, s15, v202, v180 op_sel_hi:[0,1,0]
	v_fma_mix_f32 v181, s15, v202, v181 op_sel:[0,1,0] op_sel_hi:[0,1,0]
	v_fma_mix_f32 v182, s15, v203, v182 op_sel_hi:[0,1,0]
	v_fma_mix_f32 v183, s15, v203, v183 op_sel:[0,1,0] op_sel_hi:[0,1,0]
	v_fma_mix_f32 v184, s15, v204, v184 op_sel_hi:[0,1,0]
	v_fma_mix_f32 v185, s15, v204, v185 op_sel:[0,1,0] op_sel_hi:[0,1,0]
	v_fma_mix_f32 v186, s15, v205, v186 op_sel_hi:[0,1,0]
	v_fma_mix_f32 v187, s15, v205, v187 op_sel:[0,1,0] op_sel_hi:[0,1,0]
	v_fma_mix_f32 v188, s15, v206, v188 op_sel_hi:[0,1,0]
	v_fma_mix_f32 v189, s15, v206, v189 op_sel:[0,1,0] op_sel_hi:[0,1,0]
	v_fma_mix_f32 v190, s15, v207, v190 op_sel_hi:[0,1,0]
	v_fma_mix_f32 v191, s15, v207, v191 op_sel:[0,1,0] op_sel_hi:[0,1,0]
	v_add_f32_e32 v208, v160, v161
	v_add_f32_e32 v208, v208, v162
	v_add_f32_e32 v208, v208, v163
	v_add_f32_e32 v208, v208, v164
	v_add_f32_e32 v208, v208, v165
	v_add_f32_e32 v208, v208, v166
	v_add_f32_e32 v208, v208, v167
	v_add_f32_e32 v208, v208, v168
	v_add_f32_e32 v208, v208, v169
	v_add_f32_e32 v208, v208, v170
	v_add_f32_e32 v208, v208, v171
	v_add_f32_e32 v208, v208, v172
	v_add_f32_e32 v208, v208, v173
	v_add_f32_e32 v208, v208, v174
	v_add_f32_e32 v208, v208, v175
	v_add_f32_e32 v208, v208, v176
	v_add_f32_e32 v208, v208, v177
	v_add_f32_e32 v208, v208, v178
	v_add_f32_e32 v208, v208, v179
	v_add_f32_e32 v208, v208, v180
	v_add_f32_e32 v208, v208, v181
	v_add_f32_e32 v208, v208, v182
	v_add_f32_e32 v208, v208, v183
	v_add_f32_e32 v208, v208, v184
	v_add_f32_e32 v208, v208, v185
	v_add_f32_e32 v208, v208, v186
	v_add_f32_e32 v208, v208, v187
	v_add_f32_e32 v208, v208, v188
	v_add_f32_e32 v208, v208, v189
	v_add_f32_e32 v208, v208, v190
	v_add_f32_e32 v208, v208, v191
	s_nop 1
	v_add_f32_dpp v208, v208, v208 quad_perm:[1,0,3,2] row_mask:0xf bank_mask:0xf bound_ctrl:1
	s_nop 1
	v_add_f32_dpp v208, v208, v208 quad_perm:[2,3,0,1] row_mask:0xf bank_mask:0xf bound_ctrl:1
	s_nop 1
	v_add_f32_dpp v208, v208, v208 row_ror:4 row_mask:0xf bank_mask:0xf bound_ctrl:1
	s_nop 1
	v_add_f32_dpp v208, v208, v208 row_ror:8 row_mask:0xf bank_mask:0xf bound_ctrl:1
	v_mov_b32_e32 v193, v208
	s_nop 1
	v_permlane32_swap_b32_e32 v193, v208
	v_add_f32_e32 v208, v208, v193
	v_mov_b32_e32 v193, v208
	s_nop 1
	v_permlane16_swap_b32_e32 v193, v208
	v_add_f32_e32 v208, v208, v193
	v_mul_f32_e32 v210, 0x3a000000, v208
	v_sub_f32_e32 v160, v160, v210
	v_sub_f32_e32 v161, v161, v210
	v_sub_f32_e32 v162, v162, v210
	v_sub_f32_e32 v163, v163, v210
	v_sub_f32_e32 v164, v164, v210
	v_sub_f32_e32 v165, v165, v210
	v_sub_f32_e32 v166, v166, v210
	v_sub_f32_e32 v167, v167, v210
	v_sub_f32_e32 v168, v168, v210
	v_sub_f32_e32 v169, v169, v210
	v_sub_f32_e32 v170, v170, v210
	v_sub_f32_e32 v171, v171, v210
	v_sub_f32_e32 v172, v172, v210
	v_sub_f32_e32 v173, v173, v210
	v_sub_f32_e32 v174, v174, v210
	v_sub_f32_e32 v175, v175, v210
	v_sub_f32_e32 v176, v176, v210
	v_sub_f32_e32 v177, v177, v210
	v_sub_f32_e32 v178, v178, v210
	v_sub_f32_e32 v179, v179, v210
	v_sub_f32_e32 v180, v180, v210
	v_sub_f32_e32 v181, v181, v210
	v_sub_f32_e32 v182, v182, v210
	v_sub_f32_e32 v183, v183, v210
	v_sub_f32_e32 v184, v184, v210
	v_sub_f32_e32 v185, v185, v210
	v_sub_f32_e32 v186, v186, v210
	v_sub_f32_e32 v187, v187, v210
	v_sub_f32_e32 v188, v188, v210
	v_sub_f32_e32 v189, v189, v210
	v_sub_f32_e32 v190, v190, v210
; __device__ __forceinline__ float wave_sum(float v) { v = row_sum16(v); v += __shfl_xor(v, 16); v += __shfl_xor(v, 32); return v; }
; __device__ __forceinline__ void ph_peer_apply(const Params& P, int layer, float* xlat, float* xctx_in, float* xctx_out, int nrows, bool write_next, char* smem, float* xlat_out = nullptr) {
;     ...
;     float s2 = 0.f;
; #pragma unroll
;     for (int j = 0; j < 32; ++j) { const float dd = o[j] - mu; s2 += dd * dd; }
;     s2 = wave_sum(lact ? s2 : 0.f);
;     const float rstd = rsqrtf(s2 / (float)D + LN_EPS);
;     const float* gp = g + lb * 32; const float* bp = bb + lb * 32;
;     const float* sh1n = mod_ptr(P, 1, row, 0) + lb * 32;
;     const float* sc1n = mod_ptr(P, 1, row, 1) + lb * 32;
;     if (lact) {
; #pragma unroll
;       for (int j4 = 0; j4 < 8; ++j4) {
;         const float4 gv = *(const float4*)(gp + j4 * 4), bv = *(const float4*)(bp + j4 * 4);
;         float4 ov;
;         ov.x = (o[j4 * 4 + 0] - mu) * rstd * gv.x + bv.x; ov.y = (o[j4 * 4 + 1] - mu) * rstd * gv.y + bv.y;
;         ov.z = (o[j4 * 4 + 2] - mu) * rstd * gv.z + bv.z; ov.w = (o[j4 * 4 + 3] - mu) * rstd * gv.w + bv.w;
;         if (row < NL && write_next) { h16x4 oh_; oh_[0] = (h16)ov.x; oh_[1] = (h16)ov.y; oh_[2] = (h16)ov.z; oh_[3] = (h16)ov.w; *(h16x4*)((h16*)((xlat_out ? xlat_out : xlat) + (size_t)row * D) + lb * 32 + j4 * 4) = oh_; }
;         else *(float4*)(xo + j4 * 4) = ov;
	v_sub_f32_e32 v191, v191, v210
	v_mul_f32_e32 v209, v160, v160
	v_fmac_f32_e32 v209, v161, v161
	v_fmac_f32_e32 v209, v162, v162
	v_fmac_f32_e32 v209, v163, v163
	v_fmac_f32_e32 v209, v164, v164
	v_fmac_f32_e32 v209, v165, v165
	v_fmac_f32_e32 v209, v166, v166
	v_fmac_f32_e32 v209, v167, v167
	v_fmac_f32_e32 v209, v168, v168
	v_fmac_f32_e32 v209, v169, v169
	v_fmac_f32_e32 v209, v170, v170
	v_fmac_f32_e32 v209, v171, v171
	v_fmac_f32_e32 v209, v172, v172
	v_fmac_f32_e32 v209, v173, v173
	v_fmac_f32_e32 v209, v174, v174
	v_fmac_f32_e32 v209, v175, v175
	v_fmac_f32_e32 v209, v176, v176
	v_fmac_f32_e32 v209, v177, v177
	v_fmac_f32_e32 v209, v178, v178
	v_fmac_f32_e32 v209, v179, v179
	v_fmac_f32_e32 v209, v180, v180
	v_fmac_f32_e32 v209, v181, v181
	v_fmac_f32_e32 v209, v182, v182
	v_fmac_f32_e32 v209, v183, v183
	v_fmac_f32_e32 v209, v184, v184
	v_fmac_f32_e32 v209, v185, v185
	v_fmac_f32_e32 v209, v186, v186
	v_fmac_f32_e32 v209, v187, v187
	v_fmac_f32_e32 v209, v188, v188
	v_fmac_f32_e32 v209, v189, v189
	v_fmac_f32_e32 v209, v190, v190
	v_fmac_f32_e32 v209, v191, v191
	s_nop 1
	v_add_f32_dpp v209, v209, v209 quad_perm:[1,0,3,2] row_mask:0xf bank_mask:0xf bound_ctrl:1
	s_nop 1
	v_add_f32_dpp v209, v209, v209 quad_perm:[2,3,0,1] row_mask:0xf bank_mask:0xf bound_ctrl:1
	s_nop 1
	v_add_f32_dpp v209, v209, v209 row_ror:4 row_mask:0xf bank_mask:0xf bound_ctrl:1
	s_nop 1
	v_add_f32_dpp v209, v209, v209 row_ror:8 row_mask:0xf bank_mask:0xf bound_ctrl:1
	v_mov_b32_e32 v193, v209
	s_nop 1
	v_permlane32_swap_b32_e32 v193, v209
	v_add_f32_e32 v209, v209, v193
	v_mov_b32_e32 v193, v209
	s_nop 1
	v_permlane16_swap_b32_e32 v193, v209
	v_add_f32_e32 v209, v209, v193
	v_mov_b32_e32 v211, 0x3727c5ac
	v_fmac_f32_e32 v211, 0x3a000000, v209
	v_rsq_f32_e32 v211, v211
	s_add_u32 s26, s8, 0x6000
	s_addc_u32 s27, s9, 0
	global_load_dwordx4 v[112:115], v225, s[26:27]
	global_load_dwordx4 v[116:119], v225, s[26:27] offset:16
	global_load_dwordx4 v[120:123], v225, s[26:27] offset:32
	global_load_dwordx4 v[124:127], v225, s[26:27] offset:48
	global_load_dwordx4 v[128:131], v225, s[26:27] offset:64
	global_load_dwordx4 v[132:135], v225, s[26:27] offset:80
	global_load_dwordx4 v[136:139], v225, s[26:27] offset:96
	global_load_dwordx4 v[140:143], v225, s[26:27] offset:112
	s_add_u32 s26, s10, 0x6000
	s_addc_u32 s27, s11, 0
	global_load_dwordx4 v[192:195], v225, s[26:27]
	global_load_dwordx4 v[196:199], v225, s[26:27] offset:16
	global_load_dwordx4 v[200:203], v225, s[26:27] offset:32
	global_load_dwordx4 v[204:207], v225, s[26:27] offset:48
	s_waitcnt vmcnt(4)
	v_mul_f32_e32 v160, v160, v211
	v_mul_f32_e32 v161, v161, v211
	v_mul_f32_e32 v162, v162, v211
	v_mul_f32_e32 v163, v163, v211
	v_mul_f32_e32 v164, v164, v211
	v_mul_f32_e32 v165, v165, v211
	v_mul_f32_e32 v166, v166, v211
	v_mul_f32_e32 v167, v167, v211
	v_mul_f32_e32 v168, v168, v211
	v_mul_f32_e32 v169, v169, v211
	v_mul_f32_e32 v170, v170, v211
	v_mul_f32_e32 v171, v171, v211
	v_mul_f32_e32 v172, v172, v211
	v_mul_f32_e32 v173, v173, v211
	v_mul_f32_e32 v174, v174, v211
	v_mul_f32_e32 v175, v175, v211
	v_mul_f32_e32 v176, v176, v211
	v_mul_f32_e32 v177, v177, v211
	v_mul_f32_e32 v178, v178, v211
	v_mul_f32_e32 v179, v179, v211
	v_mul_f32_e32 v180, v180, v211
	v_mul_f32_e32 v181, v181, v211
	v_mul_f32_e32 v182, v182, v211
	v_mul_f32_e32 v183, v183, v211
	v_mul_f32_e32 v184, v184, v211
	v_mul_f32_e32 v185, v185, v211
	v_mul_f32_e32 v186, v186, v211
	v_mul_f32_e32 v187, v187, v211
	v_mul_f32_e32 v188, v188, v211
	v_mul_f32_e32 v189, v189, v211
	v_mul_f32_e32 v190, v190, v211
	v_mul_f32_e32 v191, v191, v211
	v_mul_f32_e32 v160, v160, v112
	v_mul_f32_e32 v161, v161, v113
	v_mul_f32_e32 v162, v162, v114
	v_mul_f32_e32 v163, v163, v115
	v_mul_f32_e32 v164, v164, v116
	v_mul_f32_e32 v165, v165, v117
	v_mul_f32_e32 v166, v166, v118
	v_mul_f32_e32 v167, v167, v119
	v_mul_f32_e32 v168, v168, v120
	v_mul_f32_e32 v169, v169, v121
	v_mul_f32_e32 v170, v170, v122
	v_mul_f32_e32 v171, v171, v123
	v_mul_f32_e32 v172, v172, v124
	v_mul_f32_e32 v173, v173, v125
	v_mul_f32_e32 v174, v174, v126
	v_mul_f32_e32 v175, v175, v127
	v_mul_f32_e32 v176, v176, v128
	v_mul_f32_e32 v177, v177, v129
	v_mul_f32_e32 v178, v178, v130
	v_mul_f32_e32 v179, v179, v131
	v_mul_f32_e32 v180, v180, v132
	v_mul_f32_e32 v181, v181, v133
	v_mul_f32_e32 v182, v182, v134
	v_mul_f32_e32 v183, v183, v135
	v_mul_f32_e32 v184, v184, v136
	v_mul_f32_e32 v185, v185, v137
	v_mul_f32_e32 v186, v186, v138
	v_mul_f32_e32 v187, v187, v139
	v_mul_f32_e32 v188, v188, v140
	v_mul_f32_e32 v189, v189, v141
	v_mul_f32_e32 v190, v190, v142
	v_mul_f32_e32 v191, v191, v143
	s_waitcnt vmcnt(0)
	v_add_f32_e32 v160, v160, v192
	v_add_f32_e32 v161, v161, v193
	v_add_f32_e32 v162, v162, v194
	v_add_f32_e32 v163, v163, v195
	v_add_f32_e32 v164, v164, v196
	v_add_f32_e32 v165, v165, v197
	v_add_f32_e32 v166, v166, v198
	v_add_f32_e32 v167, v167, v199
	v_add_f32_e32 v168, v168, v200
	v_add_f32_e32 v169, v169, v201
	v_add_f32_e32 v170, v170, v202
	v_add_f32_e32 v171, v171, v203
	v_add_f32_e32 v172, v172, v204
	v_add_f32_e32 v173, v173, v205
	v_add_f32_e32 v174, v174, v206
	v_add_f32_e32 v175, v175, v207
	global_load_dwordx4 v[192:195], v225, s[26:27] offset:64
	global_load_dwordx4 v[196:199], v225, s[26:27] offset:80
	global_load_dwordx4 v[200:203], v225, s[26:27] offset:96
	global_load_dwordx4 v[204:207], v225, s[26:27] offset:112
	s_waitcnt vmcnt(0)
	v_add_f32_e32 v176, v176, v192
	v_add_f32_e32 v177, v177, v193
	v_add_f32_e32 v178, v178, v194
	v_add_f32_e32 v179, v179, v195
	v_add_f32_e32 v180, v180, v196
	v_add_f32_e32 v181, v181, v197
	v_add_f32_e32 v182, v182, v198
	v_add_f32_e32 v183, v183, v199
	v_add_f32_e32 v184, v184, v200
	v_add_f32_e32 v185, v185, v201
	v_add_f32_e32 v186, v186, v202
	v_add_f32_e32 v187, v187, v203
	v_add_f32_e32 v188, v188, v204
	v_add_f32_e32 v189, v189, v205
	v_add_f32_e32 v190, v190, v206
	v_add_f32_e32 v191, v191, v207
	global_store_dwordx4 v225, v[160:163], s[40:41]
	global_store_dwordx4 v225, v[164:167], s[40:41] offset:16
	global_store_dwordx4 v225, v[168:171], s[40:41] offset:32
	global_store_dwordx4 v225, v[172:175], s[40:41] offset:48
	global_store_dwordx4 v225, v[176:179], s[40:41] offset:64
	global_store_dwordx4 v225, v[180:183], s[40:41] offset:80
	global_store_dwordx4 v225, v[184:187], s[40:41] offset:96
	global_store_dwordx4 v225, v[188:191], s[40:41] offset:112
	s_add_u32 s14, s14, 1
	s_add_u32 s45, s45, s44
	s_branch .Lap1_s2_tok
.Lap1_done:
.LBB0_3724:
	s_endpgm
